# hand-written RG-LRU scan passes 1+2 (4 interleaved chains, branchless neg_expm1, DPP-operand scan) on top of v5
# speedup vs baseline: 1.0110x; 1.0110x over previous
.LBB0_240:
	s_andn2_b64 vcc, exec, s[4:5]
	v_readlane_b32 s4, v254, 28
	v_readlane_b32 s5, v254, 29
	s_nop 1
	v_cndmask_b32_e64 v0, 0, 1, s[4:5]
	v_cmp_ne_u32_e64 s[4:5], 1, v0
	s_cbranch_vccnz .LBB0_392
	v_readlane_b32 s6, v254, 0
	v_readlane_b32 s7, v254, 1
	s_load_dwordx4 s[16:19], s[6:7], 0xb8
	v_mov_b32_e32 v85, v192
	s_mov_b32 s68, s20
	s_and_b64 vcc, exec, s[4:5]
	v_readfirstlane_b32 s0, v85
	s_cbranch_vccnz .LBB0_366
	s_waitcnt lgkmcnt(0)
	s_mov_b32 s20, s68
	s_load_dwordx4 s[8:11], s[6:7], 0x18
	s_load_dwordx2 s[12:13], s[6:7], 0x30
	s_load_dwordx4 s[24:27], s[6:7], 0x40
	v_readfirstlane_b32 s21, v192
	s_lshr_b32 s21, s21, 6
	s_add_u32 s28, s18, 0x8f29000
	s_addc_u32 s29, s19, 0
	s_add_u32 s30, s16, 0x37a8000
	s_addc_u32 s31, s17, 0
	v_and_b32_e32 v238, 63, v192
	v_and_b32_e32 v239, 15, v192
	v_bfe_u32 v240, v192, 4, 2
	s_mul_i32 s0, s21, 0x2600
	s_add_i32 s0, s0, 0xa080
	v_lshl_add_u32 v226, v238, 3, s0
	v_lshl_add_u32 v227, v238, 2, s0
	v_add_u32_e32 v227, 0x1900, v227
	v_mul_u32_u24_e32 v229, 0xd0, v239
	v_lshl_add_u32 v229, v240, 4, v229
	v_add_u32_e32 v228, s0, v229
	v_add_u32_e32 v228, 0x1900, v228
	v_lshlrev_b32_e32 v237, 4, v240
	v_add_u32_e32 v230, 0x9c00, v237
	v_mul_u32_u24_e32 v231, 0x190, v239
	v_add3_u32 v231, v231, v237, s0
	v_and_or_b32 v232, v238, 48, 15
	v_lshlrev_b32_e32 v232, 2, v232
	v_min_u32_e32 v241, 47, v238
	v_lshlrev_b32_e32 v233, 2, v241
	v_lshlrev_b32_e32 v234, 3, v241
	v_mul_u32_u24_e32 v235, 0x1800, v239
	v_lshl_add_u32 v235, v240, 3, v235
	v_mul_u32_u24_e32 v236, 0xc00, v239
	v_lshl_add_u32 v236, v240, 3, v236
	s_waitcnt lgkmcnt(0)
	s_mul_i32 s0, s20, 0x6000
	s_add_u32 s8, s8, s0
	s_addc_u32 s9, s9, 0
	s_mul_i32 s0, s20, 0x1800
	s_add_u32 s10, s10, s0
	s_addc_u32 s11, s11, 0
	s_add_u32 s12, s12, s0
	s_addc_u32 s13, s13, 0
	s_add_u32 s24, s24, s0
	s_addc_u32 s25, s25, 0
	s_add_u32 s26, s26, s0
	s_addc_u32 s27, s27, 0
	s_mov_b32 s38, -1
	s_mov_b32 s23, s2
	s_branch .Lscan1_unit_test
.Lscan1_unit:
	s_and_b32 s37, s23, 15
	s_cmp_eq_u32 s37, s38
	s_cbranch_scc1 .Lscan1_staged
	s_waitcnt vmcnt(0) lgkmcnt(0)
	s_barrier
	s_lshl_b32 s0, s20, 4
	s_add_i32 s0, s0, s37
	s_mul_i32 s0, s0, 0x4800
	s_add_u32 s44, s16, 0x3688000
	s_addc_u32 s45, s17, 0
	s_add_u32 s44, s44, s0
	s_addc_u32 s45, s45, 0
	v_add_u32_e32 v239, 0, v192
	v_mul_u32_u24_e32 v240, 0xaaab, v239
	v_lshrrev_b32_e32 v240, 19, v240
	v_mul_u32_u24_e32 v241, 12, v240
	v_sub_u32_e32 v241, v239, v241
	v_lshlrev_b32_e32 v241, 4, v241
	v_mul_u32_u24_e32 v242, 0xd0, v240
	v_add_u32_e32 v242, v242, v241
	v_mul_u32_u24_e32 v243, 0xc0, v240
	v_add_u32_e32 v243, v243, v241
	v_cmp_lt_u32_e32 vcc, 95, v240
	s_nop 1
	v_mov_b32_e32 v244, 0x8b800
	v_cndmask_b32_e32 v244, 0, v244, vcc
	v_add_u32_e32 v243, v243, v244
	global_load_dwordx4 v[248:251], v243, s[44:45]
	s_waitcnt vmcnt(0)
	ds_write_b128 v242, v[248:251]
	v_add_u32_e32 v239, 512, v192
	v_mul_u32_u24_e32 v240, 0xaaab, v239
	v_lshrrev_b32_e32 v240, 19, v240
	v_mul_u32_u24_e32 v241, 12, v240
	v_sub_u32_e32 v241, v239, v241
	v_lshlrev_b32_e32 v241, 4, v241
	v_mul_u32_u24_e32 v242, 0xd0, v240
	v_add_u32_e32 v242, v242, v241
	v_mul_u32_u24_e32 v243, 0xc0, v240
	v_add_u32_e32 v243, v243, v241
	v_cmp_lt_u32_e32 vcc, 95, v240
	s_nop 1
	v_mov_b32_e32 v244, 0x8b800
	v_cndmask_b32_e32 v244, 0, v244, vcc
	v_add_u32_e32 v243, v243, v244
	global_load_dwordx4 v[248:251], v243, s[44:45]
	s_waitcnt vmcnt(0)
	ds_write_b128 v242, v[248:251]
	v_add_u32_e32 v239, 1024, v192
	v_mul_u32_u24_e32 v240, 0xaaab, v239
	v_lshrrev_b32_e32 v240, 19, v240
	v_mul_u32_u24_e32 v241, 12, v240
	v_sub_u32_e32 v241, v239, v241
	v_lshlrev_b32_e32 v241, 4, v241
	v_mul_u32_u24_e32 v242, 0xd0, v240
	v_add_u32_e32 v242, v242, v241
	v_mul_u32_u24_e32 v243, 0xc0, v240
	v_add_u32_e32 v243, v243, v241
	v_cmp_lt_u32_e32 vcc, 95, v240
	s_nop 1
	v_mov_b32_e32 v244, 0x8b800
	v_cndmask_b32_e32 v244, 0, v244, vcc
	v_add_u32_e32 v243, v243, v244
	global_load_dwordx4 v[248:251], v243, s[44:45]
	s_waitcnt vmcnt(0)
	ds_write_b128 v242, v[248:251]
	v_add_u32_e32 v239, 1536, v192
	v_mul_u32_u24_e32 v240, 0xaaab, v239
	v_lshrrev_b32_e32 v240, 19, v240
	v_mul_u32_u24_e32 v241, 12, v240
	v_sub_u32_e32 v241, v239, v241
	v_lshlrev_b32_e32 v241, 4, v241
	v_mul_u32_u24_e32 v242, 0xd0, v240
	v_add_u32_e32 v242, v242, v241
	v_mul_u32_u24_e32 v243, 0xc0, v240
	v_add_u32_e32 v243, v243, v241
	v_cmp_lt_u32_e32 vcc, 95, v240
	s_nop 1
	v_mov_b32_e32 v244, 0x8b800
	v_cndmask_b32_e32 v244, 0, v244, vcc
	v_add_u32_e32 v243, v243, v244
	global_load_dwordx4 v[248:251], v243, s[44:45]
	s_waitcnt vmcnt(0)
	ds_write_b128 v242, v[248:251]
	v_add_u32_e32 v239, 2048, v192
	v_mul_u32_u24_e32 v240, 0xaaab, v239
	v_lshrrev_b32_e32 v240, 19, v240
	v_mul_u32_u24_e32 v241, 12, v240
	v_sub_u32_e32 v241, v239, v241
	v_lshlrev_b32_e32 v241, 4, v241
	v_mul_u32_u24_e32 v242, 0xd0, v240
	v_add_u32_e32 v242, v242, v241
	v_mul_u32_u24_e32 v243, 0xc0, v240
	v_add_u32_e32 v243, v243, v241
	v_cmp_lt_u32_e32 vcc, 95, v240
	s_nop 1
	v_mov_b32_e32 v244, 0x8b800
	v_cndmask_b32_e32 v244, 0, v244, vcc
	v_add_u32_e32 v243, v243, v244
	v_cmp_gt_u32_e32 vcc, 0x900, v239
	s_and_saveexec_b64 s[62:63], vcc
	global_load_dwordx4 v[248:251], v243, s[44:45]
	s_waitcnt vmcnt(0)
	ds_write_b128 v242, v[248:251]
	s_mov_b64 exec, s[62:63]
	v_cmp_gt_u32_e32 vcc, 0x60, v192
	s_and_saveexec_b64 s[62:63], vcc
	s_mul_i32 s0, s37, 0x180
	v_lshl_add_u32 v239, v192, 2, s0
	global_load_dword v242, v239, s[12:13]
	global_load_dword v243, v239, s[24:25]
	global_load_dword v244, v239, s[26:27]
	v_lshlrev_b32_e32 v240, 2, v192
	s_waitcnt vmcnt(0)
	ds_write_b32 v240, v242 offset:39936
	ds_write_b32 v240, v243 offset:40320
	v_mul_f32_e32 v244, 0xbfb8aa3b, v244
	v_exp_f32_e32 v244, v244
	s_nop 0
	v_add_f32_e32 v245, 1.0, v244
	v_log_f32_e32 v245, v245
	v_fmamk_f32 v246, v244, 0xbe800000, v194
	v_fma_f32 v246, -v244, v246, 0.5
	v_fma_f32 v246, -v244, v246, 1.0
	v_mul_f32_e32 v246, v244, v246
	v_mul_f32_e32 v247, 0x3f317217, v245
	v_fma_f32 v247, v245, s76, -v247
	v_fmac_f32_e32 v247, 0x3377d1cf, v245
	v_fmac_f32_e32 v247, 0x3f317217, v245
	v_cmp_ngt_f32_e32 vcc, s90, v244
	s_nop 1
	v_cndmask_b32_e32 v246, v246, v247, vcc
	ds_write_b32 v240, v246 offset:40704
	s_mov_b64 exec, s[62:63]
	s_mov_b32 s38, s37
	s_waitcnt lgkmcnt(0)
	s_barrier
.Lscan1_staged:
	s_lshr_b32 s0, s23, 4
	s_lshl_b32 s0, s0, 3
	s_add_i32 s0, s0, s21
	s_mul_i32 s55, s0, 0x5f5
	s_lshr_b32 s55, s55, 16
	s_mul_i32 s56, s55, 43
	s_sub_i32 s56, s0, s56
	s_mul_i32 s57, s55, 0x810
	s_mul_i32 s39, s56, 48
	s_add_i32 s57, s57, s39
	s_mul_i32 s44, s57, 0x1800
	s_mul_hi_u32 s45, s57, 0x1800
	s_mul_i32 s39, s37, 0xc0
	s_add_i32 s39, s39, 0xc00
	s_add_u32 s44, s44, s39
	s_addc_u32 s45, s45, 0
	s_add_u32 s44, s44, s28
	s_addc_u32 s45, s45, s29
	s_add_u32 s62, s44, 0xffffb800
	s_addc_u32 s63, s45, -1
	global_load_dword v59, v233, s[62:63]
	s_add_u32 s62, s62, 0x1800
	s_addc_u32 s63, s63, 0
	global_load_dword v61, v233, s[62:63]
	s_add_u32 s62, s62, 0x1800
	s_addc_u32 s63, s63, 0
	global_load_dword v63, v233, s[62:63]
	s_mov_b64 s[62:63], s[44:45]
	global_load_dword v66, v233, s[62:63]
	s_add_u32 s62, s62, 0x1800
	s_addc_u32 s63, s63, 0
	global_load_dword v67, v233, s[62:63]
	s_add_u32 s62, s62, 0x1800
	s_addc_u32 s63, s63, 0
	global_load_dword v68, v233, s[62:63]
	s_add_u32 s62, s62, 0x1800
	s_addc_u32 s63, s63, 0
	global_load_dword v69, v233, s[62:63]
	s_add_u32 s62, s62, 0x1800
	s_addc_u32 s63, s63, 0
	global_load_dword v70, v233, s[62:63]
	s_add_u32 s62, s62, 0x1800
	s_addc_u32 s63, s63, 0
	global_load_dword v71, v233, s[62:63]
	s_add_u32 s62, s62, 0x1800
	s_addc_u32 s63, s63, 0
	global_load_dword v72, v233, s[62:63]
	s_add_u32 s62, s62, 0x1800
	s_addc_u32 s63, s63, 0
	global_load_dword v73, v233, s[62:63]
	s_add_u32 s62, s62, 0x1800
	s_addc_u32 s63, s63, 0
	global_load_dword v74, v233, s[62:63]
	s_add_u32 s62, s62, 0x1800
	s_addc_u32 s63, s63, 0
	global_load_dword v75, v233, s[62:63]
	s_add_u32 s62, s62, 0x1800
	s_addc_u32 s63, s63, 0
	global_load_dword v76, v233, s[62:63]
	s_add_u32 s62, s62, 0x1800
	s_addc_u32 s63, s63, 0
	global_load_dword v77, v233, s[62:63]
	s_add_u32 s62, s62, 0x1800
	s_addc_u32 s63, s63, 0
	global_load_dword v78, v233, s[62:63]
	s_add_u32 s62, s62, 0x1800
	s_addc_u32 s63, s63, 0
	global_load_dword v79, v233, s[62:63]
	s_add_u32 s62, s62, 0x1800
	s_addc_u32 s63, s63, 0
	global_load_dword v80, v233, s[62:63]
	s_add_u32 s62, s62, 0x1800
	s_addc_u32 s63, s63, 0
	global_load_dword v81, v233, s[62:63]
	s_add_u32 s62, s62, 0x1800
	s_addc_u32 s63, s63, 0
	s_mov_b64 s[44:45], s[62:63]
	s_mul_i32 s39, s37, 0x180
	s_add_u32 s62, s8, s39
	s_addc_u32 s63, s9, 0
	global_load_dwordx2 v[48:49], v234, s[62:63]
	s_add_u32 s62, s62, 0x1800
	s_addc_u32 s63, s63, 0
	global_load_dwordx2 v[50:51], v234, s[62:63]
	s_add_u32 s62, s62, 0x1800
	s_addc_u32 s63, s63, 0
	global_load_dwordx2 v[52:53], v234, s[62:63]
	s_add_u32 s62, s62, 0x1800
	s_addc_u32 s63, s63, 0
	global_load_dwordx2 v[54:55], v234, s[62:63]
	s_add_u32 s62, s10, s39
	s_addc_u32 s63, s11, 0
	global_load_dwordx2 v[56:57], v234, s[62:63]
	s_mul_i32 s39, s55, 43
	s_add_i32 s39, s39, s56
	s_mul_i32 s39, s39, 0x1800
	s_mul_i32 s0, s37, 0x180
	s_add_i32 s39, s39, s0
	s_add_u32 s62, s30, s39
	s_addc_u32 s63, s31, 0
	v_mov_b32_e32 v0, 0
	v_mov_b32_e32 v24, 1.0
	v_mov_b32_e32 v1, 0
	v_mov_b32_e32 v25, 1.0
	v_mov_b32_e32 v2, 0
	v_mov_b32_e32 v26, 1.0
	v_mov_b32_e32 v3, 0
	v_mov_b32_e32 v27, 1.0
	v_mov_b32_e32 v4, 0
	v_mov_b32_e32 v28, 1.0
	v_mov_b32_e32 v5, 0
	v_mov_b32_e32 v29, 1.0
	v_mov_b32_e32 v6, 0
	v_mov_b32_e32 v30, 1.0
	v_mov_b32_e32 v7, 0
	v_mov_b32_e32 v31, 1.0
	v_mov_b32_e32 v8, 0
	v_mov_b32_e32 v32, 1.0
	v_mov_b32_e32 v9, 0
	v_mov_b32_e32 v33, 1.0
	v_mov_b32_e32 v10, 0
	v_mov_b32_e32 v34, 1.0
	v_mov_b32_e32 v11, 0
	v_mov_b32_e32 v35, 1.0
	v_mov_b32_e32 v12, 0
	v_mov_b32_e32 v36, 1.0
	v_mov_b32_e32 v13, 0
	v_mov_b32_e32 v37, 1.0
	v_mov_b32_e32 v14, 0
	v_mov_b32_e32 v38, 1.0
	v_mov_b32_e32 v15, 0
	v_mov_b32_e32 v39, 1.0
	v_mov_b32_e32 v16, 0
	v_mov_b32_e32 v40, 1.0
	v_mov_b32_e32 v17, 0
	v_mov_b32_e32 v41, 1.0
	v_mov_b32_e32 v18, 0
	v_mov_b32_e32 v42, 1.0
	v_mov_b32_e32 v19, 0
	v_mov_b32_e32 v43, 1.0
	v_mov_b32_e32 v20, 0
	v_mov_b32_e32 v44, 1.0
	v_mov_b32_e32 v21, 0
	v_mov_b32_e32 v45, 1.0
	v_mov_b32_e32 v22, 0
	v_mov_b32_e32 v46, 1.0
	v_mov_b32_e32 v23, 0
	v_mov_b32_e32 v47, 1.0
	s_mov_b64 s[6:7], s[62:63]
	s_waitcnt vmcnt(0)
	s_cmp_eq_u32 s56, 0
	s_cbranch_scc1 .Lscan1_hzero
	v_lshlrev_b32_e32 v58, 16, v59
	v_and_b32_e32 v59, 0xffff0000, v59
	v_lshlrev_b32_e32 v60, 16, v61
	v_and_b32_e32 v61, 0xffff0000, v61
	v_lshlrev_b32_e32 v62, 16, v63
	v_and_b32_e32 v63, 0xffff0000, v63
	s_branch .Lscan1_hdone
.Lscan1_hzero:
	v_mov_b32_e32 v58, 0
	v_mov_b32_e32 v59, 0
	v_mov_b32_e32 v60, 0
	v_mov_b32_e32 v61, 0
	v_mov_b32_e32 v62, 0
	v_mov_b32_e32 v63, 0
.Lscan1_hdone:
	s_mov_b32 s64, 0
.Lscan1_sub:
	s_mov_b64 s[62:63], s[44:45]
	global_load_dword v82, v233, s[62:63]
	s_add_u32 s62, s62, 0x1800
	s_addc_u32 s63, s63, 0
	global_load_dword v83, v233, s[62:63]
	s_add_u32 s62, s62, 0x1800
	s_addc_u32 s63, s63, 0
	global_load_dword v84, v233, s[62:63]
	s_add_u32 s62, s62, 0x1800
	s_addc_u32 s63, s63, 0
	global_load_dword v85, v233, s[62:63]
	s_add_u32 s62, s62, 0x1800
	s_addc_u32 s63, s63, 0
	global_load_dword v86, v233, s[62:63]
	s_add_u32 s62, s62, 0x1800
	s_addc_u32 s63, s63, 0
	global_load_dword v87, v233, s[62:63]
	s_add_u32 s62, s62, 0x1800
	s_addc_u32 s63, s63, 0
	global_load_dword v88, v233, s[62:63]
	s_add_u32 s62, s62, 0x1800
	s_addc_u32 s63, s63, 0
	global_load_dword v89, v233, s[62:63]
	s_add_u32 s62, s62, 0x1800
	s_addc_u32 s63, s63, 0
	global_load_dword v90, v233, s[62:63]
	s_add_u32 s62, s62, 0x1800
	s_addc_u32 s63, s63, 0
	global_load_dword v91, v233, s[62:63]
	s_add_u32 s62, s62, 0x1800
	s_addc_u32 s63, s63, 0
	global_load_dword v92, v233, s[62:63]
	s_add_u32 s62, s62, 0x1800
	s_addc_u32 s63, s63, 0
	global_load_dword v93, v233, s[62:63]
	s_add_u32 s62, s62, 0x1800
	s_addc_u32 s63, s63, 0
	global_load_dword v94, v233, s[62:63]
	s_add_u32 s62, s62, 0x1800
	s_addc_u32 s63, s63, 0
	global_load_dword v95, v233, s[62:63]
	s_add_u32 s62, s62, 0x1800
	s_addc_u32 s63, s63, 0
	global_load_dword v96, v233, s[62:63]
	s_add_u32 s62, s62, 0x1800
	s_addc_u32 s63, s63, 0
	global_load_dword v97, v233, s[62:63]
	s_add_u32 s62, s62, 0x1800
	s_addc_u32 s63, s63, 0
	s_mov_b64 s[44:45], s[62:63]
	s_mov_b32 s62, -1
	s_mov_b32 s63, 0xffff
	s_mov_b64 exec, s[62:63]
	v_lshlrev_b32_e32 v64, 16, v66
	v_and_b32_e32 v65, 0xffff0000, v66
	v_fma_f32 v242, v58, v48, v56
	v_fma_f32 v243, v59, v49, v57
	v_lshlrev_b32_e32 v58, 16, v67
	v_and_b32_e32 v59, 0xffff0000, v67
	v_fma_f32 v244, v60, v48, v56
	v_fma_f32 v245, v61, v49, v57
	v_fma_f32 v242, v60, v50, v242
	v_fma_f32 v243, v61, v51, v243
	v_fma_f32 v244, v62, v50, v244
	v_fma_f32 v245, v63, v51, v245
	v_fma_f32 v242, v62, v52, v242
	v_fma_f32 v243, v63, v53, v243
	v_fma_f32 v244, v64, v52, v244
	v_fma_f32 v245, v65, v53, v245
	v_fma_f32 v242, v64, v54, v242
	v_fma_f32 v243, v65, v55, v243
	v_fma_f32 v244, v58, v54, v244
	v_fma_f32 v245, v59, v55, v245
	ds_write_b64 v226, v[242:243] offset:0
	v_cvt_pk_bf16_f32 v246, v242, v243
	ds_write_b64 v226, v[244:245] offset:400
	v_cvt_pk_bf16_f32 v247, v244, v245
	ds_write_b32 v227, v246 offset:0
	ds_write_b32 v227, v247 offset:208
	v_lshlrev_b32_e32 v60, 16, v68
	v_and_b32_e32 v61, 0xffff0000, v68
	v_fma_f32 v242, v62, v48, v56
	v_fma_f32 v243, v63, v49, v57
	v_lshlrev_b32_e32 v62, 16, v69
	v_and_b32_e32 v63, 0xffff0000, v69
	v_fma_f32 v244, v64, v48, v56
	v_fma_f32 v245, v65, v49, v57
	v_fma_f32 v242, v64, v50, v242
	v_fma_f32 v243, v65, v51, v243
	v_fma_f32 v244, v58, v50, v244
	v_fma_f32 v245, v59, v51, v245
	v_fma_f32 v242, v58, v52, v242
	v_fma_f32 v243, v59, v53, v243
	v_fma_f32 v244, v60, v52, v244
	v_fma_f32 v245, v61, v53, v245
	v_fma_f32 v242, v60, v54, v242
	v_fma_f32 v243, v61, v55, v243
	v_fma_f32 v244, v62, v54, v244
	v_fma_f32 v245, v63, v55, v245
	ds_write_b64 v226, v[242:243] offset:800
	v_cvt_pk_bf16_f32 v246, v242, v243
	ds_write_b64 v226, v[244:245] offset:1200
	v_cvt_pk_bf16_f32 v247, v244, v245
	ds_write_b32 v227, v246 offset:416
	ds_write_b32 v227, v247 offset:624
	v_lshlrev_b32_e32 v64, 16, v70
	v_and_b32_e32 v65, 0xffff0000, v70
	v_fma_f32 v242, v58, v48, v56
	v_fma_f32 v243, v59, v49, v57
	v_lshlrev_b32_e32 v58, 16, v71
	v_and_b32_e32 v59, 0xffff0000, v71
	v_fma_f32 v244, v60, v48, v56
	v_fma_f32 v245, v61, v49, v57
	v_fma_f32 v242, v60, v50, v242
	v_fma_f32 v243, v61, v51, v243
	v_fma_f32 v244, v62, v50, v244
	v_fma_f32 v245, v63, v51, v245
	v_fma_f32 v242, v62, v52, v242
	v_fma_f32 v243, v63, v53, v243
	v_fma_f32 v244, v64, v52, v244
	v_fma_f32 v245, v65, v53, v245
	v_fma_f32 v242, v64, v54, v242
	v_fma_f32 v243, v65, v55, v243
	v_fma_f32 v244, v58, v54, v244
	v_fma_f32 v245, v59, v55, v245
	ds_write_b64 v226, v[242:243] offset:1600
	v_cvt_pk_bf16_f32 v246, v242, v243
	ds_write_b64 v226, v[244:245] offset:2000
	v_cvt_pk_bf16_f32 v247, v244, v245
	ds_write_b32 v227, v246 offset:832
	ds_write_b32 v227, v247 offset:1040
	v_lshlrev_b32_e32 v60, 16, v72
	v_and_b32_e32 v61, 0xffff0000, v72
	v_fma_f32 v242, v62, v48, v56
	v_fma_f32 v243, v63, v49, v57
	v_lshlrev_b32_e32 v62, 16, v73
	v_and_b32_e32 v63, 0xffff0000, v73
	v_fma_f32 v244, v64, v48, v56
	v_fma_f32 v245, v65, v49, v57
	v_fma_f32 v242, v64, v50, v242
	v_fma_f32 v243, v65, v51, v243
	v_fma_f32 v244, v58, v50, v244
	v_fma_f32 v245, v59, v51, v245
	v_fma_f32 v242, v58, v52, v242
	v_fma_f32 v243, v59, v53, v243
	v_fma_f32 v244, v60, v52, v244
	v_fma_f32 v245, v61, v53, v245
	v_fma_f32 v242, v60, v54, v242
	v_fma_f32 v243, v61, v55, v243
	v_fma_f32 v244, v62, v54, v244
	v_fma_f32 v245, v63, v55, v245
	ds_write_b64 v226, v[242:243] offset:2400
	v_cvt_pk_bf16_f32 v246, v242, v243
	ds_write_b64 v226, v[244:245] offset:2800
	v_cvt_pk_bf16_f32 v247, v244, v245
	ds_write_b32 v227, v246 offset:1248
	ds_write_b32 v227, v247 offset:1456
	v_lshlrev_b32_e32 v64, 16, v74
	v_and_b32_e32 v65, 0xffff0000, v74
	v_fma_f32 v242, v58, v48, v56
	v_fma_f32 v243, v59, v49, v57
	v_lshlrev_b32_e32 v58, 16, v75
	v_and_b32_e32 v59, 0xffff0000, v75
	v_fma_f32 v244, v60, v48, v56
	v_fma_f32 v245, v61, v49, v57
	v_fma_f32 v242, v60, v50, v242
	v_fma_f32 v243, v61, v51, v243
	v_fma_f32 v244, v62, v50, v244
	v_fma_f32 v245, v63, v51, v245
	v_fma_f32 v242, v62, v52, v242
	v_fma_f32 v243, v63, v53, v243
	v_fma_f32 v244, v64, v52, v244
	v_fma_f32 v245, v65, v53, v245
	v_fma_f32 v242, v64, v54, v242
	v_fma_f32 v243, v65, v55, v243
	v_fma_f32 v244, v58, v54, v244
	v_fma_f32 v245, v59, v55, v245
	ds_write_b64 v226, v[242:243] offset:3200
	v_cvt_pk_bf16_f32 v246, v242, v243
	ds_write_b64 v226, v[244:245] offset:3600
	v_cvt_pk_bf16_f32 v247, v244, v245
	ds_write_b32 v227, v246 offset:1664
	ds_write_b32 v227, v247 offset:1872
	v_lshlrev_b32_e32 v60, 16, v76
	v_and_b32_e32 v61, 0xffff0000, v76
	v_fma_f32 v242, v62, v48, v56
	v_fma_f32 v243, v63, v49, v57
	v_lshlrev_b32_e32 v62, 16, v77
	v_and_b32_e32 v63, 0xffff0000, v77
	v_fma_f32 v244, v64, v48, v56
	v_fma_f32 v245, v65, v49, v57
	v_fma_f32 v242, v64, v50, v242
	v_fma_f32 v243, v65, v51, v243
	v_fma_f32 v244, v58, v50, v244
	v_fma_f32 v245, v59, v51, v245
	v_fma_f32 v242, v58, v52, v242
	v_fma_f32 v243, v59, v53, v243
	v_fma_f32 v244, v60, v52, v244
	v_fma_f32 v245, v61, v53, v245
	v_fma_f32 v242, v60, v54, v242
	v_fma_f32 v243, v61, v55, v243
	v_fma_f32 v244, v62, v54, v244
	v_fma_f32 v245, v63, v55, v245
	ds_write_b64 v226, v[242:243] offset:4000
	v_cvt_pk_bf16_f32 v246, v242, v243
	ds_write_b64 v226, v[244:245] offset:4400
	v_cvt_pk_bf16_f32 v247, v244, v245
	ds_write_b32 v227, v246 offset:2080
	ds_write_b32 v227, v247 offset:2288
	v_lshlrev_b32_e32 v64, 16, v78
	v_and_b32_e32 v65, 0xffff0000, v78
	v_fma_f32 v242, v58, v48, v56
	v_fma_f32 v243, v59, v49, v57
	v_lshlrev_b32_e32 v58, 16, v79
	v_and_b32_e32 v59, 0xffff0000, v79
	v_fma_f32 v244, v60, v48, v56
	v_fma_f32 v245, v61, v49, v57
	v_fma_f32 v242, v60, v50, v242
	v_fma_f32 v243, v61, v51, v243
	v_fma_f32 v244, v62, v50, v244
	v_fma_f32 v245, v63, v51, v245
	v_fma_f32 v242, v62, v52, v242
	v_fma_f32 v243, v63, v53, v243
	v_fma_f32 v244, v64, v52, v244
	v_fma_f32 v245, v65, v53, v245
	v_fma_f32 v242, v64, v54, v242
	v_fma_f32 v243, v65, v55, v243
	v_fma_f32 v244, v58, v54, v244
	v_fma_f32 v245, v59, v55, v245
	ds_write_b64 v226, v[242:243] offset:4800
	v_cvt_pk_bf16_f32 v246, v242, v243
	ds_write_b64 v226, v[244:245] offset:5200
	v_cvt_pk_bf16_f32 v247, v244, v245
	ds_write_b32 v227, v246 offset:2496
	ds_write_b32 v227, v247 offset:2704
	v_lshlrev_b32_e32 v60, 16, v80
	v_and_b32_e32 v61, 0xffff0000, v80
	v_fma_f32 v242, v62, v48, v56
	v_fma_f32 v243, v63, v49, v57
	v_lshlrev_b32_e32 v62, 16, v81
	v_and_b32_e32 v63, 0xffff0000, v81
	v_fma_f32 v244, v64, v48, v56
	v_fma_f32 v245, v65, v49, v57
	v_fma_f32 v242, v64, v50, v242
	v_fma_f32 v243, v65, v51, v243
	v_fma_f32 v244, v58, v50, v244
	v_fma_f32 v245, v59, v51, v245
	v_fma_f32 v242, v58, v52, v242
	v_fma_f32 v243, v59, v53, v243
	v_fma_f32 v244, v60, v52, v244
	v_fma_f32 v245, v61, v53, v245
	v_fma_f32 v242, v60, v54, v242
	v_fma_f32 v243, v61, v55, v243
	v_fma_f32 v244, v62, v54, v244
	v_fma_f32 v245, v63, v55, v245
	ds_write_b64 v226, v[242:243] offset:5600
	v_cvt_pk_bf16_f32 v246, v242, v243
	ds_write_b64 v226, v[244:245] offset:6000
	v_cvt_pk_bf16_f32 v247, v244, v245
	ds_write_b32 v227, v246 offset:2912
	ds_write_b32 v227, v247 offset:3120
	s_mov_b64 exec, -1
	s_waitcnt lgkmcnt(0)
	ds_read_b128 v[98:101], v228 offset:0
	ds_read_b128 v[102:105], v228 offset:64
	ds_read_b128 v[106:109], v228 offset:128
	ds_read_b128 v[110:113], v229 offset:0
	ds_read_b128 v[122:125], v229 offset:19968
	ds_read_b128 v[114:117], v229 offset:64
	ds_read_b128 v[126:129], v229 offset:20032
	ds_read_b128 v[118:121], v229 offset:128
	ds_read_b128 v[130:133], v229 offset:20096
	ds_read_b128 v[150:153], v230 offset:0
	ds_read_b128 v[154:157], v230 offset:384
	ds_read_b128 v[158:161], v230 offset:768
	ds_read_b128 v[162:165], v231 offset:0
	s_waitcnt lgkmcnt(0)
	v_mfma_f32_16x16x32_bf16 v[134:137], v[110:113], v[98:101], 0
	v_mfma_f32_16x16x32_bf16 v[138:141], v[122:125], v[98:101], 0
	v_mfma_f32_16x16x32_bf16 v[134:137], v[114:117], v[102:105], v[134:137]
	v_mfma_f32_16x16x32_bf16 v[138:141], v[126:129], v[102:105], v[138:141]
	v_mfma_f32_16x16x32_bf16 v[134:137], v[118:121], v[106:109], v[134:137]
	v_mfma_f32_16x16x32_bf16 v[138:141], v[130:133], v[106:109], v[138:141]
	ds_read_b128 v[110:113], v229 offset:3328
	ds_read_b128 v[122:125], v229 offset:23296
	ds_read_b128 v[114:117], v229 offset:3392
	ds_read_b128 v[126:129], v229 offset:23360
	ds_read_b128 v[118:121], v229 offset:3456
	ds_read_b128 v[130:133], v229 offset:23424
	s_nop 7
	s_nop 7
	v_add_f32_e32 v166, v134, v150
	v_add_f32_e32 v204, v135, v151
	v_add_f32_e32 v210, v136, v152
	v_add_f32_e32 v216, v137, v153
	v_add_f32_e32 v167, v138, v154
	v_add_f32_e32 v205, v139, v155
	v_add_f32_e32 v211, v140, v156
	v_add_f32_e32 v217, v141, v157
	v_mul_f32_e32 v166, 0xbfb8aa3b, v166
	v_mul_f32_e32 v204, 0xbfb8aa3b, v204
	v_mul_f32_e32 v210, 0xbfb8aa3b, v210
	v_mul_f32_e32 v216, 0xbfb8aa3b, v216
	v_mul_f32_e32 v167, 0xbfb8aa3b, v167
	v_mul_f32_e32 v205, 0xbfb8aa3b, v205
	v_mul_f32_e32 v211, 0xbfb8aa3b, v211
	v_mul_f32_e32 v217, 0xbfb8aa3b, v217
	v_exp_f32_e32 v166, v166
	v_exp_f32_e32 v204, v204
	v_exp_f32_e32 v210, v210
	v_exp_f32_e32 v216, v216
	v_exp_f32_e32 v167, v167
	v_exp_f32_e32 v205, v205
	v_exp_f32_e32 v211, v211
	v_exp_f32_e32 v217, v217
	v_add_f32_e32 v166, 1.0, v166
	v_add_f32_e32 v204, 1.0, v204
	v_add_f32_e32 v210, 1.0, v210
	v_add_f32_e32 v216, 1.0, v216
	v_add_f32_e32 v167, 1.0, v167
	v_add_f32_e32 v205, 1.0, v205
	v_add_f32_e32 v211, 1.0, v211
	v_add_f32_e32 v217, 1.0, v217
	v_rcp_f32_e32 v166, v166
	v_rcp_f32_e32 v204, v204
	v_rcp_f32_e32 v210, v210
	v_rcp_f32_e32 v216, v216
	v_rcp_f32_e32 v167, v167
	v_rcp_f32_e32 v205, v205
	v_rcp_f32_e32 v211, v211
	v_rcp_f32_e32 v217, v217
	v_mul_f32_e32 v168, 0xc1000000, v166
	v_mul_f32_e32 v206, 0xc1000000, v204
	v_mul_f32_e32 v212, 0xc1000000, v210
	v_mul_f32_e32 v218, 0xc1000000, v216
	v_mul_f32_e32 v168, v158, v168
	v_mul_f32_e32 v206, v159, v206
	v_mul_f32_e32 v212, v160, v212
	v_mul_f32_e32 v218, v161, v218
	v_add_f32_e32 v169, v168, v168
	v_add_f32_e32 v207, v206, v206
	v_add_f32_e32 v213, v212, v212
	v_add_f32_e32 v219, v218, v218
	v_mul_f32_e32 v171, 0x3fb8aa3b, v169
	v_mul_f32_e32 v209, 0x3fb8aa3b, v207
	v_mul_f32_e32 v215, 0x3fb8aa3b, v213
	v_mul_f32_e32 v221, 0x3fb8aa3b, v219
	v_fmamk_f32 v170, v169, 0x3c088888, v195
	v_fmamk_f32 v208, v207, 0x3c088888, v195
	v_fmamk_f32 v214, v213, 0x3c088888, v195
	v_fmamk_f32 v220, v219, 0x3c088888, v195
	v_exp_f32_e32 v171, v171
	v_exp_f32_e32 v209, v209
	v_exp_f32_e32 v215, v215
	v_exp_f32_e32 v221, v221
	v_fmaak_f32 v170, v169, v170, 0x3e2aaaab
	v_fmaak_f32 v208, v207, v208, 0x3e2aaaab
	v_fmaak_f32 v214, v213, v214, 0x3e2aaaab
	v_fmaak_f32 v220, v219, v220, 0x3e2aaaab
	v_fma_f32 v170, v169, v170, 0.5
	v_fma_f32 v208, v207, v208, 0.5
	v_fma_f32 v214, v213, v214, 0.5
	v_fma_f32 v220, v219, v220, 0.5
	v_fma_f32 v170, v169, v170, 1.0
	v_fma_f32 v208, v207, v208, 1.0
	v_fma_f32 v214, v213, v214, 1.0
	v_fma_f32 v220, v219, v220, 1.0
	v_sub_f32_e32 v171, 1.0, v171
	v_sub_f32_e32 v209, 1.0, v209
	v_sub_f32_e32 v215, 1.0, v215
	v_sub_f32_e32 v221, 1.0, v221
	v_mul_f32_e64 v170, v170, -v169
	v_mul_f32_e64 v208, v208, -v207
	v_mul_f32_e64 v214, v214, -v213
	v_mul_f32_e64 v220, v220, -v219
	v_cmp_nlt_f32_e32 vcc, s1, v169
	v_cmp_nlt_f32_e64 s[62:63], s1, v207
	v_cmp_nlt_f32_e64 s[56:57], s1, v213
	v_mul_f32_e32 v167, v162, v167
	v_mul_f32_e32 v205, v163, v205
	v_mul_f32_e32 v211, v164, v211
	v_mul_f32_e32 v217, v165, v217
	v_cndmask_b32_e32 v170, v170, v171, vcc
	v_cmp_nlt_f32_e32 vcc, s1, v219
	v_cndmask_b32_e64 v208, v208, v209, s[62:63]
	v_cndmask_b32_e64 v214, v214, v215, s[56:57]
	v_mul_f32_e32 v166, 0x3fb8aa3b, v168
	v_mul_f32_e32 v204, 0x3fb8aa3b, v206
	v_mul_f32_e32 v210, 0x3fb8aa3b, v212
	v_mul_f32_e32 v216, 0x3fb8aa3b, v218
	v_cndmask_b32_e32 v220, v220, v221, vcc
	v_sqrt_f32_e32 v170, v170
	v_sqrt_f32_e32 v208, v208
	v_sqrt_f32_e32 v214, v214
	v_sqrt_f32_e32 v220, v220
	v_exp_f32_e32 v166, v166
	v_exp_f32_e32 v204, v204
	v_exp_f32_e32 v210, v210
	v_exp_f32_e32 v216, v216
	v_mul_f32_e32 v167, v167, v170
	v_mul_f32_e32 v205, v205, v208
	v_mul_f32_e32 v211, v211, v214
	v_mul_f32_e32 v217, v217, v220
	ds_read_b128 v[150:153], v230 offset:64
	ds_read_b128 v[154:157], v230 offset:448
	ds_read_b128 v[158:161], v230 offset:832
	ds_read_b128 v[162:165], v231 offset:64
	s_waitcnt lgkmcnt(0)
	v_mfma_f32_16x16x32_bf16 v[142:145], v[110:113], v[98:101], 0
	v_mfma_f32_16x16x32_bf16 v[146:149], v[122:125], v[98:101], 0
	v_mfma_f32_16x16x32_bf16 v[142:145], v[114:117], v[102:105], v[142:145]
	v_mfma_f32_16x16x32_bf16 v[146:149], v[126:129], v[102:105], v[146:149]
	v_mfma_f32_16x16x32_bf16 v[142:145], v[118:121], v[106:109], v[142:145]
	v_mfma_f32_16x16x32_bf16 v[146:149], v[130:133], v[106:109], v[146:149]
	v_fmac_f32_dpp v167, v167, v166 row_shr:1 row_mask:0xf bank_mask:0xf bound_ctrl:1
	v_fmac_f32_dpp v205, v205, v204 row_shr:1 row_mask:0xf bank_mask:0xf bound_ctrl:1
	v_fmac_f32_dpp v211, v211, v210 row_shr:1 row_mask:0xf bank_mask:0xf bound_ctrl:1
	v_fmac_f32_dpp v217, v217, v216 row_shr:1 row_mask:0xf bank_mask:0xf bound_ctrl:1
	v_mul_f32_dpp v166, v166, v166 row_shr:1 row_mask:0xf bank_mask:0xf
	v_mul_f32_dpp v204, v204, v204 row_shr:1 row_mask:0xf bank_mask:0xf
	v_mul_f32_dpp v210, v210, v210 row_shr:1 row_mask:0xf bank_mask:0xf
	v_mul_f32_dpp v216, v216, v216 row_shr:1 row_mask:0xf bank_mask:0xf
	v_fmac_f32_dpp v167, v167, v166 row_shr:2 row_mask:0xf bank_mask:0xf bound_ctrl:1
	v_fmac_f32_dpp v205, v205, v204 row_shr:2 row_mask:0xf bank_mask:0xf bound_ctrl:1
	v_fmac_f32_dpp v211, v211, v210 row_shr:2 row_mask:0xf bank_mask:0xf bound_ctrl:1
	v_fmac_f32_dpp v217, v217, v216 row_shr:2 row_mask:0xf bank_mask:0xf bound_ctrl:1
	v_mul_f32_dpp v166, v166, v166 row_shr:2 row_mask:0xf bank_mask:0xf
	v_mul_f32_dpp v204, v204, v204 row_shr:2 row_mask:0xf bank_mask:0xf
	v_mul_f32_dpp v210, v210, v210 row_shr:2 row_mask:0xf bank_mask:0xf
	v_mul_f32_dpp v216, v216, v216 row_shr:2 row_mask:0xf bank_mask:0xf
	v_fmac_f32_dpp v167, v167, v166 row_shr:4 row_mask:0xf bank_mask:0xf bound_ctrl:1
	v_fmac_f32_dpp v205, v205, v204 row_shr:4 row_mask:0xf bank_mask:0xf bound_ctrl:1
	v_fmac_f32_dpp v211, v211, v210 row_shr:4 row_mask:0xf bank_mask:0xf bound_ctrl:1
	v_fmac_f32_dpp v217, v217, v216 row_shr:4 row_mask:0xf bank_mask:0xf bound_ctrl:1
	v_mul_f32_dpp v166, v166, v166 row_shr:4 row_mask:0xf bank_mask:0xf
	v_mul_f32_dpp v204, v204, v204 row_shr:4 row_mask:0xf bank_mask:0xf
	v_mul_f32_dpp v210, v210, v210 row_shr:4 row_mask:0xf bank_mask:0xf
	v_mul_f32_dpp v216, v216, v216 row_shr:4 row_mask:0xf bank_mask:0xf
	v_fmac_f32_dpp v167, v167, v166 row_shr:8 row_mask:0xf bank_mask:0xf bound_ctrl:1
	v_fmac_f32_dpp v205, v205, v204 row_shr:8 row_mask:0xf bank_mask:0xf bound_ctrl:1
	v_fmac_f32_dpp v211, v211, v210 row_shr:8 row_mask:0xf bank_mask:0xf bound_ctrl:1
	v_fmac_f32_dpp v217, v217, v216 row_shr:8 row_mask:0xf bank_mask:0xf bound_ctrl:1
	v_mul_f32_dpp v166, v166, v166 row_shr:8 row_mask:0xf bank_mask:0xf
	v_mul_f32_dpp v204, v204, v204 row_shr:8 row_mask:0xf bank_mask:0xf
	v_mul_f32_dpp v210, v210, v210 row_shr:8 row_mask:0xf bank_mask:0xf
	v_mul_f32_dpp v216, v216, v216 row_shr:8 row_mask:0xf bank_mask:0xf
	v_fma_f32 v168, v166, v0, v167
	v_fma_f32 v206, v204, v1, v205
	v_fma_f32 v212, v210, v2, v211
	v_fma_f32 v218, v216, v3, v217
	ds_bpermute_b32 v0, v232, v168
	ds_bpermute_b32 v1, v232, v206
	ds_bpermute_b32 v2, v232, v212
	ds_bpermute_b32 v3, v232, v218
	ds_bpermute_b32 v222, v232, v166
	ds_bpermute_b32 v223, v232, v204
	ds_bpermute_b32 v224, v232, v210
	ds_bpermute_b32 v225, v232, v216
	ds_read_b128 v[110:113], v229 offset:6656
	ds_read_b128 v[122:125], v229 offset:26624
	ds_read_b128 v[114:117], v229 offset:6720
	ds_read_b128 v[126:129], v229 offset:26688
	ds_read_b128 v[118:121], v229 offset:6784
	ds_read_b128 v[130:133], v229 offset:26752
	v_add_f32_e32 v166, v142, v150
	v_add_f32_e32 v204, v143, v151
	v_add_f32_e32 v210, v144, v152
	v_add_f32_e32 v216, v145, v153
	v_add_f32_e32 v167, v146, v154
	v_add_f32_e32 v205, v147, v155
	v_add_f32_e32 v211, v148, v156
	v_add_f32_e32 v217, v149, v157
	v_mul_f32_e32 v166, 0xbfb8aa3b, v166
	v_mul_f32_e32 v204, 0xbfb8aa3b, v204
	v_mul_f32_e32 v210, 0xbfb8aa3b, v210
	v_mul_f32_e32 v216, 0xbfb8aa3b, v216
	v_mul_f32_e32 v167, 0xbfb8aa3b, v167
	v_mul_f32_e32 v205, 0xbfb8aa3b, v205
	v_mul_f32_e32 v211, 0xbfb8aa3b, v211
	v_mul_f32_e32 v217, 0xbfb8aa3b, v217
	v_exp_f32_e32 v166, v166
	v_exp_f32_e32 v204, v204
	v_exp_f32_e32 v210, v210
	v_exp_f32_e32 v216, v216
	v_exp_f32_e32 v167, v167
	v_exp_f32_e32 v205, v205
	v_exp_f32_e32 v211, v211
	v_exp_f32_e32 v217, v217
	v_add_f32_e32 v166, 1.0, v166
	v_add_f32_e32 v204, 1.0, v204
	v_add_f32_e32 v210, 1.0, v210
	v_add_f32_e32 v216, 1.0, v216
	v_add_f32_e32 v167, 1.0, v167
	v_add_f32_e32 v205, 1.0, v205
	v_add_f32_e32 v211, 1.0, v211
	v_add_f32_e32 v217, 1.0, v217
	v_rcp_f32_e32 v166, v166
	v_rcp_f32_e32 v204, v204
	v_rcp_f32_e32 v210, v210
	v_rcp_f32_e32 v216, v216
	v_rcp_f32_e32 v167, v167
	v_rcp_f32_e32 v205, v205
	v_rcp_f32_e32 v211, v211
	v_rcp_f32_e32 v217, v217
	v_mul_f32_e32 v168, 0xc1000000, v166
	v_mul_f32_e32 v206, 0xc1000000, v204
	v_mul_f32_e32 v212, 0xc1000000, v210
	v_mul_f32_e32 v218, 0xc1000000, v216
	v_mul_f32_e32 v168, v158, v168
	v_mul_f32_e32 v206, v159, v206
	v_mul_f32_e32 v212, v160, v212
	v_mul_f32_e32 v218, v161, v218
	v_add_f32_e32 v169, v168, v168
	v_add_f32_e32 v207, v206, v206
	v_add_f32_e32 v213, v212, v212
	v_add_f32_e32 v219, v218, v218
	v_mul_f32_e32 v171, 0x3fb8aa3b, v169
	v_mul_f32_e32 v209, 0x3fb8aa3b, v207
	v_mul_f32_e32 v215, 0x3fb8aa3b, v213
	v_mul_f32_e32 v221, 0x3fb8aa3b, v219
	v_fmamk_f32 v170, v169, 0x3c088888, v195
	v_fmamk_f32 v208, v207, 0x3c088888, v195
	v_fmamk_f32 v214, v213, 0x3c088888, v195
	v_fmamk_f32 v220, v219, 0x3c088888, v195
	v_exp_f32_e32 v171, v171
	v_exp_f32_e32 v209, v209
	v_exp_f32_e32 v215, v215
	v_exp_f32_e32 v221, v221
	v_fmaak_f32 v170, v169, v170, 0x3e2aaaab
	v_fmaak_f32 v208, v207, v208, 0x3e2aaaab
	v_fmaak_f32 v214, v213, v214, 0x3e2aaaab
	v_fmaak_f32 v220, v219, v220, 0x3e2aaaab
	v_fma_f32 v170, v169, v170, 0.5
	v_fma_f32 v208, v207, v208, 0.5
	v_fma_f32 v214, v213, v214, 0.5
	v_fma_f32 v220, v219, v220, 0.5
	v_fma_f32 v170, v169, v170, 1.0
	v_fma_f32 v208, v207, v208, 1.0
	v_fma_f32 v214, v213, v214, 1.0
	v_fma_f32 v220, v219, v220, 1.0
	v_sub_f32_e32 v171, 1.0, v171
	v_sub_f32_e32 v209, 1.0, v209
	v_sub_f32_e32 v215, 1.0, v215
	v_sub_f32_e32 v221, 1.0, v221
	v_mul_f32_e64 v170, v170, -v169
	v_mul_f32_e64 v208, v208, -v207
	v_mul_f32_e64 v214, v214, -v213
	v_mul_f32_e64 v220, v220, -v219
	v_cmp_nlt_f32_e32 vcc, s1, v169
	v_cmp_nlt_f32_e64 s[62:63], s1, v207
	v_cmp_nlt_f32_e64 s[56:57], s1, v213
	v_mul_f32_e32 v167, v162, v167
	v_mul_f32_e32 v205, v163, v205
	v_mul_f32_e32 v211, v164, v211
	v_mul_f32_e32 v217, v165, v217
	v_cndmask_b32_e32 v170, v170, v171, vcc
	v_cmp_nlt_f32_e32 vcc, s1, v219
	v_cndmask_b32_e64 v208, v208, v209, s[62:63]
	v_cndmask_b32_e64 v214, v214, v215, s[56:57]
	v_mul_f32_e32 v166, 0x3fb8aa3b, v168
	v_mul_f32_e32 v204, 0x3fb8aa3b, v206
	v_mul_f32_e32 v210, 0x3fb8aa3b, v212
	v_mul_f32_e32 v216, 0x3fb8aa3b, v218
	v_cndmask_b32_e32 v220, v220, v221, vcc
	v_sqrt_f32_e32 v170, v170
	v_sqrt_f32_e32 v208, v208
	v_sqrt_f32_e32 v214, v214
	v_sqrt_f32_e32 v220, v220
	v_exp_f32_e32 v166, v166
	v_exp_f32_e32 v204, v204
	v_exp_f32_e32 v210, v210
	v_exp_f32_e32 v216, v216
	v_mul_f32_e32 v167, v167, v170
	v_mul_f32_e32 v205, v205, v208
	v_mul_f32_e32 v211, v211, v214
	v_mul_f32_e32 v217, v217, v220
	ds_read_b128 v[150:153], v230 offset:128
	ds_read_b128 v[154:157], v230 offset:512
	ds_read_b128 v[158:161], v230 offset:896
	ds_read_b128 v[162:165], v231 offset:128
	s_waitcnt lgkmcnt(0)
	v_mul_f32_e32 v24, v24, v222
	v_mul_f32_e32 v25, v25, v223
	v_mul_f32_e32 v26, v26, v224
	v_mul_f32_e32 v27, v27, v225
	v_mfma_f32_16x16x32_bf16 v[134:137], v[110:113], v[98:101], 0
	v_mfma_f32_16x16x32_bf16 v[138:141], v[122:125], v[98:101], 0
	v_mfma_f32_16x16x32_bf16 v[134:137], v[114:117], v[102:105], v[134:137]
	v_mfma_f32_16x16x32_bf16 v[138:141], v[126:129], v[102:105], v[138:141]
	v_mfma_f32_16x16x32_bf16 v[134:137], v[118:121], v[106:109], v[134:137]
	v_mfma_f32_16x16x32_bf16 v[138:141], v[130:133], v[106:109], v[138:141]
	v_fmac_f32_dpp v167, v167, v166 row_shr:1 row_mask:0xf bank_mask:0xf bound_ctrl:1
	v_fmac_f32_dpp v205, v205, v204 row_shr:1 row_mask:0xf bank_mask:0xf bound_ctrl:1
	v_fmac_f32_dpp v211, v211, v210 row_shr:1 row_mask:0xf bank_mask:0xf bound_ctrl:1
	v_fmac_f32_dpp v217, v217, v216 row_shr:1 row_mask:0xf bank_mask:0xf bound_ctrl:1
	v_mul_f32_dpp v166, v166, v166 row_shr:1 row_mask:0xf bank_mask:0xf
	v_mul_f32_dpp v204, v204, v204 row_shr:1 row_mask:0xf bank_mask:0xf
	v_mul_f32_dpp v210, v210, v210 row_shr:1 row_mask:0xf bank_mask:0xf
	v_mul_f32_dpp v216, v216, v216 row_shr:1 row_mask:0xf bank_mask:0xf
	v_fmac_f32_dpp v167, v167, v166 row_shr:2 row_mask:0xf bank_mask:0xf bound_ctrl:1
	v_fmac_f32_dpp v205, v205, v204 row_shr:2 row_mask:0xf bank_mask:0xf bound_ctrl:1
	v_fmac_f32_dpp v211, v211, v210 row_shr:2 row_mask:0xf bank_mask:0xf bound_ctrl:1
	v_fmac_f32_dpp v217, v217, v216 row_shr:2 row_mask:0xf bank_mask:0xf bound_ctrl:1
	v_mul_f32_dpp v166, v166, v166 row_shr:2 row_mask:0xf bank_mask:0xf
	v_mul_f32_dpp v204, v204, v204 row_shr:2 row_mask:0xf bank_mask:0xf
	v_mul_f32_dpp v210, v210, v210 row_shr:2 row_mask:0xf bank_mask:0xf
	v_mul_f32_dpp v216, v216, v216 row_shr:2 row_mask:0xf bank_mask:0xf
	v_fmac_f32_dpp v167, v167, v166 row_shr:4 row_mask:0xf bank_mask:0xf bound_ctrl:1
	v_fmac_f32_dpp v205, v205, v204 row_shr:4 row_mask:0xf bank_mask:0xf bound_ctrl:1
	v_fmac_f32_dpp v211, v211, v210 row_shr:4 row_mask:0xf bank_mask:0xf bound_ctrl:1
	v_fmac_f32_dpp v217, v217, v216 row_shr:4 row_mask:0xf bank_mask:0xf bound_ctrl:1
	v_mul_f32_dpp v166, v166, v166 row_shr:4 row_mask:0xf bank_mask:0xf
	v_mul_f32_dpp v204, v204, v204 row_shr:4 row_mask:0xf bank_mask:0xf
	v_mul_f32_dpp v210, v210, v210 row_shr:4 row_mask:0xf bank_mask:0xf
	v_mul_f32_dpp v216, v216, v216 row_shr:4 row_mask:0xf bank_mask:0xf
	v_fmac_f32_dpp v167, v167, v166 row_shr:8 row_mask:0xf bank_mask:0xf bound_ctrl:1
	v_fmac_f32_dpp v205, v205, v204 row_shr:8 row_mask:0xf bank_mask:0xf bound_ctrl:1
	v_fmac_f32_dpp v211, v211, v210 row_shr:8 row_mask:0xf bank_mask:0xf bound_ctrl:1
	v_fmac_f32_dpp v217, v217, v216 row_shr:8 row_mask:0xf bank_mask:0xf bound_ctrl:1
	v_mul_f32_dpp v166, v166, v166 row_shr:8 row_mask:0xf bank_mask:0xf
	v_mul_f32_dpp v204, v204, v204 row_shr:8 row_mask:0xf bank_mask:0xf
	v_mul_f32_dpp v210, v210, v210 row_shr:8 row_mask:0xf bank_mask:0xf
	v_mul_f32_dpp v216, v216, v216 row_shr:8 row_mask:0xf bank_mask:0xf
	v_fma_f32 v168, v166, v4, v167
	v_fma_f32 v206, v204, v5, v205
	v_fma_f32 v212, v210, v6, v211
	v_fma_f32 v218, v216, v7, v217
	ds_bpermute_b32 v4, v232, v168
	ds_bpermute_b32 v5, v232, v206
	ds_bpermute_b32 v6, v232, v212
	ds_bpermute_b32 v7, v232, v218
	ds_bpermute_b32 v222, v232, v166
	ds_bpermute_b32 v223, v232, v204
	ds_bpermute_b32 v224, v232, v210
	ds_bpermute_b32 v225, v232, v216
	ds_read_b128 v[110:113], v229 offset:9984
	ds_read_b128 v[122:125], v229 offset:29952
	ds_read_b128 v[114:117], v229 offset:10048
	ds_read_b128 v[126:129], v229 offset:30016
	ds_read_b128 v[118:121], v229 offset:10112
	ds_read_b128 v[130:133], v229 offset:30080
	v_add_f32_e32 v166, v134, v150
	v_add_f32_e32 v204, v135, v151
	v_add_f32_e32 v210, v136, v152
	v_add_f32_e32 v216, v137, v153
	v_add_f32_e32 v167, v138, v154
	v_add_f32_e32 v205, v139, v155
	v_add_f32_e32 v211, v140, v156
	v_add_f32_e32 v217, v141, v157
	v_mul_f32_e32 v166, 0xbfb8aa3b, v166
	v_mul_f32_e32 v204, 0xbfb8aa3b, v204
	v_mul_f32_e32 v210, 0xbfb8aa3b, v210
	v_mul_f32_e32 v216, 0xbfb8aa3b, v216
	v_mul_f32_e32 v167, 0xbfb8aa3b, v167
	v_mul_f32_e32 v205, 0xbfb8aa3b, v205
	v_mul_f32_e32 v211, 0xbfb8aa3b, v211
	v_mul_f32_e32 v217, 0xbfb8aa3b, v217
	v_exp_f32_e32 v166, v166
	v_exp_f32_e32 v204, v204
	v_exp_f32_e32 v210, v210
	v_exp_f32_e32 v216, v216
	v_exp_f32_e32 v167, v167
	v_exp_f32_e32 v205, v205
	v_exp_f32_e32 v211, v211
	v_exp_f32_e32 v217, v217
	v_add_f32_e32 v166, 1.0, v166
	v_add_f32_e32 v204, 1.0, v204
	v_add_f32_e32 v210, 1.0, v210
	v_add_f32_e32 v216, 1.0, v216
	v_add_f32_e32 v167, 1.0, v167
	v_add_f32_e32 v205, 1.0, v205
	v_add_f32_e32 v211, 1.0, v211
	v_add_f32_e32 v217, 1.0, v217
	v_rcp_f32_e32 v166, v166
	v_rcp_f32_e32 v204, v204
	v_rcp_f32_e32 v210, v210
	v_rcp_f32_e32 v216, v216
	v_rcp_f32_e32 v167, v167
	v_rcp_f32_e32 v205, v205
	v_rcp_f32_e32 v211, v211
	v_rcp_f32_e32 v217, v217
	v_mul_f32_e32 v168, 0xc1000000, v166
	v_mul_f32_e32 v206, 0xc1000000, v204
	v_mul_f32_e32 v212, 0xc1000000, v210
	v_mul_f32_e32 v218, 0xc1000000, v216
	v_mul_f32_e32 v168, v158, v168
	v_mul_f32_e32 v206, v159, v206
	v_mul_f32_e32 v212, v160, v212
	v_mul_f32_e32 v218, v161, v218
	v_add_f32_e32 v169, v168, v168
	v_add_f32_e32 v207, v206, v206
	v_add_f32_e32 v213, v212, v212
	v_add_f32_e32 v219, v218, v218
	v_mul_f32_e32 v171, 0x3fb8aa3b, v169
	v_mul_f32_e32 v209, 0x3fb8aa3b, v207
	v_mul_f32_e32 v215, 0x3fb8aa3b, v213
	v_mul_f32_e32 v221, 0x3fb8aa3b, v219
	v_fmamk_f32 v170, v169, 0x3c088888, v195
	v_fmamk_f32 v208, v207, 0x3c088888, v195
	v_fmamk_f32 v214, v213, 0x3c088888, v195
	v_fmamk_f32 v220, v219, 0x3c088888, v195
	v_exp_f32_e32 v171, v171
	v_exp_f32_e32 v209, v209
	v_exp_f32_e32 v215, v215
	v_exp_f32_e32 v221, v221
	v_fmaak_f32 v170, v169, v170, 0x3e2aaaab
	v_fmaak_f32 v208, v207, v208, 0x3e2aaaab
	v_fmaak_f32 v214, v213, v214, 0x3e2aaaab
	v_fmaak_f32 v220, v219, v220, 0x3e2aaaab
	v_fma_f32 v170, v169, v170, 0.5
	v_fma_f32 v208, v207, v208, 0.5
	v_fma_f32 v214, v213, v214, 0.5
	v_fma_f32 v220, v219, v220, 0.5
	v_fma_f32 v170, v169, v170, 1.0
	v_fma_f32 v208, v207, v208, 1.0
	v_fma_f32 v214, v213, v214, 1.0
	v_fma_f32 v220, v219, v220, 1.0
	v_sub_f32_e32 v171, 1.0, v171
	v_sub_f32_e32 v209, 1.0, v209
	v_sub_f32_e32 v215, 1.0, v215
	v_sub_f32_e32 v221, 1.0, v221
	v_mul_f32_e64 v170, v170, -v169
	v_mul_f32_e64 v208, v208, -v207
	v_mul_f32_e64 v214, v214, -v213
	v_mul_f32_e64 v220, v220, -v219
	v_cmp_nlt_f32_e32 vcc, s1, v169
	v_cmp_nlt_f32_e64 s[62:63], s1, v207
	v_cmp_nlt_f32_e64 s[56:57], s1, v213
	v_mul_f32_e32 v167, v162, v167
	v_mul_f32_e32 v205, v163, v205
	v_mul_f32_e32 v211, v164, v211
	v_mul_f32_e32 v217, v165, v217
	v_cndmask_b32_e32 v170, v170, v171, vcc
	v_cmp_nlt_f32_e32 vcc, s1, v219
	v_cndmask_b32_e64 v208, v208, v209, s[62:63]
	v_cndmask_b32_e64 v214, v214, v215, s[56:57]
	v_mul_f32_e32 v166, 0x3fb8aa3b, v168
	v_mul_f32_e32 v204, 0x3fb8aa3b, v206
	v_mul_f32_e32 v210, 0x3fb8aa3b, v212
	v_mul_f32_e32 v216, 0x3fb8aa3b, v218
	v_cndmask_b32_e32 v220, v220, v221, vcc
	v_sqrt_f32_e32 v170, v170
	v_sqrt_f32_e32 v208, v208
	v_sqrt_f32_e32 v214, v214
	v_sqrt_f32_e32 v220, v220
	v_exp_f32_e32 v166, v166
	v_exp_f32_e32 v204, v204
	v_exp_f32_e32 v210, v210
	v_exp_f32_e32 v216, v216
	v_mul_f32_e32 v167, v167, v170
	v_mul_f32_e32 v205, v205, v208
	v_mul_f32_e32 v211, v211, v214
	v_mul_f32_e32 v217, v217, v220
	ds_read_b128 v[150:153], v230 offset:192
	ds_read_b128 v[154:157], v230 offset:576
	ds_read_b128 v[158:161], v230 offset:960
	ds_read_b128 v[162:165], v231 offset:192
	s_waitcnt lgkmcnt(0)
	v_mul_f32_e32 v28, v28, v222
	v_mul_f32_e32 v29, v29, v223
	v_mul_f32_e32 v30, v30, v224
	v_mul_f32_e32 v31, v31, v225
	v_mfma_f32_16x16x32_bf16 v[142:145], v[110:113], v[98:101], 0
	v_mfma_f32_16x16x32_bf16 v[146:149], v[122:125], v[98:101], 0
	v_mfma_f32_16x16x32_bf16 v[142:145], v[114:117], v[102:105], v[142:145]
	v_mfma_f32_16x16x32_bf16 v[146:149], v[126:129], v[102:105], v[146:149]
	v_mfma_f32_16x16x32_bf16 v[142:145], v[118:121], v[106:109], v[142:145]
	v_mfma_f32_16x16x32_bf16 v[146:149], v[130:133], v[106:109], v[146:149]
	v_fmac_f32_dpp v167, v167, v166 row_shr:1 row_mask:0xf bank_mask:0xf bound_ctrl:1
	v_fmac_f32_dpp v205, v205, v204 row_shr:1 row_mask:0xf bank_mask:0xf bound_ctrl:1
	v_fmac_f32_dpp v211, v211, v210 row_shr:1 row_mask:0xf bank_mask:0xf bound_ctrl:1
	v_fmac_f32_dpp v217, v217, v216 row_shr:1 row_mask:0xf bank_mask:0xf bound_ctrl:1
	v_mul_f32_dpp v166, v166, v166 row_shr:1 row_mask:0xf bank_mask:0xf
	v_mul_f32_dpp v204, v204, v204 row_shr:1 row_mask:0xf bank_mask:0xf
	v_mul_f32_dpp v210, v210, v210 row_shr:1 row_mask:0xf bank_mask:0xf
	v_mul_f32_dpp v216, v216, v216 row_shr:1 row_mask:0xf bank_mask:0xf
	v_fmac_f32_dpp v167, v167, v166 row_shr:2 row_mask:0xf bank_mask:0xf bound_ctrl:1
	v_fmac_f32_dpp v205, v205, v204 row_shr:2 row_mask:0xf bank_mask:0xf bound_ctrl:1
	v_fmac_f32_dpp v211, v211, v210 row_shr:2 row_mask:0xf bank_mask:0xf bound_ctrl:1
	v_fmac_f32_dpp v217, v217, v216 row_shr:2 row_mask:0xf bank_mask:0xf bound_ctrl:1
	v_mul_f32_dpp v166, v166, v166 row_shr:2 row_mask:0xf bank_mask:0xf
	v_mul_f32_dpp v204, v204, v204 row_shr:2 row_mask:0xf bank_mask:0xf
	v_mul_f32_dpp v210, v210, v210 row_shr:2 row_mask:0xf bank_mask:0xf
	v_mul_f32_dpp v216, v216, v216 row_shr:2 row_mask:0xf bank_mask:0xf
	v_fmac_f32_dpp v167, v167, v166 row_shr:4 row_mask:0xf bank_mask:0xf bound_ctrl:1
	v_fmac_f32_dpp v205, v205, v204 row_shr:4 row_mask:0xf bank_mask:0xf bound_ctrl:1
	v_fmac_f32_dpp v211, v211, v210 row_shr:4 row_mask:0xf bank_mask:0xf bound_ctrl:1
	v_fmac_f32_dpp v217, v217, v216 row_shr:4 row_mask:0xf bank_mask:0xf bound_ctrl:1
	v_mul_f32_dpp v166, v166, v166 row_shr:4 row_mask:0xf bank_mask:0xf
	v_mul_f32_dpp v204, v204, v204 row_shr:4 row_mask:0xf bank_mask:0xf
	v_mul_f32_dpp v210, v210, v210 row_shr:4 row_mask:0xf bank_mask:0xf
	v_mul_f32_dpp v216, v216, v216 row_shr:4 row_mask:0xf bank_mask:0xf
	v_fmac_f32_dpp v167, v167, v166 row_shr:8 row_mask:0xf bank_mask:0xf bound_ctrl:1
	v_fmac_f32_dpp v205, v205, v204 row_shr:8 row_mask:0xf bank_mask:0xf bound_ctrl:1
	v_fmac_f32_dpp v211, v211, v210 row_shr:8 row_mask:0xf bank_mask:0xf bound_ctrl:1
	v_fmac_f32_dpp v217, v217, v216 row_shr:8 row_mask:0xf bank_mask:0xf bound_ctrl:1
	v_mul_f32_dpp v166, v166, v166 row_shr:8 row_mask:0xf bank_mask:0xf
	v_mul_f32_dpp v204, v204, v204 row_shr:8 row_mask:0xf bank_mask:0xf
	v_mul_f32_dpp v210, v210, v210 row_shr:8 row_mask:0xf bank_mask:0xf
	v_mul_f32_dpp v216, v216, v216 row_shr:8 row_mask:0xf bank_mask:0xf
	v_fma_f32 v168, v166, v8, v167
	v_fma_f32 v206, v204, v9, v205
	v_fma_f32 v212, v210, v10, v211
	v_fma_f32 v218, v216, v11, v217
	ds_bpermute_b32 v8, v232, v168
	ds_bpermute_b32 v9, v232, v206
	ds_bpermute_b32 v10, v232, v212
	ds_bpermute_b32 v11, v232, v218
	ds_bpermute_b32 v222, v232, v166
	ds_bpermute_b32 v223, v232, v204
	ds_bpermute_b32 v224, v232, v210
	ds_bpermute_b32 v225, v232, v216
	ds_read_b128 v[110:113], v229 offset:13312
	ds_read_b128 v[122:125], v229 offset:33280
	ds_read_b128 v[114:117], v229 offset:13376
	ds_read_b128 v[126:129], v229 offset:33344
	ds_read_b128 v[118:121], v229 offset:13440
	ds_read_b128 v[130:133], v229 offset:33408
	v_add_f32_e32 v166, v142, v150
	v_add_f32_e32 v204, v143, v151
	v_add_f32_e32 v210, v144, v152
	v_add_f32_e32 v216, v145, v153
	v_add_f32_e32 v167, v146, v154
	v_add_f32_e32 v205, v147, v155
	v_add_f32_e32 v211, v148, v156
	v_add_f32_e32 v217, v149, v157
	v_mul_f32_e32 v166, 0xbfb8aa3b, v166
	v_mul_f32_e32 v204, 0xbfb8aa3b, v204
	v_mul_f32_e32 v210, 0xbfb8aa3b, v210
	v_mul_f32_e32 v216, 0xbfb8aa3b, v216
	v_mul_f32_e32 v167, 0xbfb8aa3b, v167
	v_mul_f32_e32 v205, 0xbfb8aa3b, v205
	v_mul_f32_e32 v211, 0xbfb8aa3b, v211
	v_mul_f32_e32 v217, 0xbfb8aa3b, v217
	v_exp_f32_e32 v166, v166
	v_exp_f32_e32 v204, v204
	v_exp_f32_e32 v210, v210
	v_exp_f32_e32 v216, v216
	v_exp_f32_e32 v167, v167
	v_exp_f32_e32 v205, v205
	v_exp_f32_e32 v211, v211
	v_exp_f32_e32 v217, v217
	v_add_f32_e32 v166, 1.0, v166
	v_add_f32_e32 v204, 1.0, v204
	v_add_f32_e32 v210, 1.0, v210
	v_add_f32_e32 v216, 1.0, v216
	v_add_f32_e32 v167, 1.0, v167
	v_add_f32_e32 v205, 1.0, v205
	v_add_f32_e32 v211, 1.0, v211
	v_add_f32_e32 v217, 1.0, v217
	v_rcp_f32_e32 v166, v166
	v_rcp_f32_e32 v204, v204
	v_rcp_f32_e32 v210, v210
	v_rcp_f32_e32 v216, v216
	v_rcp_f32_e32 v167, v167
	v_rcp_f32_e32 v205, v205
	v_rcp_f32_e32 v211, v211
	v_rcp_f32_e32 v217, v217
	v_mul_f32_e32 v168, 0xc1000000, v166
	v_mul_f32_e32 v206, 0xc1000000, v204
	v_mul_f32_e32 v212, 0xc1000000, v210
	v_mul_f32_e32 v218, 0xc1000000, v216
	v_mul_f32_e32 v168, v158, v168
	v_mul_f32_e32 v206, v159, v206
	v_mul_f32_e32 v212, v160, v212
	v_mul_f32_e32 v218, v161, v218
	v_add_f32_e32 v169, v168, v168
	v_add_f32_e32 v207, v206, v206
	v_add_f32_e32 v213, v212, v212
	v_add_f32_e32 v219, v218, v218
	v_mul_f32_e32 v171, 0x3fb8aa3b, v169
	v_mul_f32_e32 v209, 0x3fb8aa3b, v207
	v_mul_f32_e32 v215, 0x3fb8aa3b, v213
	v_mul_f32_e32 v221, 0x3fb8aa3b, v219
	v_fmamk_f32 v170, v169, 0x3c088888, v195
	v_fmamk_f32 v208, v207, 0x3c088888, v195
	v_fmamk_f32 v214, v213, 0x3c088888, v195
	v_fmamk_f32 v220, v219, 0x3c088888, v195
	v_exp_f32_e32 v171, v171
	v_exp_f32_e32 v209, v209
	v_exp_f32_e32 v215, v215
	v_exp_f32_e32 v221, v221
	v_fmaak_f32 v170, v169, v170, 0x3e2aaaab
	v_fmaak_f32 v208, v207, v208, 0x3e2aaaab
	v_fmaak_f32 v214, v213, v214, 0x3e2aaaab
	v_fmaak_f32 v220, v219, v220, 0x3e2aaaab
	v_fma_f32 v170, v169, v170, 0.5
	v_fma_f32 v208, v207, v208, 0.5
	v_fma_f32 v214, v213, v214, 0.5
	v_fma_f32 v220, v219, v220, 0.5
	v_fma_f32 v170, v169, v170, 1.0
	v_fma_f32 v208, v207, v208, 1.0
	v_fma_f32 v214, v213, v214, 1.0
	v_fma_f32 v220, v219, v220, 1.0
	v_sub_f32_e32 v171, 1.0, v171
	v_sub_f32_e32 v209, 1.0, v209
	v_sub_f32_e32 v215, 1.0, v215
	v_sub_f32_e32 v221, 1.0, v221
	v_mul_f32_e64 v170, v170, -v169
	v_mul_f32_e64 v208, v208, -v207
	v_mul_f32_e64 v214, v214, -v213
	v_mul_f32_e64 v220, v220, -v219
	v_cmp_nlt_f32_e32 vcc, s1, v169
	v_cmp_nlt_f32_e64 s[62:63], s1, v207
	v_cmp_nlt_f32_e64 s[56:57], s1, v213
	v_mul_f32_e32 v167, v162, v167
	v_mul_f32_e32 v205, v163, v205
	v_mul_f32_e32 v211, v164, v211
	v_mul_f32_e32 v217, v165, v217
	v_cndmask_b32_e32 v170, v170, v171, vcc
	v_cmp_nlt_f32_e32 vcc, s1, v219
	v_cndmask_b32_e64 v208, v208, v209, s[62:63]
	v_cndmask_b32_e64 v214, v214, v215, s[56:57]
	v_mul_f32_e32 v166, 0x3fb8aa3b, v168
	v_mul_f32_e32 v204, 0x3fb8aa3b, v206
	v_mul_f32_e32 v210, 0x3fb8aa3b, v212
	v_mul_f32_e32 v216, 0x3fb8aa3b, v218
	v_cndmask_b32_e32 v220, v220, v221, vcc
	v_sqrt_f32_e32 v170, v170
	v_sqrt_f32_e32 v208, v208
	v_sqrt_f32_e32 v214, v214
	v_sqrt_f32_e32 v220, v220
	v_exp_f32_e32 v166, v166
	v_exp_f32_e32 v204, v204
	v_exp_f32_e32 v210, v210
	v_exp_f32_e32 v216, v216
	v_mul_f32_e32 v167, v167, v170
	v_mul_f32_e32 v205, v205, v208
	v_mul_f32_e32 v211, v211, v214
	v_mul_f32_e32 v217, v217, v220
	ds_read_b128 v[150:153], v230 offset:256
	ds_read_b128 v[154:157], v230 offset:640
	ds_read_b128 v[158:161], v230 offset:1024
	ds_read_b128 v[162:165], v231 offset:256
	s_waitcnt lgkmcnt(0)
	v_mul_f32_e32 v32, v32, v222
	v_mul_f32_e32 v33, v33, v223
	v_mul_f32_e32 v34, v34, v224
	v_mul_f32_e32 v35, v35, v225
	v_mfma_f32_16x16x32_bf16 v[134:137], v[110:113], v[98:101], 0
	v_mfma_f32_16x16x32_bf16 v[138:141], v[122:125], v[98:101], 0
	v_mfma_f32_16x16x32_bf16 v[134:137], v[114:117], v[102:105], v[134:137]
	v_mfma_f32_16x16x32_bf16 v[138:141], v[126:129], v[102:105], v[138:141]
	v_mfma_f32_16x16x32_bf16 v[134:137], v[118:121], v[106:109], v[134:137]
	v_mfma_f32_16x16x32_bf16 v[138:141], v[130:133], v[106:109], v[138:141]
	v_fmac_f32_dpp v167, v167, v166 row_shr:1 row_mask:0xf bank_mask:0xf bound_ctrl:1
	v_fmac_f32_dpp v205, v205, v204 row_shr:1 row_mask:0xf bank_mask:0xf bound_ctrl:1
	v_fmac_f32_dpp v211, v211, v210 row_shr:1 row_mask:0xf bank_mask:0xf bound_ctrl:1
	v_fmac_f32_dpp v217, v217, v216 row_shr:1 row_mask:0xf bank_mask:0xf bound_ctrl:1
	v_mul_f32_dpp v166, v166, v166 row_shr:1 row_mask:0xf bank_mask:0xf
	v_mul_f32_dpp v204, v204, v204 row_shr:1 row_mask:0xf bank_mask:0xf
	v_mul_f32_dpp v210, v210, v210 row_shr:1 row_mask:0xf bank_mask:0xf
	v_mul_f32_dpp v216, v216, v216 row_shr:1 row_mask:0xf bank_mask:0xf
	v_fmac_f32_dpp v167, v167, v166 row_shr:2 row_mask:0xf bank_mask:0xf bound_ctrl:1
	v_fmac_f32_dpp v205, v205, v204 row_shr:2 row_mask:0xf bank_mask:0xf bound_ctrl:1
	v_fmac_f32_dpp v211, v211, v210 row_shr:2 row_mask:0xf bank_mask:0xf bound_ctrl:1
	v_fmac_f32_dpp v217, v217, v216 row_shr:2 row_mask:0xf bank_mask:0xf bound_ctrl:1
	v_mul_f32_dpp v166, v166, v166 row_shr:2 row_mask:0xf bank_mask:0xf
	v_mul_f32_dpp v204, v204, v204 row_shr:2 row_mask:0xf bank_mask:0xf
	v_mul_f32_dpp v210, v210, v210 row_shr:2 row_mask:0xf bank_mask:0xf
	v_mul_f32_dpp v216, v216, v216 row_shr:2 row_mask:0xf bank_mask:0xf
	v_fmac_f32_dpp v167, v167, v166 row_shr:4 row_mask:0xf bank_mask:0xf bound_ctrl:1
	v_fmac_f32_dpp v205, v205, v204 row_shr:4 row_mask:0xf bank_mask:0xf bound_ctrl:1
	v_fmac_f32_dpp v211, v211, v210 row_shr:4 row_mask:0xf bank_mask:0xf bound_ctrl:1
	v_fmac_f32_dpp v217, v217, v216 row_shr:4 row_mask:0xf bank_mask:0xf bound_ctrl:1
	v_mul_f32_dpp v166, v166, v166 row_shr:4 row_mask:0xf bank_mask:0xf
	v_mul_f32_dpp v204, v204, v204 row_shr:4 row_mask:0xf bank_mask:0xf
	v_mul_f32_dpp v210, v210, v210 row_shr:4 row_mask:0xf bank_mask:0xf
	v_mul_f32_dpp v216, v216, v216 row_shr:4 row_mask:0xf bank_mask:0xf
	v_fmac_f32_dpp v167, v167, v166 row_shr:8 row_mask:0xf bank_mask:0xf bound_ctrl:1
	v_fmac_f32_dpp v205, v205, v204 row_shr:8 row_mask:0xf bank_mask:0xf bound_ctrl:1
	v_fmac_f32_dpp v211, v211, v210 row_shr:8 row_mask:0xf bank_mask:0xf bound_ctrl:1
	v_fmac_f32_dpp v217, v217, v216 row_shr:8 row_mask:0xf bank_mask:0xf bound_ctrl:1
	v_mul_f32_dpp v166, v166, v166 row_shr:8 row_mask:0xf bank_mask:0xf
	v_mul_f32_dpp v204, v204, v204 row_shr:8 row_mask:0xf bank_mask:0xf
	v_mul_f32_dpp v210, v210, v210 row_shr:8 row_mask:0xf bank_mask:0xf
	v_mul_f32_dpp v216, v216, v216 row_shr:8 row_mask:0xf bank_mask:0xf
	v_fma_f32 v168, v166, v12, v167
	v_fma_f32 v206, v204, v13, v205
	v_fma_f32 v212, v210, v14, v211
	v_fma_f32 v218, v216, v15, v217
	ds_bpermute_b32 v12, v232, v168
	ds_bpermute_b32 v13, v232, v206
	ds_bpermute_b32 v14, v232, v212
	ds_bpermute_b32 v15, v232, v218
	ds_bpermute_b32 v222, v232, v166
	ds_bpermute_b32 v223, v232, v204
	ds_bpermute_b32 v224, v232, v210
	ds_bpermute_b32 v225, v232, v216
	ds_read_b128 v[110:113], v229 offset:16640
	ds_read_b128 v[122:125], v229 offset:36608
	ds_read_b128 v[114:117], v229 offset:16704
	ds_read_b128 v[126:129], v229 offset:36672
	ds_read_b128 v[118:121], v229 offset:16768
	ds_read_b128 v[130:133], v229 offset:36736
	v_add_f32_e32 v166, v134, v150
	v_add_f32_e32 v204, v135, v151
	v_add_f32_e32 v210, v136, v152
	v_add_f32_e32 v216, v137, v153
	v_add_f32_e32 v167, v138, v154
	v_add_f32_e32 v205, v139, v155
	v_add_f32_e32 v211, v140, v156
	v_add_f32_e32 v217, v141, v157
	v_mul_f32_e32 v166, 0xbfb8aa3b, v166
	v_mul_f32_e32 v204, 0xbfb8aa3b, v204
	v_mul_f32_e32 v210, 0xbfb8aa3b, v210
	v_mul_f32_e32 v216, 0xbfb8aa3b, v216
	v_mul_f32_e32 v167, 0xbfb8aa3b, v167
	v_mul_f32_e32 v205, 0xbfb8aa3b, v205
	v_mul_f32_e32 v211, 0xbfb8aa3b, v211
	v_mul_f32_e32 v217, 0xbfb8aa3b, v217
	v_exp_f32_e32 v166, v166
	v_exp_f32_e32 v204, v204
	v_exp_f32_e32 v210, v210
	v_exp_f32_e32 v216, v216
	v_exp_f32_e32 v167, v167
	v_exp_f32_e32 v205, v205
	v_exp_f32_e32 v211, v211
	v_exp_f32_e32 v217, v217
	v_add_f32_e32 v166, 1.0, v166
	v_add_f32_e32 v204, 1.0, v204
	v_add_f32_e32 v210, 1.0, v210
	v_add_f32_e32 v216, 1.0, v216
	v_add_f32_e32 v167, 1.0, v167
	v_add_f32_e32 v205, 1.0, v205
	v_add_f32_e32 v211, 1.0, v211
	v_add_f32_e32 v217, 1.0, v217
	v_rcp_f32_e32 v166, v166
	v_rcp_f32_e32 v204, v204
	v_rcp_f32_e32 v210, v210
	v_rcp_f32_e32 v216, v216
	v_rcp_f32_e32 v167, v167
	v_rcp_f32_e32 v205, v205
	v_rcp_f32_e32 v211, v211
	v_rcp_f32_e32 v217, v217
	v_mul_f32_e32 v168, 0xc1000000, v166
	v_mul_f32_e32 v206, 0xc1000000, v204
	v_mul_f32_e32 v212, 0xc1000000, v210
	v_mul_f32_e32 v218, 0xc1000000, v216
	v_mul_f32_e32 v168, v158, v168
	v_mul_f32_e32 v206, v159, v206
	v_mul_f32_e32 v212, v160, v212
	v_mul_f32_e32 v218, v161, v218
	v_add_f32_e32 v169, v168, v168
	v_add_f32_e32 v207, v206, v206
	v_add_f32_e32 v213, v212, v212
	v_add_f32_e32 v219, v218, v218
	v_mul_f32_e32 v171, 0x3fb8aa3b, v169
	v_mul_f32_e32 v209, 0x3fb8aa3b, v207
	v_mul_f32_e32 v215, 0x3fb8aa3b, v213
	v_mul_f32_e32 v221, 0x3fb8aa3b, v219
	v_fmamk_f32 v170, v169, 0x3c088888, v195
	v_fmamk_f32 v208, v207, 0x3c088888, v195
	v_fmamk_f32 v214, v213, 0x3c088888, v195
	v_fmamk_f32 v220, v219, 0x3c088888, v195
	v_exp_f32_e32 v171, v171
	v_exp_f32_e32 v209, v209
	v_exp_f32_e32 v215, v215
	v_exp_f32_e32 v221, v221
	v_fmaak_f32 v170, v169, v170, 0x3e2aaaab
	v_fmaak_f32 v208, v207, v208, 0x3e2aaaab
	v_fmaak_f32 v214, v213, v214, 0x3e2aaaab
	v_fmaak_f32 v220, v219, v220, 0x3e2aaaab
	v_fma_f32 v170, v169, v170, 0.5
	v_fma_f32 v208, v207, v208, 0.5
	v_fma_f32 v214, v213, v214, 0.5
	v_fma_f32 v220, v219, v220, 0.5
	v_fma_f32 v170, v169, v170, 1.0
	v_fma_f32 v208, v207, v208, 1.0
	v_fma_f32 v214, v213, v214, 1.0
	v_fma_f32 v220, v219, v220, 1.0
	v_sub_f32_e32 v171, 1.0, v171
	v_sub_f32_e32 v209, 1.0, v209
	v_sub_f32_e32 v215, 1.0, v215
	v_sub_f32_e32 v221, 1.0, v221
	v_mul_f32_e64 v170, v170, -v169
	v_mul_f32_e64 v208, v208, -v207
	v_mul_f32_e64 v214, v214, -v213
	v_mul_f32_e64 v220, v220, -v219
	v_cmp_nlt_f32_e32 vcc, s1, v169
	v_cmp_nlt_f32_e64 s[62:63], s1, v207
	v_cmp_nlt_f32_e64 s[56:57], s1, v213
	v_mul_f32_e32 v167, v162, v167
	v_mul_f32_e32 v205, v163, v205
	v_mul_f32_e32 v211, v164, v211
	v_mul_f32_e32 v217, v165, v217
	v_cndmask_b32_e32 v170, v170, v171, vcc
	v_cmp_nlt_f32_e32 vcc, s1, v219
	v_cndmask_b32_e64 v208, v208, v209, s[62:63]
	v_cndmask_b32_e64 v214, v214, v215, s[56:57]
	v_mul_f32_e32 v166, 0x3fb8aa3b, v168
	v_mul_f32_e32 v204, 0x3fb8aa3b, v206
	v_mul_f32_e32 v210, 0x3fb8aa3b, v212
	v_mul_f32_e32 v216, 0x3fb8aa3b, v218
	v_cndmask_b32_e32 v220, v220, v221, vcc
	v_sqrt_f32_e32 v170, v170
	v_sqrt_f32_e32 v208, v208
	v_sqrt_f32_e32 v214, v214
	v_sqrt_f32_e32 v220, v220
	v_exp_f32_e32 v166, v166
	v_exp_f32_e32 v204, v204
	v_exp_f32_e32 v210, v210
	v_exp_f32_e32 v216, v216
	v_mul_f32_e32 v167, v167, v170
	v_mul_f32_e32 v205, v205, v208
	v_mul_f32_e32 v211, v211, v214
	v_mul_f32_e32 v217, v217, v220
	ds_read_b128 v[150:153], v230 offset:320
	ds_read_b128 v[154:157], v230 offset:704
	ds_read_b128 v[158:161], v230 offset:1088
	ds_read_b128 v[162:165], v231 offset:320
	s_waitcnt lgkmcnt(0)
	v_mul_f32_e32 v36, v36, v222
	v_mul_f32_e32 v37, v37, v223
	v_mul_f32_e32 v38, v38, v224
	v_mul_f32_e32 v39, v39, v225
	v_mfma_f32_16x16x32_bf16 v[142:145], v[110:113], v[98:101], 0
	v_mfma_f32_16x16x32_bf16 v[146:149], v[122:125], v[98:101], 0
	v_mfma_f32_16x16x32_bf16 v[142:145], v[114:117], v[102:105], v[142:145]
	v_mfma_f32_16x16x32_bf16 v[146:149], v[126:129], v[102:105], v[146:149]
	v_mfma_f32_16x16x32_bf16 v[142:145], v[118:121], v[106:109], v[142:145]
	v_mfma_f32_16x16x32_bf16 v[146:149], v[130:133], v[106:109], v[146:149]
	v_fmac_f32_dpp v167, v167, v166 row_shr:1 row_mask:0xf bank_mask:0xf bound_ctrl:1
	v_fmac_f32_dpp v205, v205, v204 row_shr:1 row_mask:0xf bank_mask:0xf bound_ctrl:1
	v_fmac_f32_dpp v211, v211, v210 row_shr:1 row_mask:0xf bank_mask:0xf bound_ctrl:1
	v_fmac_f32_dpp v217, v217, v216 row_shr:1 row_mask:0xf bank_mask:0xf bound_ctrl:1
	v_mul_f32_dpp v166, v166, v166 row_shr:1 row_mask:0xf bank_mask:0xf
	v_mul_f32_dpp v204, v204, v204 row_shr:1 row_mask:0xf bank_mask:0xf
	v_mul_f32_dpp v210, v210, v210 row_shr:1 row_mask:0xf bank_mask:0xf
	v_mul_f32_dpp v216, v216, v216 row_shr:1 row_mask:0xf bank_mask:0xf
	v_fmac_f32_dpp v167, v167, v166 row_shr:2 row_mask:0xf bank_mask:0xf bound_ctrl:1
	v_fmac_f32_dpp v205, v205, v204 row_shr:2 row_mask:0xf bank_mask:0xf bound_ctrl:1
	v_fmac_f32_dpp v211, v211, v210 row_shr:2 row_mask:0xf bank_mask:0xf bound_ctrl:1
	v_fmac_f32_dpp v217, v217, v216 row_shr:2 row_mask:0xf bank_mask:0xf bound_ctrl:1
	v_mul_f32_dpp v166, v166, v166 row_shr:2 row_mask:0xf bank_mask:0xf
	v_mul_f32_dpp v204, v204, v204 row_shr:2 row_mask:0xf bank_mask:0xf
	v_mul_f32_dpp v210, v210, v210 row_shr:2 row_mask:0xf bank_mask:0xf
	v_mul_f32_dpp v216, v216, v216 row_shr:2 row_mask:0xf bank_mask:0xf
	v_fmac_f32_dpp v167, v167, v166 row_shr:4 row_mask:0xf bank_mask:0xf bound_ctrl:1
	v_fmac_f32_dpp v205, v205, v204 row_shr:4 row_mask:0xf bank_mask:0xf bound_ctrl:1
	v_fmac_f32_dpp v211, v211, v210 row_shr:4 row_mask:0xf bank_mask:0xf bound_ctrl:1
	v_fmac_f32_dpp v217, v217, v216 row_shr:4 row_mask:0xf bank_mask:0xf bound_ctrl:1
	v_mul_f32_dpp v166, v166, v166 row_shr:4 row_mask:0xf bank_mask:0xf
	v_mul_f32_dpp v204, v204, v204 row_shr:4 row_mask:0xf bank_mask:0xf
	v_mul_f32_dpp v210, v210, v210 row_shr:4 row_mask:0xf bank_mask:0xf
	v_mul_f32_dpp v216, v216, v216 row_shr:4 row_mask:0xf bank_mask:0xf
	v_fmac_f32_dpp v167, v167, v166 row_shr:8 row_mask:0xf bank_mask:0xf bound_ctrl:1
	v_fmac_f32_dpp v205, v205, v204 row_shr:8 row_mask:0xf bank_mask:0xf bound_ctrl:1
	v_fmac_f32_dpp v211, v211, v210 row_shr:8 row_mask:0xf bank_mask:0xf bound_ctrl:1
	v_fmac_f32_dpp v217, v217, v216 row_shr:8 row_mask:0xf bank_mask:0xf bound_ctrl:1
	v_mul_f32_dpp v166, v166, v166 row_shr:8 row_mask:0xf bank_mask:0xf
	v_mul_f32_dpp v204, v204, v204 row_shr:8 row_mask:0xf bank_mask:0xf
	v_mul_f32_dpp v210, v210, v210 row_shr:8 row_mask:0xf bank_mask:0xf
	v_mul_f32_dpp v216, v216, v216 row_shr:8 row_mask:0xf bank_mask:0xf
	v_fma_f32 v168, v166, v16, v167
	v_fma_f32 v206, v204, v17, v205
	v_fma_f32 v212, v210, v18, v211
	v_fma_f32 v218, v216, v19, v217
	ds_bpermute_b32 v16, v232, v168
	ds_bpermute_b32 v17, v232, v206
	ds_bpermute_b32 v18, v232, v212
	ds_bpermute_b32 v19, v232, v218
	ds_bpermute_b32 v222, v232, v166
	ds_bpermute_b32 v223, v232, v204
	ds_bpermute_b32 v224, v232, v210
	ds_bpermute_b32 v225, v232, v216
	v_add_f32_e32 v166, v142, v150
	v_add_f32_e32 v204, v143, v151
	v_add_f32_e32 v210, v144, v152
	v_add_f32_e32 v216, v145, v153
	v_add_f32_e32 v167, v146, v154
	v_add_f32_e32 v205, v147, v155
	v_add_f32_e32 v211, v148, v156
	v_add_f32_e32 v217, v149, v157
	v_mul_f32_e32 v166, 0xbfb8aa3b, v166
	v_mul_f32_e32 v204, 0xbfb8aa3b, v204
	v_mul_f32_e32 v210, 0xbfb8aa3b, v210
	v_mul_f32_e32 v216, 0xbfb8aa3b, v216
	v_mul_f32_e32 v167, 0xbfb8aa3b, v167
	v_mul_f32_e32 v205, 0xbfb8aa3b, v205
	v_mul_f32_e32 v211, 0xbfb8aa3b, v211
	v_mul_f32_e32 v217, 0xbfb8aa3b, v217
	v_exp_f32_e32 v166, v166
	v_exp_f32_e32 v204, v204
	v_exp_f32_e32 v210, v210
	v_exp_f32_e32 v216, v216
	v_exp_f32_e32 v167, v167
	v_exp_f32_e32 v205, v205
	v_exp_f32_e32 v211, v211
	v_exp_f32_e32 v217, v217
	v_add_f32_e32 v166, 1.0, v166
	v_add_f32_e32 v204, 1.0, v204
	v_add_f32_e32 v210, 1.0, v210
	v_add_f32_e32 v216, 1.0, v216
	v_add_f32_e32 v167, 1.0, v167
	v_add_f32_e32 v205, 1.0, v205
	v_add_f32_e32 v211, 1.0, v211
	v_add_f32_e32 v217, 1.0, v217
	v_rcp_f32_e32 v166, v166
	v_rcp_f32_e32 v204, v204
	v_rcp_f32_e32 v210, v210
	v_rcp_f32_e32 v216, v216
	v_rcp_f32_e32 v167, v167
	v_rcp_f32_e32 v205, v205
	v_rcp_f32_e32 v211, v211
	v_rcp_f32_e32 v217, v217
	v_mul_f32_e32 v168, 0xc1000000, v166
	v_mul_f32_e32 v206, 0xc1000000, v204
	v_mul_f32_e32 v212, 0xc1000000, v210
	v_mul_f32_e32 v218, 0xc1000000, v216
	v_mul_f32_e32 v168, v158, v168
	v_mul_f32_e32 v206, v159, v206
	v_mul_f32_e32 v212, v160, v212
	v_mul_f32_e32 v218, v161, v218
	v_add_f32_e32 v169, v168, v168
	v_add_f32_e32 v207, v206, v206
	v_add_f32_e32 v213, v212, v212
	v_add_f32_e32 v219, v218, v218
	v_mul_f32_e32 v171, 0x3fb8aa3b, v169
	v_mul_f32_e32 v209, 0x3fb8aa3b, v207
	v_mul_f32_e32 v215, 0x3fb8aa3b, v213
	v_mul_f32_e32 v221, 0x3fb8aa3b, v219
	v_fmamk_f32 v170, v169, 0x3c088888, v195
	v_fmamk_f32 v208, v207, 0x3c088888, v195
	v_fmamk_f32 v214, v213, 0x3c088888, v195
	v_fmamk_f32 v220, v219, 0x3c088888, v195
	v_exp_f32_e32 v171, v171
	v_exp_f32_e32 v209, v209
	v_exp_f32_e32 v215, v215
	v_exp_f32_e32 v221, v221
	v_fmaak_f32 v170, v169, v170, 0x3e2aaaab
	v_fmaak_f32 v208, v207, v208, 0x3e2aaaab
	v_fmaak_f32 v214, v213, v214, 0x3e2aaaab
	v_fmaak_f32 v220, v219, v220, 0x3e2aaaab
	v_fma_f32 v170, v169, v170, 0.5
	v_fma_f32 v208, v207, v208, 0.5
	v_fma_f32 v214, v213, v214, 0.5
	v_fma_f32 v220, v219, v220, 0.5
	v_fma_f32 v170, v169, v170, 1.0
	v_fma_f32 v208, v207, v208, 1.0
	v_fma_f32 v214, v213, v214, 1.0
	v_fma_f32 v220, v219, v220, 1.0
	v_sub_f32_e32 v171, 1.0, v171
	v_sub_f32_e32 v209, 1.0, v209
	v_sub_f32_e32 v215, 1.0, v215
	v_sub_f32_e32 v221, 1.0, v221
	v_mul_f32_e64 v170, v170, -v169
	v_mul_f32_e64 v208, v208, -v207
	v_mul_f32_e64 v214, v214, -v213
	v_mul_f32_e64 v220, v220, -v219
	v_cmp_nlt_f32_e32 vcc, s1, v169
	v_cmp_nlt_f32_e64 s[62:63], s1, v207
	v_cmp_nlt_f32_e64 s[56:57], s1, v213
	v_mul_f32_e32 v167, v162, v167
	v_mul_f32_e32 v205, v163, v205
	v_mul_f32_e32 v211, v164, v211
	v_mul_f32_e32 v217, v165, v217
	v_cndmask_b32_e32 v170, v170, v171, vcc
	v_cmp_nlt_f32_e32 vcc, s1, v219
	v_cndmask_b32_e64 v208, v208, v209, s[62:63]
	v_cndmask_b32_e64 v214, v214, v215, s[56:57]
	v_mul_f32_e32 v166, 0x3fb8aa3b, v168
	v_mul_f32_e32 v204, 0x3fb8aa3b, v206
	v_mul_f32_e32 v210, 0x3fb8aa3b, v212
	v_mul_f32_e32 v216, 0x3fb8aa3b, v218
	v_cndmask_b32_e32 v220, v220, v221, vcc
	v_sqrt_f32_e32 v170, v170
	v_sqrt_f32_e32 v208, v208
	v_sqrt_f32_e32 v214, v214
	v_sqrt_f32_e32 v220, v220
	v_exp_f32_e32 v166, v166
	v_exp_f32_e32 v204, v204
	v_exp_f32_e32 v210, v210
	v_exp_f32_e32 v216, v216
	v_mul_f32_e32 v167, v167, v170
	v_mul_f32_e32 v205, v205, v208
	v_mul_f32_e32 v211, v211, v214
	v_mul_f32_e32 v217, v217, v220
	s_waitcnt lgkmcnt(0)
	v_mul_f32_e32 v40, v40, v222
	v_mul_f32_e32 v41, v41, v223
	v_mul_f32_e32 v42, v42, v224
	v_mul_f32_e32 v43, v43, v225
	v_fmac_f32_dpp v167, v167, v166 row_shr:1 row_mask:0xf bank_mask:0xf bound_ctrl:1
	v_fmac_f32_dpp v205, v205, v204 row_shr:1 row_mask:0xf bank_mask:0xf bound_ctrl:1
	v_fmac_f32_dpp v211, v211, v210 row_shr:1 row_mask:0xf bank_mask:0xf bound_ctrl:1
	v_fmac_f32_dpp v217, v217, v216 row_shr:1 row_mask:0xf bank_mask:0xf bound_ctrl:1
	v_mul_f32_dpp v166, v166, v166 row_shr:1 row_mask:0xf bank_mask:0xf
	v_mul_f32_dpp v204, v204, v204 row_shr:1 row_mask:0xf bank_mask:0xf
	v_mul_f32_dpp v210, v210, v210 row_shr:1 row_mask:0xf bank_mask:0xf
	v_mul_f32_dpp v216, v216, v216 row_shr:1 row_mask:0xf bank_mask:0xf
	v_fmac_f32_dpp v167, v167, v166 row_shr:2 row_mask:0xf bank_mask:0xf bound_ctrl:1
	v_fmac_f32_dpp v205, v205, v204 row_shr:2 row_mask:0xf bank_mask:0xf bound_ctrl:1
	v_fmac_f32_dpp v211, v211, v210 row_shr:2 row_mask:0xf bank_mask:0xf bound_ctrl:1
	v_fmac_f32_dpp v217, v217, v216 row_shr:2 row_mask:0xf bank_mask:0xf bound_ctrl:1
	v_mul_f32_dpp v166, v166, v166 row_shr:2 row_mask:0xf bank_mask:0xf
	v_mul_f32_dpp v204, v204, v204 row_shr:2 row_mask:0xf bank_mask:0xf
	v_mul_f32_dpp v210, v210, v210 row_shr:2 row_mask:0xf bank_mask:0xf
	v_mul_f32_dpp v216, v216, v216 row_shr:2 row_mask:0xf bank_mask:0xf
	v_fmac_f32_dpp v167, v167, v166 row_shr:4 row_mask:0xf bank_mask:0xf bound_ctrl:1
	v_fmac_f32_dpp v205, v205, v204 row_shr:4 row_mask:0xf bank_mask:0xf bound_ctrl:1
	v_fmac_f32_dpp v211, v211, v210 row_shr:4 row_mask:0xf bank_mask:0xf bound_ctrl:1
	v_fmac_f32_dpp v217, v217, v216 row_shr:4 row_mask:0xf bank_mask:0xf bound_ctrl:1
	v_mul_f32_dpp v166, v166, v166 row_shr:4 row_mask:0xf bank_mask:0xf
	v_mul_f32_dpp v204, v204, v204 row_shr:4 row_mask:0xf bank_mask:0xf
	v_mul_f32_dpp v210, v210, v210 row_shr:4 row_mask:0xf bank_mask:0xf
	v_mul_f32_dpp v216, v216, v216 row_shr:4 row_mask:0xf bank_mask:0xf
	v_fmac_f32_dpp v167, v167, v166 row_shr:8 row_mask:0xf bank_mask:0xf bound_ctrl:1
	v_fmac_f32_dpp v205, v205, v204 row_shr:8 row_mask:0xf bank_mask:0xf bound_ctrl:1
	v_fmac_f32_dpp v211, v211, v210 row_shr:8 row_mask:0xf bank_mask:0xf bound_ctrl:1
	v_fmac_f32_dpp v217, v217, v216 row_shr:8 row_mask:0xf bank_mask:0xf bound_ctrl:1
	v_mul_f32_dpp v166, v166, v166 row_shr:8 row_mask:0xf bank_mask:0xf
	v_mul_f32_dpp v204, v204, v204 row_shr:8 row_mask:0xf bank_mask:0xf
	v_mul_f32_dpp v210, v210, v210 row_shr:8 row_mask:0xf bank_mask:0xf
	v_mul_f32_dpp v216, v216, v216 row_shr:8 row_mask:0xf bank_mask:0xf
	v_fma_f32 v168, v166, v20, v167
	v_fma_f32 v206, v204, v21, v205
	v_fma_f32 v212, v210, v22, v211
	v_fma_f32 v218, v216, v23, v217
	ds_bpermute_b32 v20, v232, v168
	ds_bpermute_b32 v21, v232, v206
	ds_bpermute_b32 v22, v232, v212
	ds_bpermute_b32 v23, v232, v218
	ds_bpermute_b32 v222, v232, v166
	ds_bpermute_b32 v223, v232, v204
	ds_bpermute_b32 v224, v232, v210
	ds_bpermute_b32 v225, v232, v216
	s_waitcnt lgkmcnt(0)
	v_mul_f32_e32 v44, v44, v222
	v_mul_f32_e32 v45, v45, v223
	v_mul_f32_e32 v46, v46, v224
	v_mul_f32_e32 v47, v47, v225
	s_waitcnt vmcnt(0)
	v_mov_b32_e32 v66, v82
	v_mov_b32_e32 v67, v83
	v_mov_b32_e32 v68, v84
	v_mov_b32_e32 v69, v85
	v_mov_b32_e32 v70, v86
	v_mov_b32_e32 v71, v87
	v_mov_b32_e32 v72, v88
	v_mov_b32_e32 v73, v89
	v_mov_b32_e32 v74, v90
	v_mov_b32_e32 v75, v91
	v_mov_b32_e32 v76, v92
	v_mov_b32_e32 v77, v93
	v_mov_b32_e32 v78, v94
	v_mov_b32_e32 v79, v95
	v_mov_b32_e32 v80, v96
	v_mov_b32_e32 v81, v97
	s_add_i32 s64, s64, 1
	s_cmp_lt_u32 s64, 3
	s_cbranch_scc1 .Lscan1_sub
	s_mov_b32 s62, 0x10001
	s_mov_b32 s63, 0x10001
	s_mov_b64 exec, s[62:63]
	s_add_u32 s62, s6, 0x204000
	s_addc_u32 s63, s7, 0
	global_store_dwordx4 v237, v[24:27], s[6:7] offset:0
	global_store_dwordx4 v237, v[0:3], s[62:63] offset:0
	global_store_dwordx4 v237, v[28:31], s[6:7] offset:64
	global_store_dwordx4 v237, v[4:7], s[62:63] offset:64
	global_store_dwordx4 v237, v[32:35], s[6:7] offset:128
	global_store_dwordx4 v237, v[8:11], s[62:63] offset:128
	global_store_dwordx4 v237, v[36:39], s[6:7] offset:192
	global_store_dwordx4 v237, v[12:15], s[62:63] offset:192
	global_store_dwordx4 v237, v[40:43], s[6:7] offset:256
	global_store_dwordx4 v237, v[16:19], s[62:63] offset:256
	global_store_dwordx4 v237, v[44:47], s[6:7] offset:320
	global_store_dwordx4 v237, v[20:23], s[62:63] offset:320
	s_mov_b64 exec, -1
	s_add_i32 s23, s23, s42
.Lscan1_unit_test:
	s_cmpk_lt_u32 s23, 0x2b0
	s_cbranch_scc1 .Lscan1_unit
	s_waitcnt vmcnt(0) lgkmcnt(0)

.LBB0_424:
	s_andn2_b64 vcc, exec, s[6:7]
	s_cbranch_vccnz .LBB0_574
	v_readlane_b32 s6, v254, 0
	v_readlane_b32 s7, v254, 1
	s_load_dwordx4 s[12:15], s[6:7], 0xb8
	v_mov_b32_e32 v98, v192
	s_mov_b32 s66, s20
	s_and_b64 vcc, exec, s[4:5]
	v_readfirstlane_b32 s0, v98
	s_cbranch_vccnz .LBB0_548
	s_waitcnt lgkmcnt(0)
	s_mov_b64 s[16:17], s[12:13]
	s_mov_b64 s[18:19], s[14:15]
	s_mov_b32 s20, s66
	s_load_dwordx4 s[8:11], s[6:7], 0x18
	s_load_dwordx2 s[12:13], s[6:7], 0x30
	s_load_dwordx4 s[24:27], s[6:7], 0x40
	v_readfirstlane_b32 s21, v192
	s_lshr_b32 s21, s21, 6
	s_add_u32 s28, s18, 0x8f29000
	s_addc_u32 s29, s19, 0
	s_add_u32 s30, s16, 0x3db4000
	s_addc_u32 s31, s17, 0
	s_add_u32 s34, s18, 0xf0b5000
	s_addc_u32 s35, s19, 0
	v_and_b32_e32 v238, 63, v192
	v_and_b32_e32 v239, 15, v192
	v_bfe_u32 v240, v192, 4, 2
	s_mul_i32 s0, s21, 0x2600
	s_add_i32 s0, s0, 0xa080
	v_lshl_add_u32 v226, v238, 3, s0
	v_lshl_add_u32 v227, v238, 2, s0
	v_add_u32_e32 v227, 0x1900, v227
	v_mul_u32_u24_e32 v229, 0xd0, v239
	v_lshl_add_u32 v229, v240, 4, v229
	v_add_u32_e32 v228, s0, v229
	v_add_u32_e32 v228, 0x1900, v228
	v_lshlrev_b32_e32 v237, 4, v240
	v_add_u32_e32 v230, 0x9c00, v237
	v_mul_u32_u24_e32 v231, 0x190, v239
	v_add3_u32 v231, v231, v237, s0
	v_and_or_b32 v232, v238, 48, 15
	v_lshlrev_b32_e32 v232, 2, v232
	v_min_u32_e32 v241, 47, v238
	v_lshlrev_b32_e32 v233, 2, v241
	v_lshlrev_b32_e32 v234, 3, v241
	v_mul_u32_u24_e32 v235, 0x1800, v239
	v_lshl_add_u32 v235, v240, 3, v235
	v_mul_u32_u24_e32 v236, 0xc00, v239
	v_lshl_add_u32 v236, v240, 3, v236
	s_waitcnt lgkmcnt(0)
	s_mul_i32 s0, s20, 0x6000
	s_add_u32 s8, s8, s0
	s_addc_u32 s9, s9, 0
	s_mul_i32 s0, s20, 0x1800
	s_add_u32 s10, s10, s0
	s_addc_u32 s11, s11, 0
	s_add_u32 s12, s12, s0
	s_addc_u32 s13, s13, 0
	s_add_u32 s24, s24, s0
	s_addc_u32 s25, s25, 0
	s_add_u32 s26, s26, s0
	s_addc_u32 s27, s27, 0
	s_mov_b32 s38, -1
	s_mov_b32 s23, s2
	s_branch .Lscan2_unit_test

.Lscan2_staged:
	s_lshr_b32 s0, s23, 4
	s_lshl_b32 s0, s0, 3
	s_add_i32 s0, s0, s21
	s_mul_i32 s55, s0, 0x5f5
	s_lshr_b32 s55, s55, 16
	s_mul_i32 s56, s55, 43
	s_sub_i32 s56, s0, s56
	s_mul_i32 s57, s55, 0x810
	s_mul_i32 s39, s56, 48
	s_add_i32 s57, s57, s39
	s_mul_i32 s44, s57, 0x1800
	s_mul_hi_u32 s45, s57, 0x1800
	s_mul_i32 s39, s37, 0xc0
	s_add_i32 s39, s39, 0xc00
	s_add_u32 s44, s44, s39
	s_addc_u32 s45, s45, 0
	s_add_u32 s44, s44, s28
	s_addc_u32 s45, s45, s29
	s_add_u32 s62, s44, 0xffffb800
	s_addc_u32 s63, s45, -1
	global_load_dword v59, v233, s[62:63]
	s_add_u32 s62, s62, 0x1800
	s_addc_u32 s63, s63, 0
	global_load_dword v61, v233, s[62:63]
	s_add_u32 s62, s62, 0x1800
	s_addc_u32 s63, s63, 0
	global_load_dword v63, v233, s[62:63]
	s_mov_b64 s[62:63], s[44:45]
	global_load_dword v66, v233, s[62:63]
	s_add_u32 s62, s62, 0x1800
	s_addc_u32 s63, s63, 0
	global_load_dword v67, v233, s[62:63]
	s_add_u32 s62, s62, 0x1800
	s_addc_u32 s63, s63, 0
	global_load_dword v68, v233, s[62:63]
	s_add_u32 s62, s62, 0x1800
	s_addc_u32 s63, s63, 0
	global_load_dword v69, v233, s[62:63]
	s_add_u32 s62, s62, 0x1800
	s_addc_u32 s63, s63, 0
	global_load_dword v70, v233, s[62:63]
	s_add_u32 s62, s62, 0x1800
	s_addc_u32 s63, s63, 0
	global_load_dword v71, v233, s[62:63]
	s_add_u32 s62, s62, 0x1800
	s_addc_u32 s63, s63, 0
	global_load_dword v72, v233, s[62:63]
	s_add_u32 s62, s62, 0x1800
	s_addc_u32 s63, s63, 0
	global_load_dword v73, v233, s[62:63]
	s_add_u32 s62, s62, 0x1800
	s_addc_u32 s63, s63, 0
	global_load_dword v74, v233, s[62:63]
	s_add_u32 s62, s62, 0x1800
	s_addc_u32 s63, s63, 0
	global_load_dword v75, v233, s[62:63]
	s_add_u32 s62, s62, 0x1800
	s_addc_u32 s63, s63, 0
	global_load_dword v76, v233, s[62:63]
	s_add_u32 s62, s62, 0x1800
	s_addc_u32 s63, s63, 0
	global_load_dword v77, v233, s[62:63]
	s_add_u32 s62, s62, 0x1800
	s_addc_u32 s63, s63, 0
	global_load_dword v78, v233, s[62:63]
	s_add_u32 s62, s62, 0x1800
	s_addc_u32 s63, s63, 0
	global_load_dword v79, v233, s[62:63]
	s_add_u32 s62, s62, 0x1800
	s_addc_u32 s63, s63, 0
	global_load_dword v80, v233, s[62:63]
	s_add_u32 s62, s62, 0x1800
	s_addc_u32 s63, s63, 0
	global_load_dword v81, v233, s[62:63]
	s_add_u32 s62, s62, 0x1800
	s_addc_u32 s63, s63, 0
	s_mov_b64 s[44:45], s[62:63]
	s_mul_i32 s39, s37, 0x180
	s_add_u32 s62, s8, s39
	s_addc_u32 s63, s9, 0
	global_load_dwordx2 v[48:49], v234, s[62:63]
	s_add_u32 s62, s62, 0x1800
	s_addc_u32 s63, s63, 0
	global_load_dwordx2 v[50:51], v234, s[62:63]
	s_add_u32 s62, s62, 0x1800
	s_addc_u32 s63, s63, 0
	global_load_dwordx2 v[52:53], v234, s[62:63]
	s_add_u32 s62, s62, 0x1800
	s_addc_u32 s63, s63, 0
	global_load_dwordx2 v[54:55], v234, s[62:63]
	s_add_u32 s62, s10, s39
	s_addc_u32 s63, s11, 0
	global_load_dwordx2 v[56:57], v234, s[62:63]
	s_mul_i32 s39, s55, 43
	s_add_i32 s39, s39, s56
	s_mul_i32 s39, s39, 0x1800
	s_mul_i32 s0, s37, 0x180
	s_add_i32 s39, s39, s0
	s_add_u32 s62, s30, s39
	s_addc_u32 s63, s31, 0
	global_load_dwordx4 v[0:3], v237, s[62:63] offset:0
	global_load_dwordx4 v[4:7], v237, s[62:63] offset:64
	global_load_dwordx4 v[8:11], v237, s[62:63] offset:128
	global_load_dwordx4 v[12:15], v237, s[62:63] offset:192
	global_load_dwordx4 v[16:19], v237, s[62:63] offset:256
	global_load_dwordx4 v[20:23], v237, s[62:63] offset:320
	s_mul_i32 s6, s57, 0x1800
	s_mul_hi_u32 s7, s57, 0x1800
	s_mul_i32 s39, s37, 0xc0
	s_add_u32 s6, s6, s39
	s_addc_u32 s7, s7, 0
	s_add_u32 s6, s6, s28
	s_addc_u32 s7, s7, s29
	s_mul_i32 s100, s57, 0xc00
	s_mul_hi_u32 s101, s57, 0xc00
	s_add_u32 s100, s100, s39
	s_addc_u32 s101, s101, 0
	s_add_u32 s100, s100, s34
	s_addc_u32 s101, s101, s35
	s_waitcnt vmcnt(0)
	s_cmp_eq_u32 s56, 0
	s_cbranch_scc1 .Lscan2_hzero
	v_lshlrev_b32_e32 v58, 16, v59
	v_and_b32_e32 v59, 0xffff0000, v59
	v_lshlrev_b32_e32 v60, 16, v61
	v_and_b32_e32 v61, 0xffff0000, v61
	v_lshlrev_b32_e32 v62, 16, v63
	v_and_b32_e32 v63, 0xffff0000, v63
	s_branch .Lscan2_hdone

.Lscan2_sub:
	global_load_dwordx2 v[24:25], v235, s[6:7] offset:0
	global_load_dwordx2 v[26:27], v235, s[6:7] offset:32
	global_load_dwordx2 v[28:29], v235, s[6:7] offset:64
	global_load_dwordx2 v[30:31], v235, s[6:7] offset:96
	global_load_dwordx2 v[32:33], v235, s[6:7] offset:128
	global_load_dwordx2 v[34:35], v235, s[6:7] offset:160
	s_mov_b64 s[62:63], s[44:45]
	global_load_dword v82, v233, s[62:63]
	s_add_u32 s62, s62, 0x1800
	s_addc_u32 s63, s63, 0
	global_load_dword v83, v233, s[62:63]
	s_add_u32 s62, s62, 0x1800
	s_addc_u32 s63, s63, 0
	global_load_dword v84, v233, s[62:63]
	s_add_u32 s62, s62, 0x1800
	s_addc_u32 s63, s63, 0
	global_load_dword v85, v233, s[62:63]
	s_add_u32 s62, s62, 0x1800
	s_addc_u32 s63, s63, 0
	global_load_dword v86, v233, s[62:63]
	s_add_u32 s62, s62, 0x1800
	s_addc_u32 s63, s63, 0
	global_load_dword v87, v233, s[62:63]
	s_add_u32 s62, s62, 0x1800
	s_addc_u32 s63, s63, 0
	global_load_dword v88, v233, s[62:63]
	s_add_u32 s62, s62, 0x1800
	s_addc_u32 s63, s63, 0
	global_load_dword v89, v233, s[62:63]
	s_add_u32 s62, s62, 0x1800
	s_addc_u32 s63, s63, 0
	global_load_dword v90, v233, s[62:63]
	s_add_u32 s62, s62, 0x1800
	s_addc_u32 s63, s63, 0
	global_load_dword v91, v233, s[62:63]
	s_add_u32 s62, s62, 0x1800
	s_addc_u32 s63, s63, 0
	global_load_dword v92, v233, s[62:63]
	s_add_u32 s62, s62, 0x1800
	s_addc_u32 s63, s63, 0
	global_load_dword v93, v233, s[62:63]
	s_add_u32 s62, s62, 0x1800
	s_addc_u32 s63, s63, 0
	global_load_dword v94, v233, s[62:63]
	s_add_u32 s62, s62, 0x1800
	s_addc_u32 s63, s63, 0
	global_load_dword v95, v233, s[62:63]
	s_add_u32 s62, s62, 0x1800
	s_addc_u32 s63, s63, 0
	global_load_dword v96, v233, s[62:63]
	s_add_u32 s62, s62, 0x1800
	s_addc_u32 s63, s63, 0
	global_load_dword v97, v233, s[62:63]
	s_add_u32 s62, s62, 0x1800
	s_addc_u32 s63, s63, 0
	s_mov_b64 s[44:45], s[62:63]
	s_mov_b32 s62, -1
	s_mov_b32 s63, 0xffff
	s_mov_b64 exec, s[62:63]
	v_lshlrev_b32_e32 v64, 16, v66
	v_and_b32_e32 v65, 0xffff0000, v66
	v_fma_f32 v242, v58, v48, v56
	v_fma_f32 v243, v59, v49, v57
	v_lshlrev_b32_e32 v58, 16, v67
	v_and_b32_e32 v59, 0xffff0000, v67
	v_fma_f32 v244, v60, v48, v56
	v_fma_f32 v245, v61, v49, v57
	v_fma_f32 v242, v60, v50, v242
	v_fma_f32 v243, v61, v51, v243
	v_fma_f32 v244, v62, v50, v244
	v_fma_f32 v245, v63, v51, v245
	v_fma_f32 v242, v62, v52, v242
	v_fma_f32 v243, v63, v53, v243
	v_fma_f32 v244, v64, v52, v244
	v_fma_f32 v245, v65, v53, v245
	v_fma_f32 v242, v64, v54, v242
	v_fma_f32 v243, v65, v55, v243
	v_fma_f32 v244, v58, v54, v244
	v_fma_f32 v245, v59, v55, v245
	ds_write_b64 v226, v[242:243] offset:0
	v_cvt_pk_bf16_f32 v246, v242, v243
	ds_write_b64 v226, v[244:245] offset:400
	v_cvt_pk_bf16_f32 v247, v244, v245
	ds_write_b32 v227, v246 offset:0
	ds_write_b32 v227, v247 offset:208
	v_lshlrev_b32_e32 v60, 16, v68
	v_and_b32_e32 v61, 0xffff0000, v68
	v_fma_f32 v242, v62, v48, v56
	v_fma_f32 v243, v63, v49, v57
	v_lshlrev_b32_e32 v62, 16, v69
	v_and_b32_e32 v63, 0xffff0000, v69
	v_fma_f32 v244, v64, v48, v56
	v_fma_f32 v245, v65, v49, v57
	v_fma_f32 v242, v64, v50, v242
	v_fma_f32 v243, v65, v51, v243
	v_fma_f32 v244, v58, v50, v244
	v_fma_f32 v245, v59, v51, v245
	v_fma_f32 v242, v58, v52, v242
	v_fma_f32 v243, v59, v53, v243
	v_fma_f32 v244, v60, v52, v244
	v_fma_f32 v245, v61, v53, v245
	v_fma_f32 v242, v60, v54, v242
	v_fma_f32 v243, v61, v55, v243
	v_fma_f32 v244, v62, v54, v244
	v_fma_f32 v245, v63, v55, v245
	ds_write_b64 v226, v[242:243] offset:800
	v_cvt_pk_bf16_f32 v246, v242, v243
	ds_write_b64 v226, v[244:245] offset:1200
	v_cvt_pk_bf16_f32 v247, v244, v245
	ds_write_b32 v227, v246 offset:416
	ds_write_b32 v227, v247 offset:624
	v_lshlrev_b32_e32 v64, 16, v70
	v_and_b32_e32 v65, 0xffff0000, v70
	v_fma_f32 v242, v58, v48, v56
	v_fma_f32 v243, v59, v49, v57
	v_lshlrev_b32_e32 v58, 16, v71
	v_and_b32_e32 v59, 0xffff0000, v71
	v_fma_f32 v244, v60, v48, v56
	v_fma_f32 v245, v61, v49, v57
	v_fma_f32 v242, v60, v50, v242
	v_fma_f32 v243, v61, v51, v243
	v_fma_f32 v244, v62, v50, v244
	v_fma_f32 v245, v63, v51, v245
	v_fma_f32 v242, v62, v52, v242
	v_fma_f32 v243, v63, v53, v243
	v_fma_f32 v244, v64, v52, v244
	v_fma_f32 v245, v65, v53, v245
	v_fma_f32 v242, v64, v54, v242
	v_fma_f32 v243, v65, v55, v243
	v_fma_f32 v244, v58, v54, v244
	v_fma_f32 v245, v59, v55, v245
	ds_write_b64 v226, v[242:243] offset:1600
	v_cvt_pk_bf16_f32 v246, v242, v243
	ds_write_b64 v226, v[244:245] offset:2000
	v_cvt_pk_bf16_f32 v247, v244, v245
	ds_write_b32 v227, v246 offset:832
	ds_write_b32 v227, v247 offset:1040
	v_lshlrev_b32_e32 v60, 16, v72
	v_and_b32_e32 v61, 0xffff0000, v72
	v_fma_f32 v242, v62, v48, v56
	v_fma_f32 v243, v63, v49, v57
	v_lshlrev_b32_e32 v62, 16, v73
	v_and_b32_e32 v63, 0xffff0000, v73
	v_fma_f32 v244, v64, v48, v56
	v_fma_f32 v245, v65, v49, v57
	v_fma_f32 v242, v64, v50, v242
	v_fma_f32 v243, v65, v51, v243
	v_fma_f32 v244, v58, v50, v244
	v_fma_f32 v245, v59, v51, v245
	v_fma_f32 v242, v58, v52, v242
	v_fma_f32 v243, v59, v53, v243
	v_fma_f32 v244, v60, v52, v244
	v_fma_f32 v245, v61, v53, v245
	v_fma_f32 v242, v60, v54, v242
	v_fma_f32 v243, v61, v55, v243
	v_fma_f32 v244, v62, v54, v244
	v_fma_f32 v245, v63, v55, v245
	ds_write_b64 v226, v[242:243] offset:2400
	v_cvt_pk_bf16_f32 v246, v242, v243
	ds_write_b64 v226, v[244:245] offset:2800
	v_cvt_pk_bf16_f32 v247, v244, v245
	ds_write_b32 v227, v246 offset:1248
	ds_write_b32 v227, v247 offset:1456
	v_lshlrev_b32_e32 v64, 16, v74
	v_and_b32_e32 v65, 0xffff0000, v74
	v_fma_f32 v242, v58, v48, v56
	v_fma_f32 v243, v59, v49, v57
	v_lshlrev_b32_e32 v58, 16, v75
	v_and_b32_e32 v59, 0xffff0000, v75
	v_fma_f32 v244, v60, v48, v56
	v_fma_f32 v245, v61, v49, v57
	v_fma_f32 v242, v60, v50, v242
	v_fma_f32 v243, v61, v51, v243
	v_fma_f32 v244, v62, v50, v244
	v_fma_f32 v245, v63, v51, v245
	v_fma_f32 v242, v62, v52, v242
	v_fma_f32 v243, v63, v53, v243
	v_fma_f32 v244, v64, v52, v244
	v_fma_f32 v245, v65, v53, v245
	v_fma_f32 v242, v64, v54, v242
	v_fma_f32 v243, v65, v55, v243
	v_fma_f32 v244, v58, v54, v244
	v_fma_f32 v245, v59, v55, v245
	ds_write_b64 v226, v[242:243] offset:3200
	v_cvt_pk_bf16_f32 v246, v242, v243
	ds_write_b64 v226, v[244:245] offset:3600
	v_cvt_pk_bf16_f32 v247, v244, v245
	ds_write_b32 v227, v246 offset:1664
	ds_write_b32 v227, v247 offset:1872
	v_lshlrev_b32_e32 v60, 16, v76
	v_and_b32_e32 v61, 0xffff0000, v76
	v_fma_f32 v242, v62, v48, v56
	v_fma_f32 v243, v63, v49, v57
	v_lshlrev_b32_e32 v62, 16, v77
	v_and_b32_e32 v63, 0xffff0000, v77
	v_fma_f32 v244, v64, v48, v56
	v_fma_f32 v245, v65, v49, v57
	v_fma_f32 v242, v64, v50, v242
	v_fma_f32 v243, v65, v51, v243
	v_fma_f32 v244, v58, v50, v244
	v_fma_f32 v245, v59, v51, v245
	v_fma_f32 v242, v58, v52, v242
	v_fma_f32 v243, v59, v53, v243
	v_fma_f32 v244, v60, v52, v244
	v_fma_f32 v245, v61, v53, v245
	v_fma_f32 v242, v60, v54, v242
	v_fma_f32 v243, v61, v55, v243
	v_fma_f32 v244, v62, v54, v244
	v_fma_f32 v245, v63, v55, v245
	ds_write_b64 v226, v[242:243] offset:4000
	v_cvt_pk_bf16_f32 v246, v242, v243
	ds_write_b64 v226, v[244:245] offset:4400
	v_cvt_pk_bf16_f32 v247, v244, v245
	ds_write_b32 v227, v246 offset:2080
	ds_write_b32 v227, v247 offset:2288
	v_lshlrev_b32_e32 v64, 16, v78
	v_and_b32_e32 v65, 0xffff0000, v78
	v_fma_f32 v242, v58, v48, v56
	v_fma_f32 v243, v59, v49, v57
	v_lshlrev_b32_e32 v58, 16, v79
	v_and_b32_e32 v59, 0xffff0000, v79
	v_fma_f32 v244, v60, v48, v56
	v_fma_f32 v245, v61, v49, v57
	v_fma_f32 v242, v60, v50, v242
	v_fma_f32 v243, v61, v51, v243
	v_fma_f32 v244, v62, v50, v244
	v_fma_f32 v245, v63, v51, v245
	v_fma_f32 v242, v62, v52, v242
	v_fma_f32 v243, v63, v53, v243
	v_fma_f32 v244, v64, v52, v244
	v_fma_f32 v245, v65, v53, v245
	v_fma_f32 v242, v64, v54, v242
	v_fma_f32 v243, v65, v55, v243
	v_fma_f32 v244, v58, v54, v244
	v_fma_f32 v245, v59, v55, v245
	ds_write_b64 v226, v[242:243] offset:4800
	v_cvt_pk_bf16_f32 v246, v242, v243
	ds_write_b64 v226, v[244:245] offset:5200
	v_cvt_pk_bf16_f32 v247, v244, v245
	ds_write_b32 v227, v246 offset:2496
	ds_write_b32 v227, v247 offset:2704
	v_lshlrev_b32_e32 v60, 16, v80
	v_and_b32_e32 v61, 0xffff0000, v80
	v_fma_f32 v242, v62, v48, v56
	v_fma_f32 v243, v63, v49, v57
	v_lshlrev_b32_e32 v62, 16, v81
	v_and_b32_e32 v63, 0xffff0000, v81
	v_fma_f32 v244, v64, v48, v56
	v_fma_f32 v245, v65, v49, v57
	v_fma_f32 v242, v64, v50, v242
	v_fma_f32 v243, v65, v51, v243
	v_fma_f32 v244, v58, v50, v244
	v_fma_f32 v245, v59, v51, v245
	v_fma_f32 v242, v58, v52, v242
	v_fma_f32 v243, v59, v53, v243
	v_fma_f32 v244, v60, v52, v244
	v_fma_f32 v245, v61, v53, v245
	v_fma_f32 v242, v60, v54, v242
	v_fma_f32 v243, v61, v55, v243
	v_fma_f32 v244, v62, v54, v244
	v_fma_f32 v245, v63, v55, v245
	ds_write_b64 v226, v[242:243] offset:5600
	v_cvt_pk_bf16_f32 v246, v242, v243
	ds_write_b64 v226, v[244:245] offset:6000
	v_cvt_pk_bf16_f32 v247, v244, v245
	ds_write_b32 v227, v246 offset:2912
	ds_write_b32 v227, v247 offset:3120
	s_mov_b64 exec, -1
	s_waitcnt lgkmcnt(0)
	ds_read_b128 v[98:101], v228 offset:0
	ds_read_b128 v[102:105], v228 offset:64
	ds_read_b128 v[106:109], v228 offset:128
	ds_read_b128 v[110:113], v229 offset:0
	ds_read_b128 v[122:125], v229 offset:19968
	ds_read_b128 v[114:117], v229 offset:64
	ds_read_b128 v[126:129], v229 offset:20032
	ds_read_b128 v[118:121], v229 offset:128
	ds_read_b128 v[130:133], v229 offset:20096
	ds_read_b128 v[150:153], v230 offset:0
	ds_read_b128 v[154:157], v230 offset:384
	ds_read_b128 v[158:161], v230 offset:768
	ds_read_b128 v[162:165], v231 offset:0
	s_waitcnt lgkmcnt(0)
	v_mfma_f32_16x16x32_bf16 v[134:137], v[110:113], v[98:101], 0
	v_mfma_f32_16x16x32_bf16 v[138:141], v[122:125], v[98:101], 0
	v_mfma_f32_16x16x32_bf16 v[134:137], v[114:117], v[102:105], v[134:137]
	v_mfma_f32_16x16x32_bf16 v[138:141], v[126:129], v[102:105], v[138:141]
	v_mfma_f32_16x16x32_bf16 v[134:137], v[118:121], v[106:109], v[134:137]
	v_mfma_f32_16x16x32_bf16 v[138:141], v[130:133], v[106:109], v[138:141]
	ds_read_b128 v[110:113], v229 offset:3328
	ds_read_b128 v[122:125], v229 offset:23296
	ds_read_b128 v[114:117], v229 offset:3392
	ds_read_b128 v[126:129], v229 offset:23360
	ds_read_b128 v[118:121], v229 offset:3456
	ds_read_b128 v[130:133], v229 offset:23424
	s_nop 7
	s_nop 7
	v_add_f32_e32 v166, v134, v150
	v_add_f32_e32 v204, v135, v151
	v_add_f32_e32 v210, v136, v152
	v_add_f32_e32 v216, v137, v153
	v_add_f32_e32 v167, v138, v154
	v_add_f32_e32 v205, v139, v155
	v_add_f32_e32 v211, v140, v156
	v_add_f32_e32 v217, v141, v157
	v_mul_f32_e32 v166, 0xbfb8aa3b, v166
	v_mul_f32_e32 v204, 0xbfb8aa3b, v204
	v_mul_f32_e32 v210, 0xbfb8aa3b, v210
	v_mul_f32_e32 v216, 0xbfb8aa3b, v216
	v_mul_f32_e32 v167, 0xbfb8aa3b, v167
	v_mul_f32_e32 v205, 0xbfb8aa3b, v205
	v_mul_f32_e32 v211, 0xbfb8aa3b, v211
	v_mul_f32_e32 v217, 0xbfb8aa3b, v217
	v_exp_f32_e32 v166, v166
	v_exp_f32_e32 v204, v204
	v_exp_f32_e32 v210, v210
	v_exp_f32_e32 v216, v216
	v_exp_f32_e32 v167, v167
	v_exp_f32_e32 v205, v205
	v_exp_f32_e32 v211, v211
	v_exp_f32_e32 v217, v217
	v_add_f32_e32 v166, 1.0, v166
	v_add_f32_e32 v204, 1.0, v204
	v_add_f32_e32 v210, 1.0, v210
	v_add_f32_e32 v216, 1.0, v216
	v_add_f32_e32 v167, 1.0, v167
	v_add_f32_e32 v205, 1.0, v205
	v_add_f32_e32 v211, 1.0, v211
	v_add_f32_e32 v217, 1.0, v217
	v_rcp_f32_e32 v166, v166
	v_rcp_f32_e32 v204, v204
	v_rcp_f32_e32 v210, v210
	v_rcp_f32_e32 v216, v216
	v_rcp_f32_e32 v167, v167
	v_rcp_f32_e32 v205, v205
	v_rcp_f32_e32 v211, v211
	v_rcp_f32_e32 v217, v217
	v_mul_f32_e32 v168, 0xc1000000, v166
	v_mul_f32_e32 v206, 0xc1000000, v204
	v_mul_f32_e32 v212, 0xc1000000, v210
	v_mul_f32_e32 v218, 0xc1000000, v216
	v_mul_f32_e32 v168, v158, v168
	v_mul_f32_e32 v206, v159, v206
	v_mul_f32_e32 v212, v160, v212
	v_mul_f32_e32 v218, v161, v218
	v_add_f32_e32 v169, v168, v168
	v_add_f32_e32 v207, v206, v206
	v_add_f32_e32 v213, v212, v212
	v_add_f32_e32 v219, v218, v218
	v_mul_f32_e32 v171, 0x3fb8aa3b, v169
	v_mul_f32_e32 v209, 0x3fb8aa3b, v207
	v_mul_f32_e32 v215, 0x3fb8aa3b, v213
	v_mul_f32_e32 v221, 0x3fb8aa3b, v219
	v_fmamk_f32 v170, v169, 0x3c088888, v195
	v_fmamk_f32 v208, v207, 0x3c088888, v195
	v_fmamk_f32 v214, v213, 0x3c088888, v195
	v_fmamk_f32 v220, v219, 0x3c088888, v195
	v_exp_f32_e32 v171, v171
	v_exp_f32_e32 v209, v209
	v_exp_f32_e32 v215, v215
	v_exp_f32_e32 v221, v221
	v_fmaak_f32 v170, v169, v170, 0x3e2aaaab
	v_fmaak_f32 v208, v207, v208, 0x3e2aaaab
	v_fmaak_f32 v214, v213, v214, 0x3e2aaaab
	v_fmaak_f32 v220, v219, v220, 0x3e2aaaab
	v_fma_f32 v170, v169, v170, 0.5
	v_fma_f32 v208, v207, v208, 0.5
	v_fma_f32 v214, v213, v214, 0.5
	v_fma_f32 v220, v219, v220, 0.5
	v_fma_f32 v170, v169, v170, 1.0
	v_fma_f32 v208, v207, v208, 1.0
	v_fma_f32 v214, v213, v214, 1.0
	v_fma_f32 v220, v219, v220, 1.0
	v_sub_f32_e32 v171, 1.0, v171
	v_sub_f32_e32 v209, 1.0, v209
	v_sub_f32_e32 v215, 1.0, v215
	v_sub_f32_e32 v221, 1.0, v221
	v_mul_f32_e64 v170, v170, -v169
	v_mul_f32_e64 v208, v208, -v207
	v_mul_f32_e64 v214, v214, -v213
	v_mul_f32_e64 v220, v220, -v219
	v_cmp_nlt_f32_e32 vcc, s1, v169
	v_cmp_nlt_f32_e64 s[62:63], s1, v207
	v_cmp_nlt_f32_e64 s[56:57], s1, v213
	v_mul_f32_e32 v167, v162, v167
	v_mul_f32_e32 v205, v163, v205
	v_mul_f32_e32 v211, v164, v211
	v_mul_f32_e32 v217, v165, v217
	v_cndmask_b32_e32 v170, v170, v171, vcc
	v_cmp_nlt_f32_e32 vcc, s1, v219
	v_cndmask_b32_e64 v208, v208, v209, s[62:63]
	v_cndmask_b32_e64 v214, v214, v215, s[56:57]
	v_mul_f32_e32 v166, 0x3fb8aa3b, v168
	v_mul_f32_e32 v204, 0x3fb8aa3b, v206
	v_mul_f32_e32 v210, 0x3fb8aa3b, v212
	v_mul_f32_e32 v216, 0x3fb8aa3b, v218
	v_cndmask_b32_e32 v220, v220, v221, vcc
	v_sqrt_f32_e32 v170, v170
	v_sqrt_f32_e32 v208, v208
	v_sqrt_f32_e32 v214, v214
	v_sqrt_f32_e32 v220, v220
	v_exp_f32_e32 v166, v166
	v_exp_f32_e32 v204, v204
	v_exp_f32_e32 v210, v210
	v_exp_f32_e32 v216, v216
	v_mul_f32_e32 v167, v167, v170
	v_mul_f32_e32 v205, v205, v208
	v_mul_f32_e32 v211, v211, v214
	v_mul_f32_e32 v217, v217, v220
	ds_read_b128 v[150:153], v230 offset:64
	ds_read_b128 v[154:157], v230 offset:448
	ds_read_b128 v[158:161], v230 offset:832
	ds_read_b128 v[162:165], v231 offset:64
	s_waitcnt lgkmcnt(0)
	v_mfma_f32_16x16x32_bf16 v[142:145], v[110:113], v[98:101], 0
	v_mfma_f32_16x16x32_bf16 v[146:149], v[122:125], v[98:101], 0
	v_mfma_f32_16x16x32_bf16 v[142:145], v[114:117], v[102:105], v[142:145]
	v_mfma_f32_16x16x32_bf16 v[146:149], v[126:129], v[102:105], v[146:149]
	v_mfma_f32_16x16x32_bf16 v[142:145], v[118:121], v[106:109], v[142:145]
	v_mfma_f32_16x16x32_bf16 v[146:149], v[130:133], v[106:109], v[146:149]
	v_fmac_f32_dpp v167, v167, v166 row_shr:1 row_mask:0xf bank_mask:0xf bound_ctrl:1
	v_fmac_f32_dpp v205, v205, v204 row_shr:1 row_mask:0xf bank_mask:0xf bound_ctrl:1
	v_fmac_f32_dpp v211, v211, v210 row_shr:1 row_mask:0xf bank_mask:0xf bound_ctrl:1
	v_fmac_f32_dpp v217, v217, v216 row_shr:1 row_mask:0xf bank_mask:0xf bound_ctrl:1
	v_mul_f32_dpp v166, v166, v166 row_shr:1 row_mask:0xf bank_mask:0xf
	v_mul_f32_dpp v204, v204, v204 row_shr:1 row_mask:0xf bank_mask:0xf
	v_mul_f32_dpp v210, v210, v210 row_shr:1 row_mask:0xf bank_mask:0xf
	v_mul_f32_dpp v216, v216, v216 row_shr:1 row_mask:0xf bank_mask:0xf
	v_fmac_f32_dpp v167, v167, v166 row_shr:2 row_mask:0xf bank_mask:0xf bound_ctrl:1
	v_fmac_f32_dpp v205, v205, v204 row_shr:2 row_mask:0xf bank_mask:0xf bound_ctrl:1
	v_fmac_f32_dpp v211, v211, v210 row_shr:2 row_mask:0xf bank_mask:0xf bound_ctrl:1
	v_fmac_f32_dpp v217, v217, v216 row_shr:2 row_mask:0xf bank_mask:0xf bound_ctrl:1
	v_mul_f32_dpp v166, v166, v166 row_shr:2 row_mask:0xf bank_mask:0xf
	v_mul_f32_dpp v204, v204, v204 row_shr:2 row_mask:0xf bank_mask:0xf
	v_mul_f32_dpp v210, v210, v210 row_shr:2 row_mask:0xf bank_mask:0xf
	v_mul_f32_dpp v216, v216, v216 row_shr:2 row_mask:0xf bank_mask:0xf
	v_fmac_f32_dpp v167, v167, v166 row_shr:4 row_mask:0xf bank_mask:0xf bound_ctrl:1
	v_fmac_f32_dpp v205, v205, v204 row_shr:4 row_mask:0xf bank_mask:0xf bound_ctrl:1
	v_fmac_f32_dpp v211, v211, v210 row_shr:4 row_mask:0xf bank_mask:0xf bound_ctrl:1
	v_fmac_f32_dpp v217, v217, v216 row_shr:4 row_mask:0xf bank_mask:0xf bound_ctrl:1
	v_mul_f32_dpp v166, v166, v166 row_shr:4 row_mask:0xf bank_mask:0xf
	v_mul_f32_dpp v204, v204, v204 row_shr:4 row_mask:0xf bank_mask:0xf
	v_mul_f32_dpp v210, v210, v210 row_shr:4 row_mask:0xf bank_mask:0xf
	v_mul_f32_dpp v216, v216, v216 row_shr:4 row_mask:0xf bank_mask:0xf
	v_fmac_f32_dpp v167, v167, v166 row_shr:8 row_mask:0xf bank_mask:0xf bound_ctrl:1
	v_fmac_f32_dpp v205, v205, v204 row_shr:8 row_mask:0xf bank_mask:0xf bound_ctrl:1
	v_fmac_f32_dpp v211, v211, v210 row_shr:8 row_mask:0xf bank_mask:0xf bound_ctrl:1
	v_fmac_f32_dpp v217, v217, v216 row_shr:8 row_mask:0xf bank_mask:0xf bound_ctrl:1
	v_mul_f32_dpp v166, v166, v166 row_shr:8 row_mask:0xf bank_mask:0xf
	v_mul_f32_dpp v204, v204, v204 row_shr:8 row_mask:0xf bank_mask:0xf
	v_mul_f32_dpp v210, v210, v210 row_shr:8 row_mask:0xf bank_mask:0xf
	v_mul_f32_dpp v216, v216, v216 row_shr:8 row_mask:0xf bank_mask:0xf
	v_fma_f32 v168, v166, v0, v167
	v_fma_f32 v206, v204, v1, v205
	v_fma_f32 v212, v210, v2, v211
	v_fma_f32 v218, v216, v3, v217
	ds_bpermute_b32 v0, v232, v168
	ds_bpermute_b32 v1, v232, v206
	ds_bpermute_b32 v2, v232, v212
	ds_bpermute_b32 v3, v232, v218
	s_waitcnt vmcnt(21)
	v_lshlrev_b32_e32 v169, 16, v24
	v_and_b32_e32 v207, 0xffff0000, v24
	v_lshlrev_b32_e32 v213, 16, v25
	v_and_b32_e32 v219, 0xffff0000, v25
	v_mul_f32_e32 v170, 0x3d372713, v169
	v_mul_f32_e32 v208, 0x3d372713, v207
	v_mul_f32_e32 v214, 0x3d372713, v213
	v_mul_f32_e32 v220, 0x3d372713, v219
	v_mul_f32_e32 v170, v169, v170
	v_mul_f32_e32 v208, v207, v208
	v_mul_f32_e32 v214, v213, v214
	v_mul_f32_e32 v220, v219, v220
	v_fma_f32 v170, v169, v170, v169
	v_fma_f32 v208, v207, v208, v207
	v_fma_f32 v214, v213, v214, v213
	v_fma_f32 v220, v219, v220, v219
	v_mul_f32_e32 v170, 0x3f4c422a, v170
	v_mul_f32_e32 v208, 0x3f4c422a, v208
	v_mul_f32_e32 v214, 0x3f4c422a, v214
	v_mul_f32_e32 v220, 0x3f4c422a, v220
	v_mul_f32_e32 v170, 0xc038aa3b, v170
	v_mul_f32_e32 v208, 0xc038aa3b, v208
	v_mul_f32_e32 v214, 0xc038aa3b, v214
	v_mul_f32_e32 v220, 0xc038aa3b, v220
	v_exp_f32_e32 v170, v170
	v_exp_f32_e32 v208, v208
	v_exp_f32_e32 v214, v214
	v_exp_f32_e32 v220, v220
	v_add_f32_e32 v170, 1.0, v170
	v_add_f32_e32 v208, 1.0, v208
	v_add_f32_e32 v214, 1.0, v214
	v_add_f32_e32 v220, 1.0, v220
	v_rcp_f32_e32 v170, v170
	v_rcp_f32_e32 v208, v208
	v_rcp_f32_e32 v214, v214
	v_rcp_f32_e32 v220, v220
	v_mul_f32_e32 v170, v169, v170
	v_mul_f32_e32 v208, v207, v208
	v_mul_f32_e32 v214, v213, v214
	v_mul_f32_e32 v220, v219, v220
	v_mul_f32_e32 v170, v170, v168
	v_mul_f32_e32 v208, v208, v206
	v_mul_f32_e32 v214, v214, v212
	v_mul_f32_e32 v220, v220, v218
	v_cvt_pk_bf16_f32 v242, v170, v208
	v_cvt_pk_bf16_f32 v243, v214, v220
	global_store_dwordx2 v236, v[242:243], s[100:101] offset:0
	ds_read_b128 v[110:113], v229 offset:6656
	ds_read_b128 v[122:125], v229 offset:26624
	ds_read_b128 v[114:117], v229 offset:6720
	ds_read_b128 v[126:129], v229 offset:26688
	ds_read_b128 v[118:121], v229 offset:6784
	ds_read_b128 v[130:133], v229 offset:26752
	v_add_f32_e32 v166, v142, v150
	v_add_f32_e32 v204, v143, v151
	v_add_f32_e32 v210, v144, v152
	v_add_f32_e32 v216, v145, v153
	v_add_f32_e32 v167, v146, v154
	v_add_f32_e32 v205, v147, v155
	v_add_f32_e32 v211, v148, v156
	v_add_f32_e32 v217, v149, v157
	v_mul_f32_e32 v166, 0xbfb8aa3b, v166
	v_mul_f32_e32 v204, 0xbfb8aa3b, v204
	v_mul_f32_e32 v210, 0xbfb8aa3b, v210
	v_mul_f32_e32 v216, 0xbfb8aa3b, v216
	v_mul_f32_e32 v167, 0xbfb8aa3b, v167
	v_mul_f32_e32 v205, 0xbfb8aa3b, v205
	v_mul_f32_e32 v211, 0xbfb8aa3b, v211
	v_mul_f32_e32 v217, 0xbfb8aa3b, v217
	v_exp_f32_e32 v166, v166
	v_exp_f32_e32 v204, v204
	v_exp_f32_e32 v210, v210
	v_exp_f32_e32 v216, v216
	v_exp_f32_e32 v167, v167
	v_exp_f32_e32 v205, v205
	v_exp_f32_e32 v211, v211
	v_exp_f32_e32 v217, v217
	v_add_f32_e32 v166, 1.0, v166
	v_add_f32_e32 v204, 1.0, v204
	v_add_f32_e32 v210, 1.0, v210
	v_add_f32_e32 v216, 1.0, v216
	v_add_f32_e32 v167, 1.0, v167
	v_add_f32_e32 v205, 1.0, v205
	v_add_f32_e32 v211, 1.0, v211
	v_add_f32_e32 v217, 1.0, v217
	v_rcp_f32_e32 v166, v166
	v_rcp_f32_e32 v204, v204
	v_rcp_f32_e32 v210, v210
	v_rcp_f32_e32 v216, v216
	v_rcp_f32_e32 v167, v167
	v_rcp_f32_e32 v205, v205
	v_rcp_f32_e32 v211, v211
	v_rcp_f32_e32 v217, v217
	v_mul_f32_e32 v168, 0xc1000000, v166
	v_mul_f32_e32 v206, 0xc1000000, v204
	v_mul_f32_e32 v212, 0xc1000000, v210
	v_mul_f32_e32 v218, 0xc1000000, v216
	v_mul_f32_e32 v168, v158, v168
	v_mul_f32_e32 v206, v159, v206
	v_mul_f32_e32 v212, v160, v212
	v_mul_f32_e32 v218, v161, v218
	v_add_f32_e32 v169, v168, v168
	v_add_f32_e32 v207, v206, v206
	v_add_f32_e32 v213, v212, v212
	v_add_f32_e32 v219, v218, v218
	v_mul_f32_e32 v171, 0x3fb8aa3b, v169
	v_mul_f32_e32 v209, 0x3fb8aa3b, v207
	v_mul_f32_e32 v215, 0x3fb8aa3b, v213
	v_mul_f32_e32 v221, 0x3fb8aa3b, v219
	v_fmamk_f32 v170, v169, 0x3c088888, v195
	v_fmamk_f32 v208, v207, 0x3c088888, v195
	v_fmamk_f32 v214, v213, 0x3c088888, v195
	v_fmamk_f32 v220, v219, 0x3c088888, v195
	v_exp_f32_e32 v171, v171
	v_exp_f32_e32 v209, v209
	v_exp_f32_e32 v215, v215
	v_exp_f32_e32 v221, v221
	v_fmaak_f32 v170, v169, v170, 0x3e2aaaab
	v_fmaak_f32 v208, v207, v208, 0x3e2aaaab
	v_fmaak_f32 v214, v213, v214, 0x3e2aaaab
	v_fmaak_f32 v220, v219, v220, 0x3e2aaaab
	v_fma_f32 v170, v169, v170, 0.5
	v_fma_f32 v208, v207, v208, 0.5
	v_fma_f32 v214, v213, v214, 0.5
	v_fma_f32 v220, v219, v220, 0.5
	v_fma_f32 v170, v169, v170, 1.0
	v_fma_f32 v208, v207, v208, 1.0
	v_fma_f32 v214, v213, v214, 1.0
	v_fma_f32 v220, v219, v220, 1.0
	v_sub_f32_e32 v171, 1.0, v171
	v_sub_f32_e32 v209, 1.0, v209
	v_sub_f32_e32 v215, 1.0, v215
	v_sub_f32_e32 v221, 1.0, v221
	v_mul_f32_e64 v170, v170, -v169
	v_mul_f32_e64 v208, v208, -v207
	v_mul_f32_e64 v214, v214, -v213
	v_mul_f32_e64 v220, v220, -v219
	v_cmp_nlt_f32_e32 vcc, s1, v169
	v_cmp_nlt_f32_e64 s[62:63], s1, v207
	v_cmp_nlt_f32_e64 s[56:57], s1, v213
	v_mul_f32_e32 v167, v162, v167
	v_mul_f32_e32 v205, v163, v205
	v_mul_f32_e32 v211, v164, v211
	v_mul_f32_e32 v217, v165, v217
	v_cndmask_b32_e32 v170, v170, v171, vcc
	v_cmp_nlt_f32_e32 vcc, s1, v219
	v_cndmask_b32_e64 v208, v208, v209, s[62:63]
	v_cndmask_b32_e64 v214, v214, v215, s[56:57]
	v_mul_f32_e32 v166, 0x3fb8aa3b, v168
	v_mul_f32_e32 v204, 0x3fb8aa3b, v206
	v_mul_f32_e32 v210, 0x3fb8aa3b, v212
	v_mul_f32_e32 v216, 0x3fb8aa3b, v218
	v_cndmask_b32_e32 v220, v220, v221, vcc
	v_sqrt_f32_e32 v170, v170
	v_sqrt_f32_e32 v208, v208
	v_sqrt_f32_e32 v214, v214
	v_sqrt_f32_e32 v220, v220
	v_exp_f32_e32 v166, v166
	v_exp_f32_e32 v204, v204
	v_exp_f32_e32 v210, v210
	v_exp_f32_e32 v216, v216
	v_mul_f32_e32 v167, v167, v170
	v_mul_f32_e32 v205, v205, v208
	v_mul_f32_e32 v211, v211, v214
	v_mul_f32_e32 v217, v217, v220
	ds_read_b128 v[150:153], v230 offset:128
	ds_read_b128 v[154:157], v230 offset:512
	ds_read_b128 v[158:161], v230 offset:896
	ds_read_b128 v[162:165], v231 offset:128
	s_waitcnt lgkmcnt(0)
	v_mfma_f32_16x16x32_bf16 v[134:137], v[110:113], v[98:101], 0
	v_mfma_f32_16x16x32_bf16 v[138:141], v[122:125], v[98:101], 0
	v_mfma_f32_16x16x32_bf16 v[134:137], v[114:117], v[102:105], v[134:137]
	v_mfma_f32_16x16x32_bf16 v[138:141], v[126:129], v[102:105], v[138:141]
	v_mfma_f32_16x16x32_bf16 v[134:137], v[118:121], v[106:109], v[134:137]
	v_mfma_f32_16x16x32_bf16 v[138:141], v[130:133], v[106:109], v[138:141]
	v_fmac_f32_dpp v167, v167, v166 row_shr:1 row_mask:0xf bank_mask:0xf bound_ctrl:1
	v_fmac_f32_dpp v205, v205, v204 row_shr:1 row_mask:0xf bank_mask:0xf bound_ctrl:1
	v_fmac_f32_dpp v211, v211, v210 row_shr:1 row_mask:0xf bank_mask:0xf bound_ctrl:1
	v_fmac_f32_dpp v217, v217, v216 row_shr:1 row_mask:0xf bank_mask:0xf bound_ctrl:1
	v_mul_f32_dpp v166, v166, v166 row_shr:1 row_mask:0xf bank_mask:0xf
	v_mul_f32_dpp v204, v204, v204 row_shr:1 row_mask:0xf bank_mask:0xf
	v_mul_f32_dpp v210, v210, v210 row_shr:1 row_mask:0xf bank_mask:0xf
	v_mul_f32_dpp v216, v216, v216 row_shr:1 row_mask:0xf bank_mask:0xf
	v_fmac_f32_dpp v167, v167, v166 row_shr:2 row_mask:0xf bank_mask:0xf bound_ctrl:1
	v_fmac_f32_dpp v205, v205, v204 row_shr:2 row_mask:0xf bank_mask:0xf bound_ctrl:1
	v_fmac_f32_dpp v211, v211, v210 row_shr:2 row_mask:0xf bank_mask:0xf bound_ctrl:1
	v_fmac_f32_dpp v217, v217, v216 row_shr:2 row_mask:0xf bank_mask:0xf bound_ctrl:1
	v_mul_f32_dpp v166, v166, v166 row_shr:2 row_mask:0xf bank_mask:0xf
	v_mul_f32_dpp v204, v204, v204 row_shr:2 row_mask:0xf bank_mask:0xf
	v_mul_f32_dpp v210, v210, v210 row_shr:2 row_mask:0xf bank_mask:0xf
	v_mul_f32_dpp v216, v216, v216 row_shr:2 row_mask:0xf bank_mask:0xf
	v_fmac_f32_dpp v167, v167, v166 row_shr:4 row_mask:0xf bank_mask:0xf bound_ctrl:1
	v_fmac_f32_dpp v205, v205, v204 row_shr:4 row_mask:0xf bank_mask:0xf bound_ctrl:1
	v_fmac_f32_dpp v211, v211, v210 row_shr:4 row_mask:0xf bank_mask:0xf bound_ctrl:1
	v_fmac_f32_dpp v217, v217, v216 row_shr:4 row_mask:0xf bank_mask:0xf bound_ctrl:1
	v_mul_f32_dpp v166, v166, v166 row_shr:4 row_mask:0xf bank_mask:0xf
	v_mul_f32_dpp v204, v204, v204 row_shr:4 row_mask:0xf bank_mask:0xf
	v_mul_f32_dpp v210, v210, v210 row_shr:4 row_mask:0xf bank_mask:0xf
	v_mul_f32_dpp v216, v216, v216 row_shr:4 row_mask:0xf bank_mask:0xf
	v_fmac_f32_dpp v167, v167, v166 row_shr:8 row_mask:0xf bank_mask:0xf bound_ctrl:1
	v_fmac_f32_dpp v205, v205, v204 row_shr:8 row_mask:0xf bank_mask:0xf bound_ctrl:1
	v_fmac_f32_dpp v211, v211, v210 row_shr:8 row_mask:0xf bank_mask:0xf bound_ctrl:1
	v_fmac_f32_dpp v217, v217, v216 row_shr:8 row_mask:0xf bank_mask:0xf bound_ctrl:1
	v_mul_f32_dpp v166, v166, v166 row_shr:8 row_mask:0xf bank_mask:0xf
	v_mul_f32_dpp v204, v204, v204 row_shr:8 row_mask:0xf bank_mask:0xf
	v_mul_f32_dpp v210, v210, v210 row_shr:8 row_mask:0xf bank_mask:0xf
	v_mul_f32_dpp v216, v216, v216 row_shr:8 row_mask:0xf bank_mask:0xf
	v_fma_f32 v168, v166, v4, v167
	v_fma_f32 v206, v204, v5, v205
	v_fma_f32 v212, v210, v6, v211
	v_fma_f32 v218, v216, v7, v217
	ds_bpermute_b32 v4, v232, v168
	ds_bpermute_b32 v5, v232, v206
	ds_bpermute_b32 v6, v232, v212
	ds_bpermute_b32 v7, v232, v218
	s_waitcnt vmcnt(21)
	v_lshlrev_b32_e32 v169, 16, v26
	v_and_b32_e32 v207, 0xffff0000, v26
	v_lshlrev_b32_e32 v213, 16, v27
	v_and_b32_e32 v219, 0xffff0000, v27
	v_mul_f32_e32 v170, 0x3d372713, v169
	v_mul_f32_e32 v208, 0x3d372713, v207
	v_mul_f32_e32 v214, 0x3d372713, v213
	v_mul_f32_e32 v220, 0x3d372713, v219
	v_mul_f32_e32 v170, v169, v170
	v_mul_f32_e32 v208, v207, v208
	v_mul_f32_e32 v214, v213, v214
	v_mul_f32_e32 v220, v219, v220
	v_fma_f32 v170, v169, v170, v169
	v_fma_f32 v208, v207, v208, v207
	v_fma_f32 v214, v213, v214, v213
	v_fma_f32 v220, v219, v220, v219
	v_mul_f32_e32 v170, 0x3f4c422a, v170
	v_mul_f32_e32 v208, 0x3f4c422a, v208
	v_mul_f32_e32 v214, 0x3f4c422a, v214
	v_mul_f32_e32 v220, 0x3f4c422a, v220
	v_mul_f32_e32 v170, 0xc038aa3b, v170
	v_mul_f32_e32 v208, 0xc038aa3b, v208
	v_mul_f32_e32 v214, 0xc038aa3b, v214
	v_mul_f32_e32 v220, 0xc038aa3b, v220
	v_exp_f32_e32 v170, v170
	v_exp_f32_e32 v208, v208
	v_exp_f32_e32 v214, v214
	v_exp_f32_e32 v220, v220
	v_add_f32_e32 v170, 1.0, v170
	v_add_f32_e32 v208, 1.0, v208
	v_add_f32_e32 v214, 1.0, v214
	v_add_f32_e32 v220, 1.0, v220
	v_rcp_f32_e32 v170, v170
	v_rcp_f32_e32 v208, v208
	v_rcp_f32_e32 v214, v214
	v_rcp_f32_e32 v220, v220
	v_mul_f32_e32 v170, v169, v170
	v_mul_f32_e32 v208, v207, v208
	v_mul_f32_e32 v214, v213, v214
	v_mul_f32_e32 v220, v219, v220
	v_mul_f32_e32 v170, v170, v168
	v_mul_f32_e32 v208, v208, v206
	v_mul_f32_e32 v214, v214, v212
	v_mul_f32_e32 v220, v220, v218
	v_cvt_pk_bf16_f32 v242, v170, v208
	v_cvt_pk_bf16_f32 v243, v214, v220
	global_store_dwordx2 v236, v[242:243], s[100:101] offset:32
	ds_read_b128 v[110:113], v229 offset:9984
	ds_read_b128 v[122:125], v229 offset:29952
	ds_read_b128 v[114:117], v229 offset:10048
	ds_read_b128 v[126:129], v229 offset:30016
	ds_read_b128 v[118:121], v229 offset:10112
	ds_read_b128 v[130:133], v229 offset:30080
	v_add_f32_e32 v166, v134, v150
	v_add_f32_e32 v204, v135, v151
	v_add_f32_e32 v210, v136, v152
	v_add_f32_e32 v216, v137, v153
	v_add_f32_e32 v167, v138, v154
	v_add_f32_e32 v205, v139, v155
	v_add_f32_e32 v211, v140, v156
	v_add_f32_e32 v217, v141, v157
	v_mul_f32_e32 v166, 0xbfb8aa3b, v166
	v_mul_f32_e32 v204, 0xbfb8aa3b, v204
	v_mul_f32_e32 v210, 0xbfb8aa3b, v210
	v_mul_f32_e32 v216, 0xbfb8aa3b, v216
	v_mul_f32_e32 v167, 0xbfb8aa3b, v167
	v_mul_f32_e32 v205, 0xbfb8aa3b, v205
	v_mul_f32_e32 v211, 0xbfb8aa3b, v211
	v_mul_f32_e32 v217, 0xbfb8aa3b, v217
	v_exp_f32_e32 v166, v166
	v_exp_f32_e32 v204, v204
	v_exp_f32_e32 v210, v210
	v_exp_f32_e32 v216, v216
	v_exp_f32_e32 v167, v167
	v_exp_f32_e32 v205, v205
	v_exp_f32_e32 v211, v211
	v_exp_f32_e32 v217, v217
	v_add_f32_e32 v166, 1.0, v166
	v_add_f32_e32 v204, 1.0, v204
	v_add_f32_e32 v210, 1.0, v210
	v_add_f32_e32 v216, 1.0, v216
	v_add_f32_e32 v167, 1.0, v167
	v_add_f32_e32 v205, 1.0, v205
	v_add_f32_e32 v211, 1.0, v211
	v_add_f32_e32 v217, 1.0, v217
	v_rcp_f32_e32 v166, v166
	v_rcp_f32_e32 v204, v204
	v_rcp_f32_e32 v210, v210
	v_rcp_f32_e32 v216, v216
	v_rcp_f32_e32 v167, v167
	v_rcp_f32_e32 v205, v205
	v_rcp_f32_e32 v211, v211
	v_rcp_f32_e32 v217, v217
	v_mul_f32_e32 v168, 0xc1000000, v166
	v_mul_f32_e32 v206, 0xc1000000, v204
	v_mul_f32_e32 v212, 0xc1000000, v210
	v_mul_f32_e32 v218, 0xc1000000, v216
	v_mul_f32_e32 v168, v158, v168
	v_mul_f32_e32 v206, v159, v206
	v_mul_f32_e32 v212, v160, v212
	v_mul_f32_e32 v218, v161, v218
	v_add_f32_e32 v169, v168, v168
	v_add_f32_e32 v207, v206, v206
	v_add_f32_e32 v213, v212, v212
	v_add_f32_e32 v219, v218, v218
	v_mul_f32_e32 v171, 0x3fb8aa3b, v169
	v_mul_f32_e32 v209, 0x3fb8aa3b, v207
	v_mul_f32_e32 v215, 0x3fb8aa3b, v213
	v_mul_f32_e32 v221, 0x3fb8aa3b, v219
	v_fmamk_f32 v170, v169, 0x3c088888, v195
	v_fmamk_f32 v208, v207, 0x3c088888, v195
	v_fmamk_f32 v214, v213, 0x3c088888, v195
	v_fmamk_f32 v220, v219, 0x3c088888, v195
	v_exp_f32_e32 v171, v171
	v_exp_f32_e32 v209, v209
	v_exp_f32_e32 v215, v215
	v_exp_f32_e32 v221, v221
	v_fmaak_f32 v170, v169, v170, 0x3e2aaaab
	v_fmaak_f32 v208, v207, v208, 0x3e2aaaab
	v_fmaak_f32 v214, v213, v214, 0x3e2aaaab
	v_fmaak_f32 v220, v219, v220, 0x3e2aaaab
	v_fma_f32 v170, v169, v170, 0.5
	v_fma_f32 v208, v207, v208, 0.5
	v_fma_f32 v214, v213, v214, 0.5
	v_fma_f32 v220, v219, v220, 0.5
	v_fma_f32 v170, v169, v170, 1.0
	v_fma_f32 v208, v207, v208, 1.0
	v_fma_f32 v214, v213, v214, 1.0
	v_fma_f32 v220, v219, v220, 1.0
	v_sub_f32_e32 v171, 1.0, v171
	v_sub_f32_e32 v209, 1.0, v209
	v_sub_f32_e32 v215, 1.0, v215
	v_sub_f32_e32 v221, 1.0, v221
	v_mul_f32_e64 v170, v170, -v169
	v_mul_f32_e64 v208, v208, -v207
	v_mul_f32_e64 v214, v214, -v213
	v_mul_f32_e64 v220, v220, -v219
	v_cmp_nlt_f32_e32 vcc, s1, v169
	v_cmp_nlt_f32_e64 s[62:63], s1, v207
	v_cmp_nlt_f32_e64 s[56:57], s1, v213
	v_mul_f32_e32 v167, v162, v167
	v_mul_f32_e32 v205, v163, v205
	v_mul_f32_e32 v211, v164, v211
	v_mul_f32_e32 v217, v165, v217
	v_cndmask_b32_e32 v170, v170, v171, vcc
	v_cmp_nlt_f32_e32 vcc, s1, v219
	v_cndmask_b32_e64 v208, v208, v209, s[62:63]
	v_cndmask_b32_e64 v214, v214, v215, s[56:57]
	v_mul_f32_e32 v166, 0x3fb8aa3b, v168
	v_mul_f32_e32 v204, 0x3fb8aa3b, v206
	v_mul_f32_e32 v210, 0x3fb8aa3b, v212
	v_mul_f32_e32 v216, 0x3fb8aa3b, v218
	v_cndmask_b32_e32 v220, v220, v221, vcc
	v_sqrt_f32_e32 v170, v170
	v_sqrt_f32_e32 v208, v208
	v_sqrt_f32_e32 v214, v214
	v_sqrt_f32_e32 v220, v220
	v_exp_f32_e32 v166, v166
	v_exp_f32_e32 v204, v204
	v_exp_f32_e32 v210, v210
	v_exp_f32_e32 v216, v216
	v_mul_f32_e32 v167, v167, v170
	v_mul_f32_e32 v205, v205, v208
	v_mul_f32_e32 v211, v211, v214
	v_mul_f32_e32 v217, v217, v220
	ds_read_b128 v[150:153], v230 offset:192
	ds_read_b128 v[154:157], v230 offset:576
	ds_read_b128 v[158:161], v230 offset:960
	ds_read_b128 v[162:165], v231 offset:192
	s_waitcnt lgkmcnt(0)
	v_mfma_f32_16x16x32_bf16 v[142:145], v[110:113], v[98:101], 0
	v_mfma_f32_16x16x32_bf16 v[146:149], v[122:125], v[98:101], 0
	v_mfma_f32_16x16x32_bf16 v[142:145], v[114:117], v[102:105], v[142:145]
	v_mfma_f32_16x16x32_bf16 v[146:149], v[126:129], v[102:105], v[146:149]
	v_mfma_f32_16x16x32_bf16 v[142:145], v[118:121], v[106:109], v[142:145]
	v_mfma_f32_16x16x32_bf16 v[146:149], v[130:133], v[106:109], v[146:149]
	v_fmac_f32_dpp v167, v167, v166 row_shr:1 row_mask:0xf bank_mask:0xf bound_ctrl:1
	v_fmac_f32_dpp v205, v205, v204 row_shr:1 row_mask:0xf bank_mask:0xf bound_ctrl:1
	v_fmac_f32_dpp v211, v211, v210 row_shr:1 row_mask:0xf bank_mask:0xf bound_ctrl:1
	v_fmac_f32_dpp v217, v217, v216 row_shr:1 row_mask:0xf bank_mask:0xf bound_ctrl:1
	v_mul_f32_dpp v166, v166, v166 row_shr:1 row_mask:0xf bank_mask:0xf
	v_mul_f32_dpp v204, v204, v204 row_shr:1 row_mask:0xf bank_mask:0xf
	v_mul_f32_dpp v210, v210, v210 row_shr:1 row_mask:0xf bank_mask:0xf
	v_mul_f32_dpp v216, v216, v216 row_shr:1 row_mask:0xf bank_mask:0xf
	v_fmac_f32_dpp v167, v167, v166 row_shr:2 row_mask:0xf bank_mask:0xf bound_ctrl:1
	v_fmac_f32_dpp v205, v205, v204 row_shr:2 row_mask:0xf bank_mask:0xf bound_ctrl:1
	v_fmac_f32_dpp v211, v211, v210 row_shr:2 row_mask:0xf bank_mask:0xf bound_ctrl:1
	v_fmac_f32_dpp v217, v217, v216 row_shr:2 row_mask:0xf bank_mask:0xf bound_ctrl:1
	v_mul_f32_dpp v166, v166, v166 row_shr:2 row_mask:0xf bank_mask:0xf
	v_mul_f32_dpp v204, v204, v204 row_shr:2 row_mask:0xf bank_mask:0xf
	v_mul_f32_dpp v210, v210, v210 row_shr:2 row_mask:0xf bank_mask:0xf
	v_mul_f32_dpp v216, v216, v216 row_shr:2 row_mask:0xf bank_mask:0xf
	v_fmac_f32_dpp v167, v167, v166 row_shr:4 row_mask:0xf bank_mask:0xf bound_ctrl:1
	v_fmac_f32_dpp v205, v205, v204 row_shr:4 row_mask:0xf bank_mask:0xf bound_ctrl:1
	v_fmac_f32_dpp v211, v211, v210 row_shr:4 row_mask:0xf bank_mask:0xf bound_ctrl:1
	v_fmac_f32_dpp v217, v217, v216 row_shr:4 row_mask:0xf bank_mask:0xf bound_ctrl:1
	v_mul_f32_dpp v166, v166, v166 row_shr:4 row_mask:0xf bank_mask:0xf
	v_mul_f32_dpp v204, v204, v204 row_shr:4 row_mask:0xf bank_mask:0xf
	v_mul_f32_dpp v210, v210, v210 row_shr:4 row_mask:0xf bank_mask:0xf
	v_mul_f32_dpp v216, v216, v216 row_shr:4 row_mask:0xf bank_mask:0xf
	v_fmac_f32_dpp v167, v167, v166 row_shr:8 row_mask:0xf bank_mask:0xf bound_ctrl:1
	v_fmac_f32_dpp v205, v205, v204 row_shr:8 row_mask:0xf bank_mask:0xf bound_ctrl:1
	v_fmac_f32_dpp v211, v211, v210 row_shr:8 row_mask:0xf bank_mask:0xf bound_ctrl:1
	v_fmac_f32_dpp v217, v217, v216 row_shr:8 row_mask:0xf bank_mask:0xf bound_ctrl:1
	v_mul_f32_dpp v166, v166, v166 row_shr:8 row_mask:0xf bank_mask:0xf
	v_mul_f32_dpp v204, v204, v204 row_shr:8 row_mask:0xf bank_mask:0xf
	v_mul_f32_dpp v210, v210, v210 row_shr:8 row_mask:0xf bank_mask:0xf
	v_mul_f32_dpp v216, v216, v216 row_shr:8 row_mask:0xf bank_mask:0xf
	v_fma_f32 v168, v166, v8, v167
	v_fma_f32 v206, v204, v9, v205
	v_fma_f32 v212, v210, v10, v211
	v_fma_f32 v218, v216, v11, v217
	ds_bpermute_b32 v8, v232, v168
	ds_bpermute_b32 v9, v232, v206
	ds_bpermute_b32 v10, v232, v212
	ds_bpermute_b32 v11, v232, v218
	s_waitcnt vmcnt(21)
	v_lshlrev_b32_e32 v169, 16, v28
	v_and_b32_e32 v207, 0xffff0000, v28
	v_lshlrev_b32_e32 v213, 16, v29
	v_and_b32_e32 v219, 0xffff0000, v29
	v_mul_f32_e32 v170, 0x3d372713, v169
	v_mul_f32_e32 v208, 0x3d372713, v207
	v_mul_f32_e32 v214, 0x3d372713, v213
	v_mul_f32_e32 v220, 0x3d372713, v219
	v_mul_f32_e32 v170, v169, v170
	v_mul_f32_e32 v208, v207, v208
	v_mul_f32_e32 v214, v213, v214
	v_mul_f32_e32 v220, v219, v220
	v_fma_f32 v170, v169, v170, v169
	v_fma_f32 v208, v207, v208, v207
	v_fma_f32 v214, v213, v214, v213
	v_fma_f32 v220, v219, v220, v219
	v_mul_f32_e32 v170, 0x3f4c422a, v170
	v_mul_f32_e32 v208, 0x3f4c422a, v208
	v_mul_f32_e32 v214, 0x3f4c422a, v214
	v_mul_f32_e32 v220, 0x3f4c422a, v220
	v_mul_f32_e32 v170, 0xc038aa3b, v170
	v_mul_f32_e32 v208, 0xc038aa3b, v208
	v_mul_f32_e32 v214, 0xc038aa3b, v214
	v_mul_f32_e32 v220, 0xc038aa3b, v220
	v_exp_f32_e32 v170, v170
	v_exp_f32_e32 v208, v208
	v_exp_f32_e32 v214, v214
	v_exp_f32_e32 v220, v220
	v_add_f32_e32 v170, 1.0, v170
	v_add_f32_e32 v208, 1.0, v208
	v_add_f32_e32 v214, 1.0, v214
	v_add_f32_e32 v220, 1.0, v220
	v_rcp_f32_e32 v170, v170
	v_rcp_f32_e32 v208, v208
	v_rcp_f32_e32 v214, v214
	v_rcp_f32_e32 v220, v220
	v_mul_f32_e32 v170, v169, v170
	v_mul_f32_e32 v208, v207, v208
	v_mul_f32_e32 v214, v213, v214
	v_mul_f32_e32 v220, v219, v220
	v_mul_f32_e32 v170, v170, v168
	v_mul_f32_e32 v208, v208, v206
	v_mul_f32_e32 v214, v214, v212
	v_mul_f32_e32 v220, v220, v218
	v_cvt_pk_bf16_f32 v242, v170, v208
	v_cvt_pk_bf16_f32 v243, v214, v220
	global_store_dwordx2 v236, v[242:243], s[100:101] offset:64
	ds_read_b128 v[110:113], v229 offset:13312
	ds_read_b128 v[122:125], v229 offset:33280
	ds_read_b128 v[114:117], v229 offset:13376
	ds_read_b128 v[126:129], v229 offset:33344
	ds_read_b128 v[118:121], v229 offset:13440
	ds_read_b128 v[130:133], v229 offset:33408
	v_add_f32_e32 v166, v142, v150
	v_add_f32_e32 v204, v143, v151
	v_add_f32_e32 v210, v144, v152
	v_add_f32_e32 v216, v145, v153
	v_add_f32_e32 v167, v146, v154
	v_add_f32_e32 v205, v147, v155
	v_add_f32_e32 v211, v148, v156
	v_add_f32_e32 v217, v149, v157
	v_mul_f32_e32 v166, 0xbfb8aa3b, v166
	v_mul_f32_e32 v204, 0xbfb8aa3b, v204
	v_mul_f32_e32 v210, 0xbfb8aa3b, v210
	v_mul_f32_e32 v216, 0xbfb8aa3b, v216
	v_mul_f32_e32 v167, 0xbfb8aa3b, v167
	v_mul_f32_e32 v205, 0xbfb8aa3b, v205
	v_mul_f32_e32 v211, 0xbfb8aa3b, v211
	v_mul_f32_e32 v217, 0xbfb8aa3b, v217
	v_exp_f32_e32 v166, v166
	v_exp_f32_e32 v204, v204
	v_exp_f32_e32 v210, v210
	v_exp_f32_e32 v216, v216
	v_exp_f32_e32 v167, v167
	v_exp_f32_e32 v205, v205
	v_exp_f32_e32 v211, v211
	v_exp_f32_e32 v217, v217
	v_add_f32_e32 v166, 1.0, v166
	v_add_f32_e32 v204, 1.0, v204
	v_add_f32_e32 v210, 1.0, v210
	v_add_f32_e32 v216, 1.0, v216
	v_add_f32_e32 v167, 1.0, v167
	v_add_f32_e32 v205, 1.0, v205
	v_add_f32_e32 v211, 1.0, v211
	v_add_f32_e32 v217, 1.0, v217
	v_rcp_f32_e32 v166, v166
	v_rcp_f32_e32 v204, v204
	v_rcp_f32_e32 v210, v210
	v_rcp_f32_e32 v216, v216
	v_rcp_f32_e32 v167, v167
	v_rcp_f32_e32 v205, v205
	v_rcp_f32_e32 v211, v211
	v_rcp_f32_e32 v217, v217
	v_mul_f32_e32 v168, 0xc1000000, v166
	v_mul_f32_e32 v206, 0xc1000000, v204
	v_mul_f32_e32 v212, 0xc1000000, v210
	v_mul_f32_e32 v218, 0xc1000000, v216
	v_mul_f32_e32 v168, v158, v168
	v_mul_f32_e32 v206, v159, v206
	v_mul_f32_e32 v212, v160, v212
	v_mul_f32_e32 v218, v161, v218
	v_add_f32_e32 v169, v168, v168
	v_add_f32_e32 v207, v206, v206
	v_add_f32_e32 v213, v212, v212
	v_add_f32_e32 v219, v218, v218
	v_mul_f32_e32 v171, 0x3fb8aa3b, v169
	v_mul_f32_e32 v209, 0x3fb8aa3b, v207
	v_mul_f32_e32 v215, 0x3fb8aa3b, v213
	v_mul_f32_e32 v221, 0x3fb8aa3b, v219
	v_fmamk_f32 v170, v169, 0x3c088888, v195
	v_fmamk_f32 v208, v207, 0x3c088888, v195
	v_fmamk_f32 v214, v213, 0x3c088888, v195
	v_fmamk_f32 v220, v219, 0x3c088888, v195
	v_exp_f32_e32 v171, v171
	v_exp_f32_e32 v209, v209
	v_exp_f32_e32 v215, v215
	v_exp_f32_e32 v221, v221
	v_fmaak_f32 v170, v169, v170, 0x3e2aaaab
	v_fmaak_f32 v208, v207, v208, 0x3e2aaaab
	v_fmaak_f32 v214, v213, v214, 0x3e2aaaab
	v_fmaak_f32 v220, v219, v220, 0x3e2aaaab
	v_fma_f32 v170, v169, v170, 0.5
	v_fma_f32 v208, v207, v208, 0.5
	v_fma_f32 v214, v213, v214, 0.5
	v_fma_f32 v220, v219, v220, 0.5
	v_fma_f32 v170, v169, v170, 1.0
	v_fma_f32 v208, v207, v208, 1.0
	v_fma_f32 v214, v213, v214, 1.0
	v_fma_f32 v220, v219, v220, 1.0
	v_sub_f32_e32 v171, 1.0, v171
	v_sub_f32_e32 v209, 1.0, v209
	v_sub_f32_e32 v215, 1.0, v215
	v_sub_f32_e32 v221, 1.0, v221
	v_mul_f32_e64 v170, v170, -v169
	v_mul_f32_e64 v208, v208, -v207
	v_mul_f32_e64 v214, v214, -v213
	v_mul_f32_e64 v220, v220, -v219
	v_cmp_nlt_f32_e32 vcc, s1, v169
	v_cmp_nlt_f32_e64 s[62:63], s1, v207
	v_cmp_nlt_f32_e64 s[56:57], s1, v213
	v_mul_f32_e32 v167, v162, v167
	v_mul_f32_e32 v205, v163, v205
	v_mul_f32_e32 v211, v164, v211
	v_mul_f32_e32 v217, v165, v217
	v_cndmask_b32_e32 v170, v170, v171, vcc
	v_cmp_nlt_f32_e32 vcc, s1, v219
	v_cndmask_b32_e64 v208, v208, v209, s[62:63]
	v_cndmask_b32_e64 v214, v214, v215, s[56:57]
	v_mul_f32_e32 v166, 0x3fb8aa3b, v168
	v_mul_f32_e32 v204, 0x3fb8aa3b, v206
	v_mul_f32_e32 v210, 0x3fb8aa3b, v212
	v_mul_f32_e32 v216, 0x3fb8aa3b, v218
	v_cndmask_b32_e32 v220, v220, v221, vcc
	v_sqrt_f32_e32 v170, v170
	v_sqrt_f32_e32 v208, v208
	v_sqrt_f32_e32 v214, v214
	v_sqrt_f32_e32 v220, v220
	v_exp_f32_e32 v166, v166
	v_exp_f32_e32 v204, v204
	v_exp_f32_e32 v210, v210
	v_exp_f32_e32 v216, v216
	v_mul_f32_e32 v167, v167, v170
	v_mul_f32_e32 v205, v205, v208
	v_mul_f32_e32 v211, v211, v214
	v_mul_f32_e32 v217, v217, v220
	ds_read_b128 v[150:153], v230 offset:256
	ds_read_b128 v[154:157], v230 offset:640
	ds_read_b128 v[158:161], v230 offset:1024
	ds_read_b128 v[162:165], v231 offset:256
	s_waitcnt lgkmcnt(0)
	v_mfma_f32_16x16x32_bf16 v[134:137], v[110:113], v[98:101], 0
	v_mfma_f32_16x16x32_bf16 v[138:141], v[122:125], v[98:101], 0
	v_mfma_f32_16x16x32_bf16 v[134:137], v[114:117], v[102:105], v[134:137]
	v_mfma_f32_16x16x32_bf16 v[138:141], v[126:129], v[102:105], v[138:141]
	v_mfma_f32_16x16x32_bf16 v[134:137], v[118:121], v[106:109], v[134:137]
	v_mfma_f32_16x16x32_bf16 v[138:141], v[130:133], v[106:109], v[138:141]
	v_fmac_f32_dpp v167, v167, v166 row_shr:1 row_mask:0xf bank_mask:0xf bound_ctrl:1
	v_fmac_f32_dpp v205, v205, v204 row_shr:1 row_mask:0xf bank_mask:0xf bound_ctrl:1
	v_fmac_f32_dpp v211, v211, v210 row_shr:1 row_mask:0xf bank_mask:0xf bound_ctrl:1
	v_fmac_f32_dpp v217, v217, v216 row_shr:1 row_mask:0xf bank_mask:0xf bound_ctrl:1
	v_mul_f32_dpp v166, v166, v166 row_shr:1 row_mask:0xf bank_mask:0xf
	v_mul_f32_dpp v204, v204, v204 row_shr:1 row_mask:0xf bank_mask:0xf
	v_mul_f32_dpp v210, v210, v210 row_shr:1 row_mask:0xf bank_mask:0xf
	v_mul_f32_dpp v216, v216, v216 row_shr:1 row_mask:0xf bank_mask:0xf
	v_fmac_f32_dpp v167, v167, v166 row_shr:2 row_mask:0xf bank_mask:0xf bound_ctrl:1
	v_fmac_f32_dpp v205, v205, v204 row_shr:2 row_mask:0xf bank_mask:0xf bound_ctrl:1
	v_fmac_f32_dpp v211, v211, v210 row_shr:2 row_mask:0xf bank_mask:0xf bound_ctrl:1
	v_fmac_f32_dpp v217, v217, v216 row_shr:2 row_mask:0xf bank_mask:0xf bound_ctrl:1
	v_mul_f32_dpp v166, v166, v166 row_shr:2 row_mask:0xf bank_mask:0xf
	v_mul_f32_dpp v204, v204, v204 row_shr:2 row_mask:0xf bank_mask:0xf
	v_mul_f32_dpp v210, v210, v210 row_shr:2 row_mask:0xf bank_mask:0xf
	v_mul_f32_dpp v216, v216, v216 row_shr:2 row_mask:0xf bank_mask:0xf
	v_fmac_f32_dpp v167, v167, v166 row_shr:4 row_mask:0xf bank_mask:0xf bound_ctrl:1
	v_fmac_f32_dpp v205, v205, v204 row_shr:4 row_mask:0xf bank_mask:0xf bound_ctrl:1
	v_fmac_f32_dpp v211, v211, v210 row_shr:4 row_mask:0xf bank_mask:0xf bound_ctrl:1
	v_fmac_f32_dpp v217, v217, v216 row_shr:4 row_mask:0xf bank_mask:0xf bound_ctrl:1
	v_mul_f32_dpp v166, v166, v166 row_shr:4 row_mask:0xf bank_mask:0xf
	v_mul_f32_dpp v204, v204, v204 row_shr:4 row_mask:0xf bank_mask:0xf
	v_mul_f32_dpp v210, v210, v210 row_shr:4 row_mask:0xf bank_mask:0xf
	v_mul_f32_dpp v216, v216, v216 row_shr:4 row_mask:0xf bank_mask:0xf
	v_fmac_f32_dpp v167, v167, v166 row_shr:8 row_mask:0xf bank_mask:0xf bound_ctrl:1
	v_fmac_f32_dpp v205, v205, v204 row_shr:8 row_mask:0xf bank_mask:0xf bound_ctrl:1
	v_fmac_f32_dpp v211, v211, v210 row_shr:8 row_mask:0xf bank_mask:0xf bound_ctrl:1
	v_fmac_f32_dpp v217, v217, v216 row_shr:8 row_mask:0xf bank_mask:0xf bound_ctrl:1
	v_mul_f32_dpp v166, v166, v166 row_shr:8 row_mask:0xf bank_mask:0xf
	v_mul_f32_dpp v204, v204, v204 row_shr:8 row_mask:0xf bank_mask:0xf
	v_mul_f32_dpp v210, v210, v210 row_shr:8 row_mask:0xf bank_mask:0xf
	v_mul_f32_dpp v216, v216, v216 row_shr:8 row_mask:0xf bank_mask:0xf
	v_fma_f32 v168, v166, v12, v167
	v_fma_f32 v206, v204, v13, v205
	v_fma_f32 v212, v210, v14, v211
	v_fma_f32 v218, v216, v15, v217
	ds_bpermute_b32 v12, v232, v168
	ds_bpermute_b32 v13, v232, v206
	ds_bpermute_b32 v14, v232, v212
	ds_bpermute_b32 v15, v232, v218
	s_waitcnt vmcnt(21)
	v_lshlrev_b32_e32 v169, 16, v30
	v_and_b32_e32 v207, 0xffff0000, v30
	v_lshlrev_b32_e32 v213, 16, v31
	v_and_b32_e32 v219, 0xffff0000, v31
	v_mul_f32_e32 v170, 0x3d372713, v169
	v_mul_f32_e32 v208, 0x3d372713, v207
	v_mul_f32_e32 v214, 0x3d372713, v213
	v_mul_f32_e32 v220, 0x3d372713, v219
	v_mul_f32_e32 v170, v169, v170
	v_mul_f32_e32 v208, v207, v208
	v_mul_f32_e32 v214, v213, v214
	v_mul_f32_e32 v220, v219, v220
	v_fma_f32 v170, v169, v170, v169
	v_fma_f32 v208, v207, v208, v207
	v_fma_f32 v214, v213, v214, v213
	v_fma_f32 v220, v219, v220, v219
	v_mul_f32_e32 v170, 0x3f4c422a, v170
	v_mul_f32_e32 v208, 0x3f4c422a, v208
	v_mul_f32_e32 v214, 0x3f4c422a, v214
	v_mul_f32_e32 v220, 0x3f4c422a, v220
	v_mul_f32_e32 v170, 0xc038aa3b, v170
	v_mul_f32_e32 v208, 0xc038aa3b, v208
	v_mul_f32_e32 v214, 0xc038aa3b, v214
	v_mul_f32_e32 v220, 0xc038aa3b, v220
	v_exp_f32_e32 v170, v170
	v_exp_f32_e32 v208, v208
	v_exp_f32_e32 v214, v214
	v_exp_f32_e32 v220, v220
	v_add_f32_e32 v170, 1.0, v170
	v_add_f32_e32 v208, 1.0, v208
	v_add_f32_e32 v214, 1.0, v214
	v_add_f32_e32 v220, 1.0, v220
	v_rcp_f32_e32 v170, v170
	v_rcp_f32_e32 v208, v208
	v_rcp_f32_e32 v214, v214
	v_rcp_f32_e32 v220, v220
	v_mul_f32_e32 v170, v169, v170
	v_mul_f32_e32 v208, v207, v208
	v_mul_f32_e32 v214, v213, v214
	v_mul_f32_e32 v220, v219, v220
	v_mul_f32_e32 v170, v170, v168
	v_mul_f32_e32 v208, v208, v206
	v_mul_f32_e32 v214, v214, v212
	v_mul_f32_e32 v220, v220, v218
	v_cvt_pk_bf16_f32 v242, v170, v208
	v_cvt_pk_bf16_f32 v243, v214, v220
	global_store_dwordx2 v236, v[242:243], s[100:101] offset:96
	ds_read_b128 v[110:113], v229 offset:16640
	ds_read_b128 v[122:125], v229 offset:36608
	ds_read_b128 v[114:117], v229 offset:16704
	ds_read_b128 v[126:129], v229 offset:36672
	ds_read_b128 v[118:121], v229 offset:16768
	ds_read_b128 v[130:133], v229 offset:36736
	v_add_f32_e32 v166, v134, v150
	v_add_f32_e32 v204, v135, v151
	v_add_f32_e32 v210, v136, v152
	v_add_f32_e32 v216, v137, v153
	v_add_f32_e32 v167, v138, v154
	v_add_f32_e32 v205, v139, v155
	v_add_f32_e32 v211, v140, v156
	v_add_f32_e32 v217, v141, v157
	v_mul_f32_e32 v166, 0xbfb8aa3b, v166
	v_mul_f32_e32 v204, 0xbfb8aa3b, v204
	v_mul_f32_e32 v210, 0xbfb8aa3b, v210
	v_mul_f32_e32 v216, 0xbfb8aa3b, v216
	v_mul_f32_e32 v167, 0xbfb8aa3b, v167
	v_mul_f32_e32 v205, 0xbfb8aa3b, v205
	v_mul_f32_e32 v211, 0xbfb8aa3b, v211
	v_mul_f32_e32 v217, 0xbfb8aa3b, v217
	v_exp_f32_e32 v166, v166
	v_exp_f32_e32 v204, v204
	v_exp_f32_e32 v210, v210
	v_exp_f32_e32 v216, v216
	v_exp_f32_e32 v167, v167
	v_exp_f32_e32 v205, v205
	v_exp_f32_e32 v211, v211
	v_exp_f32_e32 v217, v217
	v_add_f32_e32 v166, 1.0, v166
	v_add_f32_e32 v204, 1.0, v204
	v_add_f32_e32 v210, 1.0, v210
	v_add_f32_e32 v216, 1.0, v216
	v_add_f32_e32 v167, 1.0, v167
	v_add_f32_e32 v205, 1.0, v205
	v_add_f32_e32 v211, 1.0, v211
	v_add_f32_e32 v217, 1.0, v217
	v_rcp_f32_e32 v166, v166
	v_rcp_f32_e32 v204, v204
	v_rcp_f32_e32 v210, v210
	v_rcp_f32_e32 v216, v216
	v_rcp_f32_e32 v167, v167
	v_rcp_f32_e32 v205, v205
	v_rcp_f32_e32 v211, v211
	v_rcp_f32_e32 v217, v217
	v_mul_f32_e32 v168, 0xc1000000, v166
	v_mul_f32_e32 v206, 0xc1000000, v204
	v_mul_f32_e32 v212, 0xc1000000, v210
	v_mul_f32_e32 v218, 0xc1000000, v216
	v_mul_f32_e32 v168, v158, v168
	v_mul_f32_e32 v206, v159, v206
	v_mul_f32_e32 v212, v160, v212
	v_mul_f32_e32 v218, v161, v218
	v_add_f32_e32 v169, v168, v168
	v_add_f32_e32 v207, v206, v206
	v_add_f32_e32 v213, v212, v212
	v_add_f32_e32 v219, v218, v218
	v_mul_f32_e32 v171, 0x3fb8aa3b, v169
	v_mul_f32_e32 v209, 0x3fb8aa3b, v207
	v_mul_f32_e32 v215, 0x3fb8aa3b, v213
	v_mul_f32_e32 v221, 0x3fb8aa3b, v219
	v_fmamk_f32 v170, v169, 0x3c088888, v195
	v_fmamk_f32 v208, v207, 0x3c088888, v195
	v_fmamk_f32 v214, v213, 0x3c088888, v195
	v_fmamk_f32 v220, v219, 0x3c088888, v195
	v_exp_f32_e32 v171, v171
	v_exp_f32_e32 v209, v209
	v_exp_f32_e32 v215, v215
	v_exp_f32_e32 v221, v221
	v_fmaak_f32 v170, v169, v170, 0x3e2aaaab
	v_fmaak_f32 v208, v207, v208, 0x3e2aaaab
	v_fmaak_f32 v214, v213, v214, 0x3e2aaaab
	v_fmaak_f32 v220, v219, v220, 0x3e2aaaab
	v_fma_f32 v170, v169, v170, 0.5
	v_fma_f32 v208, v207, v208, 0.5
	v_fma_f32 v214, v213, v214, 0.5
	v_fma_f32 v220, v219, v220, 0.5
	v_fma_f32 v170, v169, v170, 1.0
	v_fma_f32 v208, v207, v208, 1.0
	v_fma_f32 v214, v213, v214, 1.0
	v_fma_f32 v220, v219, v220, 1.0
	v_sub_f32_e32 v171, 1.0, v171
	v_sub_f32_e32 v209, 1.0, v209
	v_sub_f32_e32 v215, 1.0, v215
	v_sub_f32_e32 v221, 1.0, v221
	v_mul_f32_e64 v170, v170, -v169
	v_mul_f32_e64 v208, v208, -v207
	v_mul_f32_e64 v214, v214, -v213
	v_mul_f32_e64 v220, v220, -v219
	v_cmp_nlt_f32_e32 vcc, s1, v169
	v_cmp_nlt_f32_e64 s[62:63], s1, v207
	v_cmp_nlt_f32_e64 s[56:57], s1, v213
	v_mul_f32_e32 v167, v162, v167
	v_mul_f32_e32 v205, v163, v205
	v_mul_f32_e32 v211, v164, v211
	v_mul_f32_e32 v217, v165, v217
	v_cndmask_b32_e32 v170, v170, v171, vcc
	v_cmp_nlt_f32_e32 vcc, s1, v219
	v_cndmask_b32_e64 v208, v208, v209, s[62:63]
	v_cndmask_b32_e64 v214, v214, v215, s[56:57]
	v_mul_f32_e32 v166, 0x3fb8aa3b, v168
	v_mul_f32_e32 v204, 0x3fb8aa3b, v206
	v_mul_f32_e32 v210, 0x3fb8aa3b, v212
	v_mul_f32_e32 v216, 0x3fb8aa3b, v218
	v_cndmask_b32_e32 v220, v220, v221, vcc
	v_sqrt_f32_e32 v170, v170
	v_sqrt_f32_e32 v208, v208
	v_sqrt_f32_e32 v214, v214
	v_sqrt_f32_e32 v220, v220
	v_exp_f32_e32 v166, v166
	v_exp_f32_e32 v204, v204
	v_exp_f32_e32 v210, v210
	v_exp_f32_e32 v216, v216
	v_mul_f32_e32 v167, v167, v170
	v_mul_f32_e32 v205, v205, v208
	v_mul_f32_e32 v211, v211, v214
	v_mul_f32_e32 v217, v217, v220
	ds_read_b128 v[150:153], v230 offset:320
	ds_read_b128 v[154:157], v230 offset:704
	ds_read_b128 v[158:161], v230 offset:1088
	ds_read_b128 v[162:165], v231 offset:320
	s_waitcnt lgkmcnt(0)
	v_mfma_f32_16x16x32_bf16 v[142:145], v[110:113], v[98:101], 0
	v_mfma_f32_16x16x32_bf16 v[146:149], v[122:125], v[98:101], 0
	v_mfma_f32_16x16x32_bf16 v[142:145], v[114:117], v[102:105], v[142:145]
	v_mfma_f32_16x16x32_bf16 v[146:149], v[126:129], v[102:105], v[146:149]
	v_mfma_f32_16x16x32_bf16 v[142:145], v[118:121], v[106:109], v[142:145]
	v_mfma_f32_16x16x32_bf16 v[146:149], v[130:133], v[106:109], v[146:149]
	v_fmac_f32_dpp v167, v167, v166 row_shr:1 row_mask:0xf bank_mask:0xf bound_ctrl:1
	v_fmac_f32_dpp v205, v205, v204 row_shr:1 row_mask:0xf bank_mask:0xf bound_ctrl:1
	v_fmac_f32_dpp v211, v211, v210 row_shr:1 row_mask:0xf bank_mask:0xf bound_ctrl:1
	v_fmac_f32_dpp v217, v217, v216 row_shr:1 row_mask:0xf bank_mask:0xf bound_ctrl:1
	v_mul_f32_dpp v166, v166, v166 row_shr:1 row_mask:0xf bank_mask:0xf
	v_mul_f32_dpp v204, v204, v204 row_shr:1 row_mask:0xf bank_mask:0xf
	v_mul_f32_dpp v210, v210, v210 row_shr:1 row_mask:0xf bank_mask:0xf
	v_mul_f32_dpp v216, v216, v216 row_shr:1 row_mask:0xf bank_mask:0xf
	v_fmac_f32_dpp v167, v167, v166 row_shr:2 row_mask:0xf bank_mask:0xf bound_ctrl:1
	v_fmac_f32_dpp v205, v205, v204 row_shr:2 row_mask:0xf bank_mask:0xf bound_ctrl:1
	v_fmac_f32_dpp v211, v211, v210 row_shr:2 row_mask:0xf bank_mask:0xf bound_ctrl:1
	v_fmac_f32_dpp v217, v217, v216 row_shr:2 row_mask:0xf bank_mask:0xf bound_ctrl:1
	v_mul_f32_dpp v166, v166, v166 row_shr:2 row_mask:0xf bank_mask:0xf
	v_mul_f32_dpp v204, v204, v204 row_shr:2 row_mask:0xf bank_mask:0xf
	v_mul_f32_dpp v210, v210, v210 row_shr:2 row_mask:0xf bank_mask:0xf
	v_mul_f32_dpp v216, v216, v216 row_shr:2 row_mask:0xf bank_mask:0xf
	v_fmac_f32_dpp v167, v167, v166 row_shr:4 row_mask:0xf bank_mask:0xf bound_ctrl:1
	v_fmac_f32_dpp v205, v205, v204 row_shr:4 row_mask:0xf bank_mask:0xf bound_ctrl:1
	v_fmac_f32_dpp v211, v211, v210 row_shr:4 row_mask:0xf bank_mask:0xf bound_ctrl:1
	v_fmac_f32_dpp v217, v217, v216 row_shr:4 row_mask:0xf bank_mask:0xf bound_ctrl:1
	v_mul_f32_dpp v166, v166, v166 row_shr:4 row_mask:0xf bank_mask:0xf
	v_mul_f32_dpp v204, v204, v204 row_shr:4 row_mask:0xf bank_mask:0xf
	v_mul_f32_dpp v210, v210, v210 row_shr:4 row_mask:0xf bank_mask:0xf
	v_mul_f32_dpp v216, v216, v216 row_shr:4 row_mask:0xf bank_mask:0xf
	v_fmac_f32_dpp v167, v167, v166 row_shr:8 row_mask:0xf bank_mask:0xf bound_ctrl:1
	v_fmac_f32_dpp v205, v205, v204 row_shr:8 row_mask:0xf bank_mask:0xf bound_ctrl:1
	v_fmac_f32_dpp v211, v211, v210 row_shr:8 row_mask:0xf bank_mask:0xf bound_ctrl:1
	v_fmac_f32_dpp v217, v217, v216 row_shr:8 row_mask:0xf bank_mask:0xf bound_ctrl:1
	v_mul_f32_dpp v166, v166, v166 row_shr:8 row_mask:0xf bank_mask:0xf
	v_mul_f32_dpp v204, v204, v204 row_shr:8 row_mask:0xf bank_mask:0xf
	v_mul_f32_dpp v210, v210, v210 row_shr:8 row_mask:0xf bank_mask:0xf
	v_mul_f32_dpp v216, v216, v216 row_shr:8 row_mask:0xf bank_mask:0xf
	v_fma_f32 v168, v166, v16, v167
	v_fma_f32 v206, v204, v17, v205
	v_fma_f32 v212, v210, v18, v211
	v_fma_f32 v218, v216, v19, v217
	ds_bpermute_b32 v16, v232, v168
	ds_bpermute_b32 v17, v232, v206
	ds_bpermute_b32 v18, v232, v212
	ds_bpermute_b32 v19, v232, v218
	s_waitcnt vmcnt(21)
	v_lshlrev_b32_e32 v169, 16, v32
	v_and_b32_e32 v207, 0xffff0000, v32
	v_lshlrev_b32_e32 v213, 16, v33
	v_and_b32_e32 v219, 0xffff0000, v33
	v_mul_f32_e32 v170, 0x3d372713, v169
	v_mul_f32_e32 v208, 0x3d372713, v207
	v_mul_f32_e32 v214, 0x3d372713, v213
	v_mul_f32_e32 v220, 0x3d372713, v219
	v_mul_f32_e32 v170, v169, v170
	v_mul_f32_e32 v208, v207, v208
	v_mul_f32_e32 v214, v213, v214
	v_mul_f32_e32 v220, v219, v220
	v_fma_f32 v170, v169, v170, v169
	v_fma_f32 v208, v207, v208, v207
	v_fma_f32 v214, v213, v214, v213
	v_fma_f32 v220, v219, v220, v219
	v_mul_f32_e32 v170, 0x3f4c422a, v170
	v_mul_f32_e32 v208, 0x3f4c422a, v208
	v_mul_f32_e32 v214, 0x3f4c422a, v214
	v_mul_f32_e32 v220, 0x3f4c422a, v220
	v_mul_f32_e32 v170, 0xc038aa3b, v170
	v_mul_f32_e32 v208, 0xc038aa3b, v208
	v_mul_f32_e32 v214, 0xc038aa3b, v214
	v_mul_f32_e32 v220, 0xc038aa3b, v220
	v_exp_f32_e32 v170, v170
	v_exp_f32_e32 v208, v208
	v_exp_f32_e32 v214, v214
	v_exp_f32_e32 v220, v220
	v_add_f32_e32 v170, 1.0, v170
	v_add_f32_e32 v208, 1.0, v208
	v_add_f32_e32 v214, 1.0, v214
	v_add_f32_e32 v220, 1.0, v220
	v_rcp_f32_e32 v170, v170
	v_rcp_f32_e32 v208, v208
	v_rcp_f32_e32 v214, v214
	v_rcp_f32_e32 v220, v220
	v_mul_f32_e32 v170, v169, v170
	v_mul_f32_e32 v208, v207, v208
	v_mul_f32_e32 v214, v213, v214
	v_mul_f32_e32 v220, v219, v220
	v_mul_f32_e32 v170, v170, v168
	v_mul_f32_e32 v208, v208, v206
	v_mul_f32_e32 v214, v214, v212
	v_mul_f32_e32 v220, v220, v218
	v_cvt_pk_bf16_f32 v242, v170, v208
	v_cvt_pk_bf16_f32 v243, v214, v220
	global_store_dwordx2 v236, v[242:243], s[100:101] offset:128
	v_add_f32_e32 v166, v142, v150
	v_add_f32_e32 v204, v143, v151
	v_add_f32_e32 v210, v144, v152
	v_add_f32_e32 v216, v145, v153
	v_add_f32_e32 v167, v146, v154
	v_add_f32_e32 v205, v147, v155
	v_add_f32_e32 v211, v148, v156
	v_add_f32_e32 v217, v149, v157
	v_mul_f32_e32 v166, 0xbfb8aa3b, v166
	v_mul_f32_e32 v204, 0xbfb8aa3b, v204
	v_mul_f32_e32 v210, 0xbfb8aa3b, v210
	v_mul_f32_e32 v216, 0xbfb8aa3b, v216
	v_mul_f32_e32 v167, 0xbfb8aa3b, v167
	v_mul_f32_e32 v205, 0xbfb8aa3b, v205
	v_mul_f32_e32 v211, 0xbfb8aa3b, v211
	v_mul_f32_e32 v217, 0xbfb8aa3b, v217
	v_exp_f32_e32 v166, v166
	v_exp_f32_e32 v204, v204
	v_exp_f32_e32 v210, v210
	v_exp_f32_e32 v216, v216
	v_exp_f32_e32 v167, v167
	v_exp_f32_e32 v205, v205
	v_exp_f32_e32 v211, v211
	v_exp_f32_e32 v217, v217
	v_add_f32_e32 v166, 1.0, v166
	v_add_f32_e32 v204, 1.0, v204
	v_add_f32_e32 v210, 1.0, v210
	v_add_f32_e32 v216, 1.0, v216
	v_add_f32_e32 v167, 1.0, v167
	v_add_f32_e32 v205, 1.0, v205
	v_add_f32_e32 v211, 1.0, v211
	v_add_f32_e32 v217, 1.0, v217
	v_rcp_f32_e32 v166, v166
	v_rcp_f32_e32 v204, v204
	v_rcp_f32_e32 v210, v210
	v_rcp_f32_e32 v216, v216
	v_rcp_f32_e32 v167, v167
	v_rcp_f32_e32 v205, v205
	v_rcp_f32_e32 v211, v211
	v_rcp_f32_e32 v217, v217
	v_mul_f32_e32 v168, 0xc1000000, v166
	v_mul_f32_e32 v206, 0xc1000000, v204
	v_mul_f32_e32 v212, 0xc1000000, v210
	v_mul_f32_e32 v218, 0xc1000000, v216
	v_mul_f32_e32 v168, v158, v168
	v_mul_f32_e32 v206, v159, v206
	v_mul_f32_e32 v212, v160, v212
	v_mul_f32_e32 v218, v161, v218
	v_add_f32_e32 v169, v168, v168
	v_add_f32_e32 v207, v206, v206
	v_add_f32_e32 v213, v212, v212
	v_add_f32_e32 v219, v218, v218
	v_mul_f32_e32 v171, 0x3fb8aa3b, v169
	v_mul_f32_e32 v209, 0x3fb8aa3b, v207
	v_mul_f32_e32 v215, 0x3fb8aa3b, v213
	v_mul_f32_e32 v221, 0x3fb8aa3b, v219
	v_fmamk_f32 v170, v169, 0x3c088888, v195
	v_fmamk_f32 v208, v207, 0x3c088888, v195
	v_fmamk_f32 v214, v213, 0x3c088888, v195
	v_fmamk_f32 v220, v219, 0x3c088888, v195
	v_exp_f32_e32 v171, v171
	v_exp_f32_e32 v209, v209
	v_exp_f32_e32 v215, v215
	v_exp_f32_e32 v221, v221
	v_fmaak_f32 v170, v169, v170, 0x3e2aaaab
	v_fmaak_f32 v208, v207, v208, 0x3e2aaaab
	v_fmaak_f32 v214, v213, v214, 0x3e2aaaab
	v_fmaak_f32 v220, v219, v220, 0x3e2aaaab
	v_fma_f32 v170, v169, v170, 0.5
	v_fma_f32 v208, v207, v208, 0.5
	v_fma_f32 v214, v213, v214, 0.5
	v_fma_f32 v220, v219, v220, 0.5
	v_fma_f32 v170, v169, v170, 1.0
	v_fma_f32 v208, v207, v208, 1.0
	v_fma_f32 v214, v213, v214, 1.0
	v_fma_f32 v220, v219, v220, 1.0
	v_sub_f32_e32 v171, 1.0, v171
	v_sub_f32_e32 v209, 1.0, v209
	v_sub_f32_e32 v215, 1.0, v215
	v_sub_f32_e32 v221, 1.0, v221
	v_mul_f32_e64 v170, v170, -v169
	v_mul_f32_e64 v208, v208, -v207
	v_mul_f32_e64 v214, v214, -v213
	v_mul_f32_e64 v220, v220, -v219
	v_cmp_nlt_f32_e32 vcc, s1, v169
	v_cmp_nlt_f32_e64 s[62:63], s1, v207
	v_cmp_nlt_f32_e64 s[56:57], s1, v213
	v_mul_f32_e32 v167, v162, v167
	v_mul_f32_e32 v205, v163, v205
	v_mul_f32_e32 v211, v164, v211
	v_mul_f32_e32 v217, v165, v217
	v_cndmask_b32_e32 v170, v170, v171, vcc
	v_cmp_nlt_f32_e32 vcc, s1, v219
	v_cndmask_b32_e64 v208, v208, v209, s[62:63]
	v_cndmask_b32_e64 v214, v214, v215, s[56:57]
	v_mul_f32_e32 v166, 0x3fb8aa3b, v168
	v_mul_f32_e32 v204, 0x3fb8aa3b, v206
	v_mul_f32_e32 v210, 0x3fb8aa3b, v212
	v_mul_f32_e32 v216, 0x3fb8aa3b, v218
	v_cndmask_b32_e32 v220, v220, v221, vcc
	v_sqrt_f32_e32 v170, v170
	v_sqrt_f32_e32 v208, v208
	v_sqrt_f32_e32 v214, v214
	v_sqrt_f32_e32 v220, v220
	v_exp_f32_e32 v166, v166
	v_exp_f32_e32 v204, v204
	v_exp_f32_e32 v210, v210
	v_exp_f32_e32 v216, v216
	v_mul_f32_e32 v167, v167, v170
	v_mul_f32_e32 v205, v205, v208
	v_mul_f32_e32 v211, v211, v214
	v_mul_f32_e32 v217, v217, v220
	s_waitcnt lgkmcnt(0)
	v_fmac_f32_dpp v167, v167, v166 row_shr:1 row_mask:0xf bank_mask:0xf bound_ctrl:1
	v_fmac_f32_dpp v205, v205, v204 row_shr:1 row_mask:0xf bank_mask:0xf bound_ctrl:1
	v_fmac_f32_dpp v211, v211, v210 row_shr:1 row_mask:0xf bank_mask:0xf bound_ctrl:1
	v_fmac_f32_dpp v217, v217, v216 row_shr:1 row_mask:0xf bank_mask:0xf bound_ctrl:1
	v_mul_f32_dpp v166, v166, v166 row_shr:1 row_mask:0xf bank_mask:0xf
	v_mul_f32_dpp v204, v204, v204 row_shr:1 row_mask:0xf bank_mask:0xf
	v_mul_f32_dpp v210, v210, v210 row_shr:1 row_mask:0xf bank_mask:0xf
	v_mul_f32_dpp v216, v216, v216 row_shr:1 row_mask:0xf bank_mask:0xf
	v_fmac_f32_dpp v167, v167, v166 row_shr:2 row_mask:0xf bank_mask:0xf bound_ctrl:1
	v_fmac_f32_dpp v205, v205, v204 row_shr:2 row_mask:0xf bank_mask:0xf bound_ctrl:1
	v_fmac_f32_dpp v211, v211, v210 row_shr:2 row_mask:0xf bank_mask:0xf bound_ctrl:1
	v_fmac_f32_dpp v217, v217, v216 row_shr:2 row_mask:0xf bank_mask:0xf bound_ctrl:1
	v_mul_f32_dpp v166, v166, v166 row_shr:2 row_mask:0xf bank_mask:0xf
	v_mul_f32_dpp v204, v204, v204 row_shr:2 row_mask:0xf bank_mask:0xf
	v_mul_f32_dpp v210, v210, v210 row_shr:2 row_mask:0xf bank_mask:0xf
	v_mul_f32_dpp v216, v216, v216 row_shr:2 row_mask:0xf bank_mask:0xf
	v_fmac_f32_dpp v167, v167, v166 row_shr:4 row_mask:0xf bank_mask:0xf bound_ctrl:1
	v_fmac_f32_dpp v205, v205, v204 row_shr:4 row_mask:0xf bank_mask:0xf bound_ctrl:1
	v_fmac_f32_dpp v211, v211, v210 row_shr:4 row_mask:0xf bank_mask:0xf bound_ctrl:1
	v_fmac_f32_dpp v217, v217, v216 row_shr:4 row_mask:0xf bank_mask:0xf bound_ctrl:1
	v_mul_f32_dpp v166, v166, v166 row_shr:4 row_mask:0xf bank_mask:0xf
	v_mul_f32_dpp v204, v204, v204 row_shr:4 row_mask:0xf bank_mask:0xf
	v_mul_f32_dpp v210, v210, v210 row_shr:4 row_mask:0xf bank_mask:0xf
	v_mul_f32_dpp v216, v216, v216 row_shr:4 row_mask:0xf bank_mask:0xf
	v_fmac_f32_dpp v167, v167, v166 row_shr:8 row_mask:0xf bank_mask:0xf bound_ctrl:1
	v_fmac_f32_dpp v205, v205, v204 row_shr:8 row_mask:0xf bank_mask:0xf bound_ctrl:1
	v_fmac_f32_dpp v211, v211, v210 row_shr:8 row_mask:0xf bank_mask:0xf bound_ctrl:1
	v_fmac_f32_dpp v217, v217, v216 row_shr:8 row_mask:0xf bank_mask:0xf bound_ctrl:1
	v_mul_f32_dpp v166, v166, v166 row_shr:8 row_mask:0xf bank_mask:0xf
	v_mul_f32_dpp v204, v204, v204 row_shr:8 row_mask:0xf bank_mask:0xf
	v_mul_f32_dpp v210, v210, v210 row_shr:8 row_mask:0xf bank_mask:0xf
	v_mul_f32_dpp v216, v216, v216 row_shr:8 row_mask:0xf bank_mask:0xf
	v_fma_f32 v168, v166, v20, v167
	v_fma_f32 v206, v204, v21, v205
	v_fma_f32 v212, v210, v22, v211
	v_fma_f32 v218, v216, v23, v217
	ds_bpermute_b32 v20, v232, v168
	ds_bpermute_b32 v21, v232, v206
	ds_bpermute_b32 v22, v232, v212
	ds_bpermute_b32 v23, v232, v218
	s_waitcnt vmcnt(21)
	v_lshlrev_b32_e32 v169, 16, v34
	v_and_b32_e32 v207, 0xffff0000, v34
	v_lshlrev_b32_e32 v213, 16, v35
	v_and_b32_e32 v219, 0xffff0000, v35
	v_mul_f32_e32 v170, 0x3d372713, v169
	v_mul_f32_e32 v208, 0x3d372713, v207
	v_mul_f32_e32 v214, 0x3d372713, v213
	v_mul_f32_e32 v220, 0x3d372713, v219
	v_mul_f32_e32 v170, v169, v170
	v_mul_f32_e32 v208, v207, v208
	v_mul_f32_e32 v214, v213, v214
	v_mul_f32_e32 v220, v219, v220
	v_fma_f32 v170, v169, v170, v169
	v_fma_f32 v208, v207, v208, v207
	v_fma_f32 v214, v213, v214, v213
	v_fma_f32 v220, v219, v220, v219
	v_mul_f32_e32 v170, 0x3f4c422a, v170
	v_mul_f32_e32 v208, 0x3f4c422a, v208
	v_mul_f32_e32 v214, 0x3f4c422a, v214
	v_mul_f32_e32 v220, 0x3f4c422a, v220
	v_mul_f32_e32 v170, 0xc038aa3b, v170
	v_mul_f32_e32 v208, 0xc038aa3b, v208
	v_mul_f32_e32 v214, 0xc038aa3b, v214
	v_mul_f32_e32 v220, 0xc038aa3b, v220
	v_exp_f32_e32 v170, v170
	v_exp_f32_e32 v208, v208
	v_exp_f32_e32 v214, v214
	v_exp_f32_e32 v220, v220
	v_add_f32_e32 v170, 1.0, v170
	v_add_f32_e32 v208, 1.0, v208
	v_add_f32_e32 v214, 1.0, v214
	v_add_f32_e32 v220, 1.0, v220
	v_rcp_f32_e32 v170, v170
	v_rcp_f32_e32 v208, v208
	v_rcp_f32_e32 v214, v214
	v_rcp_f32_e32 v220, v220
	v_mul_f32_e32 v170, v169, v170
	v_mul_f32_e32 v208, v207, v208
	v_mul_f32_e32 v214, v213, v214
	v_mul_f32_e32 v220, v219, v220
	v_mul_f32_e32 v170, v170, v168
	v_mul_f32_e32 v208, v208, v206
	v_mul_f32_e32 v214, v214, v212
	v_mul_f32_e32 v220, v220, v218
	v_cvt_pk_bf16_f32 v242, v170, v208
	v_cvt_pk_bf16_f32 v243, v214, v220
	global_store_dwordx2 v236, v[242:243], s[100:101] offset:160
	s_waitcnt lgkmcnt(0)
	s_waitcnt vmcnt(6)
	v_mov_b32_e32 v66, v82
	v_mov_b32_e32 v67, v83
	v_mov_b32_e32 v68, v84
	v_mov_b32_e32 v69, v85
	v_mov_b32_e32 v70, v86
	v_mov_b32_e32 v71, v87
	v_mov_b32_e32 v72, v88
	v_mov_b32_e32 v73, v89
	v_mov_b32_e32 v74, v90
	v_mov_b32_e32 v75, v91
	v_mov_b32_e32 v76, v92
	v_mov_b32_e32 v77, v93
	v_mov_b32_e32 v78, v94
	v_mov_b32_e32 v79, v95
	v_mov_b32_e32 v80, v96
	v_mov_b32_e32 v81, v97
	s_add_u32 s6, s6, 0x18000
	s_addc_u32 s7, s7, 0
	s_add_u32 s100, s100, 0xc000
	s_addc_u32 s101, s101, 0
	s_add_i32 s64, s64, 1
	s_cmp_lt_u32 s64, 3
	s_cbranch_scc1 .Lscan2_sub
	s_add_i32 s23, s23, s42
